# speedup vs baseline: 1.0079x; 1.0079x over previous
; #define STAGE(Pp, BASE, br, kt) do { const u16* _g = (BASE) + ((long)(br) * K + (long)(kt) * BK); \
;     __builtin_amdgcn_global_load_lds((const unsigned*)(_g + voff0), (unsigned*)((char*)(Pp) + tb16), 16, 0, 0); \
;     __builtin_amdgcn_global_load_lds((const unsigned*)(_g + voff1), (unsigned*)((char*)(Pp) + tb16 + 8192), 16, 0, 0); } while (0)
; #define LDA(dst, b, h) _Pragma("unroll") for (int m = 0; m < 4; ++m) _Pragma("unroll") for (int k = 0; k < 2; ++k) \
;     dst[m][k] = *reinterpret_cast<const bf16x8*>((const char*)shm + aB + (((b) * 2 + (h)) * 16384 + (m * 2 + k) * 1024))
; #define LDB(dst, b, h) _Pragma("unroll") for (int n = 0; n < 2; ++n) _Pragma("unroll") for (int k = 0; k < 2; ++k) \
;     dst[n][k] = *reinterpret_cast<const bf16x8*>((const char*)shm + bB + (((b) * 2 + (h)) * 16384 + (n * 2 + k) * 1024))
; #define WAIT_V(n) asm volatile("s_waitcnt vmcnt(" #n ")" ::: "memory")
; #define WAIT_L(n) asm volatile("s_waitcnt lgkmcnt(" #n ")" ::: "memory")
; #define BAR __builtin_amdgcn_s_barrier()
; #define SCHED __builtin_amdgcn_sched_barrier(0)
; template <int MODE> ...
;     ...
;     for (int t = 0; t < nt - 2; t += 2) {
;       LDB(B0, 0, 0); LDB(B1, 0, 1); LDA(At, 0, 0); STAGE(SA(1, 1), A, brow + HALF, t + 1);
;       WAIT_L(0); BAR; MMA2(0, 0, 0, 1); BAR; SCHED;
;       LDA(At, 0, 1); STAGE(SB(0, 0), Bt, bcol, t + 2); STAGE(SB(0, 1), Bt, bcol + HALF, t + 2); STAGE(SA(0, 0), A, brow, t + 2);
;       WAIT_V(6); WAIT_L(0); BAR; MMA2(1, 0, 1, 1); BAR; SCHED;
.LBB0_154:
	s_add_u32 s71, s32, 0xc000
	s_mov_b32 m0, s71
	ds_read_b128 v[170:173], v149
	ds_read_b128 v[174:177], v149 offset:1024
	ds_read_b128 v[178:181], v149 offset:2048
	ds_read_b128 v[182:185], v149 offset:3072
	ds_read_b128 v[186:189], v149 offset:16384
	ds_read_b128 v[190:193], v149 offset:17408
	ds_read_b128 v[194:197], v149 offset:18432
	ds_read_b128 v[198:201], v149 offset:19456
	ds_read_b128 v[202:205], v151
	ds_read_b128 v[206:209], v151 offset:1024
	ds_read_b128 v[210:213], v151 offset:2048
	ds_read_b128 v[214:217], v151 offset:3072
	ds_read_b128 v[218:221], v151 offset:4096
	ds_read_b128 v[222:225], v151 offset:5120
	ds_read_b128 v[226:229], v151 offset:6144
	ds_read_b128 v[230:233], v151 offset:7168
	s_add_u32 s88, s74, s40
	s_addc_u32 s89, s75, s41
	global_load_lds_dwordx4 v142, s[88:89]
	s_add_u32 s71, s32, 0xe000
	s_mov_b32 m0, s71
	s_nop 0
	s_add_u32 s90, s74, s40
	s_addc_u32 s91, s75, s41
	global_load_lds_dwordx4 v144, s[90:91]
	s_waitcnt lgkmcnt(0)
	s_setprio 1
	s_barrier
	v_mfma_f32_16x16x32_bf16 v[124:127], v[202:205], v[170:173], v[124:127]
	v_mfma_f32_16x16x32_bf16 v[120:123], v[202:205], v[178:181], v[120:123]
	v_mfma_f32_16x16x32_bf16 v[116:119], v[210:213], v[170:173], v[116:119]
	v_mfma_f32_16x16x32_bf16 v[112:115], v[210:213], v[178:181], v[112:115]
	v_mfma_f32_16x16x32_bf16 v[108:111], v[218:221], v[170:173], v[108:111]
	v_mfma_f32_16x16x32_bf16 v[104:107], v[218:221], v[178:181], v[104:107]
	v_mfma_f32_16x16x32_bf16 v[100:103], v[226:229], v[170:173], v[100:103]
	v_mfma_f32_16x16x32_bf16 v[96:99], v[226:229], v[178:181], v[96:99]
	v_mfma_f32_16x16x32_bf16 v[92:95], v[202:205], v[186:189], v[92:95]
	v_mfma_f32_16x16x32_bf16 v[88:91], v[202:205], v[194:197], v[88:91]
	v_mfma_f32_16x16x32_bf16 v[84:87], v[210:213], v[186:189], v[84:87]
	v_mfma_f32_16x16x32_bf16 v[80:83], v[210:213], v[194:197], v[80:83]
	v_mfma_f32_16x16x32_bf16 v[76:79], v[218:221], v[186:189], v[76:79]
	v_mfma_f32_16x16x32_bf16 v[72:75], v[218:221], v[194:197], v[72:75]
	v_mfma_f32_16x16x32_bf16 v[68:71], v[226:229], v[186:189], v[68:71]
	v_mfma_f32_16x16x32_bf16 v[64:67], v[226:229], v[194:197], v[64:67]
	v_mfma_f32_16x16x32_bf16 v[124:127], v[206:209], v[174:177], v[124:127]
	v_mfma_f32_16x16x32_bf16 v[120:123], v[206:209], v[182:185], v[120:123]
	v_mfma_f32_16x16x32_bf16 v[116:119], v[214:217], v[174:177], v[116:119]
	v_mfma_f32_16x16x32_bf16 v[112:115], v[214:217], v[182:185], v[112:115]
	v_mfma_f32_16x16x32_bf16 v[108:111], v[222:225], v[174:177], v[108:111]
	v_mfma_f32_16x16x32_bf16 v[104:107], v[222:225], v[182:185], v[104:107]
	v_mfma_f32_16x16x32_bf16 v[100:103], v[230:233], v[174:177], v[100:103]
	v_mfma_f32_16x16x32_bf16 v[96:99], v[230:233], v[182:185], v[96:99]
	v_mfma_f32_16x16x32_bf16 v[92:95], v[206:209], v[190:193], v[92:95]
	v_mfma_f32_16x16x32_bf16 v[88:91], v[206:209], v[198:201], v[88:91]
	v_mfma_f32_16x16x32_bf16 v[84:87], v[214:217], v[190:193], v[84:87]
	v_mfma_f32_16x16x32_bf16 v[80:83], v[214:217], v[198:201], v[80:83]
	v_mfma_f32_16x16x32_bf16 v[76:79], v[222:225], v[190:193], v[76:79]
	v_mfma_f32_16x16x32_bf16 v[72:75], v[222:225], v[198:201], v[72:75]
	v_mfma_f32_16x16x32_bf16 v[68:71], v[230:233], v[190:193], v[68:71]
	v_mfma_f32_16x16x32_bf16 v[64:67], v[230:233], v[198:201], v[64:67]
	s_barrier
	s_setprio 0
	s_add_u32 s71, s32, 0x10000
	s_mov_b32 m0, s71
	ds_read_b128 v[202:205], v151 offset:16384
	ds_read_b128 v[206:209], v151 offset:17408
	ds_read_b128 v[210:213], v151 offset:18432
	ds_read_b128 v[214:217], v151 offset:19456
	ds_read_b128 v[218:221], v151 offset:20480
	ds_read_b128 v[222:225], v151 offset:21504
	ds_read_b128 v[226:229], v151 offset:22528
	ds_read_b128 v[230:233], v151 offset:23552
	s_add_u32 s92, s74, s42
	s_addc_u32 s93, s75, s43
	global_load_lds_dwordx4 v138, s[92:93]
	s_add_u32 s71, s32, 0x12000
	s_mov_b32 m0, s71
	s_add_u32 s71, s32, 0x14000
	s_add_u32 s96, s74, s42
	s_addc_u32 s97, s75, s43
	global_load_lds_dwordx4 v140, s[96:97]
	s_mov_b32 m0, s71
	s_add_u32 s71, s32, 0x16000
	s_add_u32 s88, s74, s44
	s_addc_u32 s89, s75, s45
	global_load_lds_dwordx4 v138, s[88:89]
	s_mov_b32 m0, s71
	s_mov_b32 s71, s32
	s_add_u32 s90, s74, s44
	s_addc_u32 s91, s75, s45
	global_load_lds_dwordx4 v140, s[90:91]
	s_mov_b32 m0, s71
	s_add_u32 s71, s32, 0x2000
	s_add_u32 s92, s74, s48
	s_addc_u32 s93, s75, s49
	global_load_lds_dwordx4 v142, s[92:93]
	s_mov_b32 m0, s71
	s_nop 0
	s_add_u32 s96, s74, s48
	s_addc_u32 s97, s75, s49
	global_load_lds_dwordx4 v144, s[96:97]
	s_waitcnt vmcnt(6)
	s_waitcnt lgkmcnt(0)
	s_setprio 1
	s_barrier
; #define STAGE(Pp, BASE, br, kt) do { const u16* _g = (BASE) + ((long)(br) * K + (long)(kt) * BK); \
;     __builtin_amdgcn_global_load_lds((const unsigned*)(_g + voff0), (unsigned*)((char*)(Pp) + tb16), 16, 0, 0); \
;     __builtin_amdgcn_global_load_lds((const unsigned*)(_g + voff1), (unsigned*)((char*)(Pp) + tb16 + 8192), 16, 0, 0); } while (0)
; #define LDA(dst, b, h) _Pragma("unroll") for (int m = 0; m < 4; ++m) _Pragma("unroll") for (int k = 0; k < 2; ++k) \
;     dst[m][k] = *reinterpret_cast<const bf16x8*>((const char*)shm + aB + (((b) * 2 + (h)) * 16384 + (m * 2 + k) * 1024))
; #define LDB(dst, b, h) _Pragma("unroll") for (int n = 0; n < 2; ++n) _Pragma("unroll") for (int k = 0; k < 2; ++k) \
;     dst[n][k] = *reinterpret_cast<const bf16x8*>((const char*)shm + bB + (((b) * 2 + (h)) * 16384 + (n * 2 + k) * 1024))
; #define WAIT_V(n) asm volatile("s_waitcnt vmcnt(" #n ")" ::: "memory")
; #define WAIT_L(n) asm volatile("s_waitcnt lgkmcnt(" #n ")" ::: "memory")
; #define BAR __builtin_amdgcn_s_barrier()
; #define SCHED __builtin_amdgcn_sched_barrier(0)
; template <int MODE> ...
;     ...
;       WAIT_L(0); BAR; MMA2(0, 0, 0, 1); BAR; SCHED;
;       LDA(At, 0, 1); STAGE(SB(0, 0), Bt, bcol, t + 2); STAGE(SB(0, 1), Bt, bcol + HALF, t + 2); STAGE(SA(0, 0), A, brow, t + 2);
;       WAIT_V(6); WAIT_L(0); BAR; MMA2(1, 0, 1, 1); BAR; SCHED;
;       LDB(B0, 1, 0); LDB(B1, 1, 1); LDA(At, 1, 0); STAGE(SA(0, 1), A, brow + HALF, t + 2);
;       WAIT_L(0); BAR; MMA2(0, 0, 0, 1); BAR; SCHED;
	v_mfma_f32_16x16x32_bf16 v[60:63], v[202:205], v[170:173], v[60:63]
	v_mfma_f32_16x16x32_bf16 v[56:59], v[202:205], v[178:181], v[56:59]
	v_mfma_f32_16x16x32_bf16 v[52:55], v[210:213], v[170:173], v[52:55]
	v_mfma_f32_16x16x32_bf16 v[48:51], v[210:213], v[178:181], v[48:51]
	v_mfma_f32_16x16x32_bf16 v[44:47], v[218:221], v[170:173], v[44:47]
	v_mfma_f32_16x16x32_bf16 v[40:43], v[218:221], v[178:181], v[40:43]
	v_mfma_f32_16x16x32_bf16 v[36:39], v[226:229], v[170:173], v[36:39]
	v_mfma_f32_16x16x32_bf16 v[32:35], v[226:229], v[178:181], v[32:35]
	v_mfma_f32_16x16x32_bf16 v[28:31], v[202:205], v[186:189], v[28:31]
	v_mfma_f32_16x16x32_bf16 v[24:27], v[202:205], v[194:197], v[24:27]
	v_mfma_f32_16x16x32_bf16 v[20:23], v[210:213], v[186:189], v[20:23]
	v_mfma_f32_16x16x32_bf16 v[16:19], v[210:213], v[194:197], v[16:19]
	v_mfma_f32_16x16x32_bf16 v[12:15], v[218:221], v[186:189], v[12:15]
	v_mfma_f32_16x16x32_bf16 v[8:11], v[218:221], v[194:197], v[8:11]
	v_mfma_f32_16x16x32_bf16 v[4:7], v[226:229], v[186:189], v[4:7]
	v_mfma_f32_16x16x32_bf16 v[0:3], v[226:229], v[194:197], v[0:3]
	v_mfma_f32_16x16x32_bf16 v[60:63], v[206:209], v[174:177], v[60:63]
	v_mfma_f32_16x16x32_bf16 v[56:59], v[206:209], v[182:185], v[56:59]
	v_mfma_f32_16x16x32_bf16 v[52:55], v[214:217], v[174:177], v[52:55]
	v_mfma_f32_16x16x32_bf16 v[48:51], v[214:217], v[182:185], v[48:51]
	v_mfma_f32_16x16x32_bf16 v[44:47], v[222:225], v[174:177], v[44:47]
	v_mfma_f32_16x16x32_bf16 v[40:43], v[222:225], v[182:185], v[40:43]
	v_mfma_f32_16x16x32_bf16 v[36:39], v[230:233], v[174:177], v[36:39]
	v_mfma_f32_16x16x32_bf16 v[32:35], v[230:233], v[182:185], v[32:35]
	v_mfma_f32_16x16x32_bf16 v[28:31], v[206:209], v[190:193], v[28:31]
	v_mfma_f32_16x16x32_bf16 v[24:27], v[206:209], v[198:201], v[24:27]
	v_mfma_f32_16x16x32_bf16 v[20:23], v[214:217], v[190:193], v[20:23]
	v_mfma_f32_16x16x32_bf16 v[16:19], v[214:217], v[198:201], v[16:19]
	v_mfma_f32_16x16x32_bf16 v[12:15], v[222:225], v[190:193], v[12:15]
	v_mfma_f32_16x16x32_bf16 v[8:11], v[222:225], v[198:201], v[8:11]
	v_mfma_f32_16x16x32_bf16 v[4:7], v[230:233], v[190:193], v[4:7]
	v_mfma_f32_16x16x32_bf16 v[0:3], v[230:233], v[198:201], v[0:3]
	s_barrier
	s_setprio 0
	s_add_u32 s71, s32, 0x4000
	s_mov_b32 m0, s71
	s_add_u32 s71, s32, 0x6000
	ds_read_b128 v[170:173], v149 offset:32768
	ds_read_b128 v[174:177], v149 offset:33792
	ds_read_b128 v[178:181], v149 offset:34816
	ds_read_b128 v[182:185], v149 offset:35840
	ds_read_b128 v[186:189], v149 offset:49152
	ds_read_b128 v[190:193], v149 offset:50176
	ds_read_b128 v[194:197], v149 offset:51200
	ds_read_b128 v[198:201], v149 offset:52224
	ds_read_b128 v[202:205], v151 offset:32768
	ds_read_b128 v[206:209], v151 offset:33792
	ds_read_b128 v[210:213], v151 offset:34816
	ds_read_b128 v[214:217], v151 offset:35840
	ds_read_b128 v[218:221], v151 offset:36864
	ds_read_b128 v[222:225], v151 offset:37888
	ds_read_b128 v[226:229], v151 offset:38912
	ds_read_b128 v[230:233], v151 offset:39936
	s_add_u32 s88, s74, s50
	s_addc_u32 s89, s75, s51
	global_load_lds_dwordx4 v142, s[88:89]
	s_mov_b32 m0, s71
	s_nop 0
	s_add_u32 s90, s74, s50
	s_addc_u32 s91, s75, s51
	global_load_lds_dwordx4 v144, s[90:91]
	s_waitcnt lgkmcnt(0)
	s_setprio 1
	s_barrier
	v_mfma_f32_16x16x32_bf16 v[124:127], v[202:205], v[170:173], v[124:127]
	v_mfma_f32_16x16x32_bf16 v[120:123], v[202:205], v[178:181], v[120:123]
	v_mfma_f32_16x16x32_bf16 v[116:119], v[210:213], v[170:173], v[116:119]
	v_mfma_f32_16x16x32_bf16 v[112:115], v[210:213], v[178:181], v[112:115]
	v_mfma_f32_16x16x32_bf16 v[108:111], v[218:221], v[170:173], v[108:111]
	v_mfma_f32_16x16x32_bf16 v[104:107], v[218:221], v[178:181], v[104:107]
	v_mfma_f32_16x16x32_bf16 v[100:103], v[226:229], v[170:173], v[100:103]
	v_mfma_f32_16x16x32_bf16 v[96:99], v[226:229], v[178:181], v[96:99]
	v_mfma_f32_16x16x32_bf16 v[92:95], v[202:205], v[186:189], v[92:95]
	v_mfma_f32_16x16x32_bf16 v[88:91], v[202:205], v[194:197], v[88:91]
	v_mfma_f32_16x16x32_bf16 v[84:87], v[210:213], v[186:189], v[84:87]
	v_mfma_f32_16x16x32_bf16 v[80:83], v[210:213], v[194:197], v[80:83]
	v_mfma_f32_16x16x32_bf16 v[76:79], v[218:221], v[186:189], v[76:79]
	v_mfma_f32_16x16x32_bf16 v[72:75], v[218:221], v[194:197], v[72:75]
	v_mfma_f32_16x16x32_bf16 v[68:71], v[226:229], v[186:189], v[68:71]
	v_mfma_f32_16x16x32_bf16 v[64:67], v[226:229], v[194:197], v[64:67]
	v_mfma_f32_16x16x32_bf16 v[124:127], v[206:209], v[174:177], v[124:127]
	v_mfma_f32_16x16x32_bf16 v[120:123], v[206:209], v[182:185], v[120:123]
	v_mfma_f32_16x16x32_bf16 v[116:119], v[214:217], v[174:177], v[116:119]
	v_mfma_f32_16x16x32_bf16 v[112:115], v[214:217], v[182:185], v[112:115]
	v_mfma_f32_16x16x32_bf16 v[108:111], v[222:225], v[174:177], v[108:111]
	v_mfma_f32_16x16x32_bf16 v[104:107], v[222:225], v[182:185], v[104:107]
	v_mfma_f32_16x16x32_bf16 v[100:103], v[230:233], v[174:177], v[100:103]
	v_mfma_f32_16x16x32_bf16 v[96:99], v[230:233], v[182:185], v[96:99]
	v_mfma_f32_16x16x32_bf16 v[92:95], v[206:209], v[190:193], v[92:95]
	v_mfma_f32_16x16x32_bf16 v[88:91], v[206:209], v[198:201], v[88:91]
	v_mfma_f32_16x16x32_bf16 v[84:87], v[214:217], v[190:193], v[84:87]
	v_mfma_f32_16x16x32_bf16 v[80:83], v[214:217], v[198:201], v[80:83]
	v_mfma_f32_16x16x32_bf16 v[76:79], v[222:225], v[190:193], v[76:79]
	v_mfma_f32_16x16x32_bf16 v[72:75], v[222:225], v[198:201], v[72:75]
	v_mfma_f32_16x16x32_bf16 v[68:71], v[230:233], v[190:193], v[68:71]
	v_mfma_f32_16x16x32_bf16 v[64:67], v[230:233], v[198:201], v[64:67]
	s_barrier
; #define STAGE(Pp, BASE, br, kt) do { const u16* _g = (BASE) + ((long)(br) * K + (long)(kt) * BK); \
;     __builtin_amdgcn_global_load_lds((const unsigned*)(_g + voff0), (unsigned*)((char*)(Pp) + tb16), 16, 0, 0); \
;     __builtin_amdgcn_global_load_lds((const unsigned*)(_g + voff1), (unsigned*)((char*)(Pp) + tb16 + 8192), 16, 0, 0); } while (0)
; #define LDA(dst, b, h) _Pragma("unroll") for (int m = 0; m < 4; ++m) _Pragma("unroll") for (int k = 0; k < 2; ++k) \
;     dst[m][k] = *reinterpret_cast<const bf16x8*>((const char*)shm + aB + (((b) * 2 + (h)) * 16384 + (m * 2 + k) * 1024))
; #define LDB(dst, b, h) _Pragma("unroll") for (int n = 0; n < 2; ++n) _Pragma("unroll") for (int k = 0; k < 2; ++k) \
;     dst[n][k] = *reinterpret_cast<const bf16x8*>((const char*)shm + bB + (((b) * 2 + (h)) * 16384 + (n * 2 + k) * 1024))
; #define WAIT_V(n) asm volatile("s_waitcnt vmcnt(" #n ")" ::: "memory")
; #define WAIT_L(n) asm volatile("s_waitcnt lgkmcnt(" #n ")" ::: "memory")
; #define BAR __builtin_amdgcn_s_barrier()
; #define SCHED __builtin_amdgcn_sched_barrier(0)
; template <int MODE> ...
;     ...
;       LDA(At, 1, 1); STAGE(SB(1, 0), Bt, bcol, t + 3); STAGE(SB(1, 1), Bt, bcol + HALF, t + 3); STAGE(SA(1, 0), A, brow, t + 3);
;       WAIT_V(6); WAIT_L(0); BAR; MMA2(1, 0, 1, 1); BAR; SCHED;
;     }
;     {
;       LDB(B0, 0, 0); LDB(B1, 0, 1); LDA(At, 0, 0); STAGE(SA(1, 1), A, brow + HALF, nt - 1);
;       WAIT_L(0); BAR; MMA2(0, 0, 0, 1); BAR; SCHED;
;       LDA(At, 0, 1); WAIT_V(0); WAIT_L(0); BAR; MMA2(1, 0, 1, 1); BAR; SCHED;
	s_setprio 0
	s_add_u32 s71, s32, 0x18000
	s_mov_b32 m0, s71
	s_add_u32 s71, s32, 0x1a000
	ds_read_b128 v[202:205], v151 offset:49152
	ds_read_b128 v[206:209], v151 offset:50176
	ds_read_b128 v[210:213], v151 offset:51200
	ds_read_b128 v[214:217], v151 offset:52224
	ds_read_b128 v[218:221], v151 offset:53248
	ds_read_b128 v[222:225], v151 offset:54272
	ds_read_b128 v[226:229], v151 offset:55296
	ds_read_b128 v[230:233], v151 offset:56320
	s_add_u32 s92, s74, s60
	s_addc_u32 s93, s75, s61
	global_load_lds_dwordx4 v138, s[92:93]
	s_mov_b32 m0, s71
	s_add_u32 s71, s32, 0x1c000
	s_add_u32 s96, s74, s60
	s_addc_u32 s97, s75, s61
	global_load_lds_dwordx4 v140, s[96:97]
	s_mov_b32 m0, s71
	s_add_u32 s71, s32, 0x1e000
	s_add_u32 s88, s74, s62
	s_addc_u32 s89, s75, s63
	global_load_lds_dwordx4 v138, s[88:89]
	s_mov_b32 m0, s71
	s_add_u32 s71, s32, 0x8000
	s_add_u32 s90, s74, s62
	s_addc_u32 s91, s75, s63
	global_load_lds_dwordx4 v140, s[90:91]
	s_mov_b32 m0, s71
	s_add_u32 s71, s32, 0xa000
	s_add_u32 s92, s74, s64
	s_addc_u32 s93, s75, s65
	global_load_lds_dwordx4 v142, s[92:93]
	s_mov_b32 m0, s71
	s_nop 0
	s_add_u32 s96, s74, s64
	s_addc_u32 s97, s75, s65
	global_load_lds_dwordx4 v144, s[96:97]
	s_waitcnt vmcnt(6)
	s_waitcnt lgkmcnt(0)
	s_setprio 1
	s_barrier
	v_mfma_f32_16x16x32_bf16 v[60:63], v[202:205], v[170:173], v[60:63]
	v_mfma_f32_16x16x32_bf16 v[56:59], v[202:205], v[178:181], v[56:59]
	v_mfma_f32_16x16x32_bf16 v[52:55], v[210:213], v[170:173], v[52:55]
	v_mfma_f32_16x16x32_bf16 v[48:51], v[210:213], v[178:181], v[48:51]
	v_mfma_f32_16x16x32_bf16 v[44:47], v[218:221], v[170:173], v[44:47]
	v_mfma_f32_16x16x32_bf16 v[40:43], v[218:221], v[178:181], v[40:43]
	v_mfma_f32_16x16x32_bf16 v[36:39], v[226:229], v[170:173], v[36:39]
	v_mfma_f32_16x16x32_bf16 v[32:35], v[226:229], v[178:181], v[32:35]
	v_mfma_f32_16x16x32_bf16 v[28:31], v[202:205], v[186:189], v[28:31]
	v_mfma_f32_16x16x32_bf16 v[24:27], v[202:205], v[194:197], v[24:27]
	v_mfma_f32_16x16x32_bf16 v[20:23], v[210:213], v[186:189], v[20:23]
	v_mfma_f32_16x16x32_bf16 v[16:19], v[210:213], v[194:197], v[16:19]
	v_mfma_f32_16x16x32_bf16 v[12:15], v[218:221], v[186:189], v[12:15]
	v_mfma_f32_16x16x32_bf16 v[8:11], v[218:221], v[194:197], v[8:11]
	v_mfma_f32_16x16x32_bf16 v[4:7], v[226:229], v[186:189], v[4:7]
	v_mfma_f32_16x16x32_bf16 v[0:3], v[226:229], v[194:197], v[0:3]
	v_mfma_f32_16x16x32_bf16 v[60:63], v[206:209], v[174:177], v[60:63]
	v_mfma_f32_16x16x32_bf16 v[56:59], v[206:209], v[182:185], v[56:59]
	v_mfma_f32_16x16x32_bf16 v[52:55], v[214:217], v[174:177], v[52:55]
	v_mfma_f32_16x16x32_bf16 v[48:51], v[214:217], v[182:185], v[48:51]
	v_mfma_f32_16x16x32_bf16 v[44:47], v[222:225], v[174:177], v[44:47]
	v_mfma_f32_16x16x32_bf16 v[40:43], v[222:225], v[182:185], v[40:43]
	v_mfma_f32_16x16x32_bf16 v[36:39], v[230:233], v[174:177], v[36:39]
	v_mfma_f32_16x16x32_bf16 v[32:35], v[230:233], v[182:185], v[32:35]
	v_mfma_f32_16x16x32_bf16 v[28:31], v[206:209], v[190:193], v[28:31]
	v_mfma_f32_16x16x32_bf16 v[24:27], v[206:209], v[198:201], v[24:27]
	v_mfma_f32_16x16x32_bf16 v[20:23], v[214:217], v[190:193], v[20:23]
	v_mfma_f32_16x16x32_bf16 v[16:19], v[214:217], v[198:201], v[16:19]
	v_mfma_f32_16x16x32_bf16 v[12:15], v[222:225], v[190:193], v[12:15]
	v_mfma_f32_16x16x32_bf16 v[8:11], v[222:225], v[198:201], v[8:11]
	v_mfma_f32_16x16x32_bf16 v[4:7], v[230:233], v[190:193], v[4:7]
	v_mfma_f32_16x16x32_bf16 v[0:3], v[230:233], v[198:201], v[0:3]
	s_barrier
	s_setprio 0
	s_add_i32 s69, s69, 2
	s_add_u32 s74, s74, 0x100
	s_addc_u32 s75, s75, 0
	s_cmp_lt_u32 s69, 60
	s_cbranch_scc1 .LBB0_154
	s_add_u32 s72, s72, 0x1f80
	v_readfirstlane_b32 s69, v167
	s_addc_u32 s73, s73, 0
	s_mov_b32 m0, s69
	v_readfirstlane_b32 s69, v168
	ds_read_b128 v[138:141], v149
	ds_read_b128 v[142:145], v149 offset:1024
	ds_read_b128 v[170:173], v149 offset:2048
	ds_read_b128 v[174:177], v149 offset:3072
	ds_read_b128 v[178:181], v149 offset:16384
	ds_read_b128 v[182:185], v149 offset:17408
	ds_read_b128 v[186:189], v149 offset:18432
	ds_read_b128 v[190:193], v149 offset:19456
	ds_read_b128 v[194:197], v151
	ds_read_b128 v[198:201], v151 offset:1024
	ds_read_b128 v[202:205], v151 offset:2048
	ds_read_b128 v[206:209], v151 offset:3072
	ds_read_b128 v[210:213], v151 offset:4096
	ds_read_b128 v[214:217], v151 offset:5120
	ds_read_b128 v[218:221], v151 offset:6144
	ds_read_b128 v[222:225], v151 offset:7168
	global_load_lds_dwordx4 v134, s[72:73]
	s_mov_b32 m0, s69
	s_nop 0
	global_load_lds_dwordx4 v136, s[72:73]
	s_waitcnt lgkmcnt(0)
	s_setprio 1
	s_barrier
; #define STAGE(Pp, BASE, br, kt) do { const u16* _g = (BASE) + ((long)(br) * K + (long)(kt) * BK); \
;     __builtin_amdgcn_global_load_lds((const unsigned*)(_g + voff0), (unsigned*)((char*)(Pp) + tb16), 16, 0, 0); \
;     __builtin_amdgcn_global_load_lds((const unsigned*)(_g + voff1), (unsigned*)((char*)(Pp) + tb16 + 8192), 16, 0, 0); } while (0)
; #define LDA(dst, b, h) _Pragma("unroll") for (int m = 0; m < 4; ++m) _Pragma("unroll") for (int k = 0; k < 2; ++k) \
;     dst[m][k] = *reinterpret_cast<const bf16x8*>((const char*)shm + aB + (((b) * 2 + (h)) * 16384 + (m * 2 + k) * 1024))
; #define LDB(dst, b, h) _Pragma("unroll") for (int n = 0; n < 2; ++n) _Pragma("unroll") for (int k = 0; k < 2; ++k) \
;     dst[n][k] = *reinterpret_cast<const bf16x8*>((const char*)shm + bB + (((b) * 2 + (h)) * 16384 + (n * 2 + k) * 1024))
; #define WAIT_V(n) asm volatile("s_waitcnt vmcnt(" #n ")" ::: "memory")
; #define WAIT_L(n) asm volatile("s_waitcnt lgkmcnt(" #n ")" ::: "memory")
; #define BAR __builtin_amdgcn_s_barrier()
; #define SCHED __builtin_amdgcn_sched_barrier(0)
; template <int MODE> ...
;     ...
;       LDB(B0, 0, 0); LDB(B1, 0, 1); LDA(At, 0, 0); STAGE(SA(1, 1), A, brow + HALF, nt - 1);
;       WAIT_L(0); BAR; MMA2(0, 0, 0, 1); BAR; SCHED;
;       LDA(At, 0, 1); WAIT_V(0); WAIT_L(0); BAR; MMA2(1, 0, 1, 1); BAR; SCHED;
;       LDB(B0, 1, 0); LDB(B1, 1, 1); LDA(At, 1, 0); WAIT_L(0); BAR; MMA2(0, 0, 0, 1); BAR; SCHED;
	v_mfma_f32_16x16x32_bf16 v[124:127], v[194:197], v[138:141], v[124:127]
	v_mfma_f32_16x16x32_bf16 v[120:123], v[194:197], v[170:173], v[120:123]
	v_mfma_f32_16x16x32_bf16 v[116:119], v[202:205], v[138:141], v[116:119]
	v_mfma_f32_16x16x32_bf16 v[112:115], v[202:205], v[170:173], v[112:115]
	v_mfma_f32_16x16x32_bf16 v[108:111], v[210:213], v[138:141], v[108:111]
	v_mfma_f32_16x16x32_bf16 v[104:107], v[210:213], v[170:173], v[104:107]
	v_mfma_f32_16x16x32_bf16 v[100:103], v[218:221], v[138:141], v[100:103]
	v_mfma_f32_16x16x32_bf16 v[96:99], v[218:221], v[170:173], v[96:99]
	v_mfma_f32_16x16x32_bf16 v[92:95], v[194:197], v[178:181], v[92:95]
	v_mfma_f32_16x16x32_bf16 v[88:91], v[194:197], v[186:189], v[88:91]
	v_mfma_f32_16x16x32_bf16 v[84:87], v[202:205], v[178:181], v[84:87]
	v_mfma_f32_16x16x32_bf16 v[80:83], v[202:205], v[186:189], v[80:83]
	v_mfma_f32_16x16x32_bf16 v[76:79], v[210:213], v[178:181], v[76:79]
	v_mfma_f32_16x16x32_bf16 v[72:75], v[210:213], v[186:189], v[72:75]
	v_mfma_f32_16x16x32_bf16 v[68:71], v[218:221], v[178:181], v[68:71]
	v_mfma_f32_16x16x32_bf16 v[64:67], v[218:221], v[186:189], v[64:67]
	v_mfma_f32_16x16x32_bf16 v[124:127], v[198:201], v[142:145], v[124:127]
	v_mfma_f32_16x16x32_bf16 v[120:123], v[198:201], v[174:177], v[120:123]
	v_mfma_f32_16x16x32_bf16 v[116:119], v[206:209], v[142:145], v[116:119]
	v_mfma_f32_16x16x32_bf16 v[112:115], v[206:209], v[174:177], v[112:115]
	v_mfma_f32_16x16x32_bf16 v[108:111], v[214:217], v[142:145], v[108:111]
	v_mfma_f32_16x16x32_bf16 v[104:107], v[214:217], v[174:177], v[104:107]
	v_mfma_f32_16x16x32_bf16 v[100:103], v[222:225], v[142:145], v[100:103]
	v_mfma_f32_16x16x32_bf16 v[96:99], v[222:225], v[174:177], v[96:99]
	v_mfma_f32_16x16x32_bf16 v[92:95], v[198:201], v[182:185], v[92:95]
	v_mfma_f32_16x16x32_bf16 v[88:91], v[198:201], v[190:193], v[88:91]
	v_mfma_f32_16x16x32_bf16 v[84:87], v[206:209], v[182:185], v[84:87]
	v_mfma_f32_16x16x32_bf16 v[80:83], v[206:209], v[190:193], v[80:83]
	v_mfma_f32_16x16x32_bf16 v[76:79], v[214:217], v[182:185], v[76:79]
	v_mfma_f32_16x16x32_bf16 v[72:75], v[214:217], v[190:193], v[72:75]
	v_mfma_f32_16x16x32_bf16 v[68:71], v[222:225], v[182:185], v[68:71]
	v_mfma_f32_16x16x32_bf16 v[64:67], v[222:225], v[190:193], v[64:67]
	s_barrier
	s_setprio 0
	ds_read_b128 v[194:197], v151 offset:16384
	ds_read_b128 v[198:201], v151 offset:17408
	ds_read_b128 v[202:205], v151 offset:18432
	ds_read_b128 v[206:209], v151 offset:19456
	ds_read_b128 v[210:213], v151 offset:20480
	ds_read_b128 v[214:217], v151 offset:21504
	ds_read_b128 v[218:221], v151 offset:22528
	ds_read_b128 v[222:225], v151 offset:23552
	s_waitcnt vmcnt(0)
	s_waitcnt lgkmcnt(0)
	s_setprio 1
	s_barrier
	v_mfma_f32_16x16x32_bf16 v[56:59], v[194:197], v[170:173], v[56:59]
	v_mfma_f32_16x16x32_bf16 v[52:55], v[202:205], v[138:141], v[52:55]
	v_mfma_f32_16x16x32_bf16 v[48:51], v[202:205], v[170:173], v[48:51]
	v_mfma_f32_16x16x32_bf16 v[44:47], v[210:213], v[138:141], v[44:47]
	v_mfma_f32_16x16x32_bf16 v[40:43], v[210:213], v[170:173], v[40:43]
	v_mfma_f32_16x16x32_bf16 v[36:39], v[218:221], v[138:141], v[36:39]
	v_mfma_f32_16x16x32_bf16 v[32:35], v[218:221], v[170:173], v[32:35]
	v_mfma_f32_16x16x32_bf16 v[28:31], v[194:197], v[178:181], v[28:31]
	v_mfma_f32_16x16x32_bf16 v[24:27], v[194:197], v[186:189], v[24:27]
	v_mfma_f32_16x16x32_bf16 v[20:23], v[202:205], v[178:181], v[20:23]
	v_mfma_f32_16x16x32_bf16 v[16:19], v[202:205], v[186:189], v[16:19]
	v_mfma_f32_16x16x32_bf16 v[12:15], v[210:213], v[178:181], v[12:15]
	v_mfma_f32_16x16x32_bf16 v[8:11], v[210:213], v[186:189], v[8:11]
	v_mfma_f32_16x16x32_bf16 v[4:7], v[218:221], v[178:181], v[4:7]
	v_mfma_f32_16x16x32_bf16 v[0:3], v[218:221], v[186:189], v[0:3]
	v_mfma_f32_16x16x32_bf16 v[60:63], v[194:197], v[138:141], v[60:63]
	v_mfma_f32_16x16x32_bf16 v[56:59], v[198:201], v[174:177], v[56:59]
	v_mfma_f32_16x16x32_bf16 v[52:55], v[206:209], v[142:145], v[52:55]
	v_mfma_f32_16x16x32_bf16 v[48:51], v[206:209], v[174:177], v[48:51]
	v_mfma_f32_16x16x32_bf16 v[44:47], v[214:217], v[142:145], v[44:47]
	v_mfma_f32_16x16x32_bf16 v[40:43], v[214:217], v[174:177], v[40:43]
	v_mfma_f32_16x16x32_bf16 v[36:39], v[222:225], v[142:145], v[36:39]
	v_mfma_f32_16x16x32_bf16 v[32:35], v[222:225], v[174:177], v[32:35]
	v_mfma_f32_16x16x32_bf16 v[28:31], v[198:201], v[182:185], v[28:31]
	v_mfma_f32_16x16x32_bf16 v[24:27], v[198:201], v[190:193], v[24:27]
	v_mfma_f32_16x16x32_bf16 v[20:23], v[206:209], v[182:185], v[20:23]
	v_mfma_f32_16x16x32_bf16 v[16:19], v[206:209], v[190:193], v[16:19]
	v_mfma_f32_16x16x32_bf16 v[12:15], v[214:217], v[182:185], v[12:15]
	v_mfma_f32_16x16x32_bf16 v[8:11], v[214:217], v[190:193], v[8:11]
	v_mfma_f32_16x16x32_bf16 v[4:7], v[222:225], v[182:185], v[4:7]
	v_mfma_f32_16x16x32_bf16 v[0:3], v[222:225], v[190:193], v[0:3]
	v_mfma_f32_16x16x32_bf16 v[226:229], v[198:201], v[142:145], v[60:63]
	s_barrier
	s_setprio 0
	ds_read_b128 v[138:141], v149 offset:32768
	ds_read_b128 v[142:145], v149 offset:33792
	ds_read_b128 v[170:173], v149 offset:34816
	ds_read_b128 v[174:177], v149 offset:35840
	ds_read_b128 v[178:181], v149 offset:49152
	ds_read_b128 v[182:185], v149 offset:50176
	ds_read_b128 v[186:189], v149 offset:51200
	ds_read_b128 v[190:193], v149 offset:52224
	ds_read_b128 v[60:63], v151 offset:32768
	ds_read_b128 v[194:197], v151 offset:33792
	ds_read_b128 v[198:201], v151 offset:34816
	ds_read_b128 v[202:205], v151 offset:35840
	ds_read_b128 v[206:209], v151 offset:36864
	ds_read_b128 v[210:213], v151 offset:37888
	ds_read_b128 v[214:217], v151 offset:38912
	ds_read_b128 v[218:221], v151 offset:39936
	s_waitcnt lgkmcnt(0)
	s_setprio 1
	s_barrier
; #define LDA(dst, b, h) _Pragma("unroll") for (int m = 0; m < 4; ++m) _Pragma("unroll") for (int k = 0; k < 2; ++k) \
;     dst[m][k] = *reinterpret_cast<const bf16x8*>((const char*)shm + aB + (((b) * 2 + (h)) * 16384 + (m * 2 + k) * 1024))
; #define LDB(dst, b, h) _Pragma("unroll") for (int n = 0; n < 2; ++n) _Pragma("unroll") for (int k = 0; k < 2; ++k) \
;     dst[n][k] = *reinterpret_cast<const bf16x8*>((const char*)shm + bB + (((b) * 2 + (h)) * 16384 + (n * 2 + k) * 1024))
; #define WAIT_L(n) asm volatile("s_waitcnt lgkmcnt(" #n ")" ::: "memory")
; #define BAR __builtin_amdgcn_s_barrier()
; #define SCHED __builtin_amdgcn_sched_barrier(0)
; template <int MODE> ...
;     ...
;       LDB(B0, 1, 0); LDB(B1, 1, 1); LDA(At, 1, 0); WAIT_L(0); BAR; MMA2(0, 0, 0, 1); BAR; SCHED;
;       LDA(At, 1, 1); WAIT_L(0); BAR; MMA2(1, 0, 1, 1); BAR; SCHED;
;     }
;     ...
;     if (wr == 0) BAR;
	v_mfma_f32_16x16x32_bf16 v[124:127], v[60:63], v[138:141], v[124:127]
	v_mfma_f32_16x16x32_bf16 v[120:123], v[60:63], v[170:173], v[120:123]
	v_mfma_f32_16x16x32_bf16 v[92:95], v[60:63], v[178:181], v[92:95]
	v_mfma_f32_16x16x32_bf16 v[60:63], v[60:63], v[186:189], v[88:91]
	v_mfma_f32_16x16x32_bf16 v[88:91], v[194:197], v[190:193], v[60:63]
	v_mfma_f32_16x16x32_bf16 v[60:63], v[198:201], v[178:181], v[84:87]
	v_mfma_f32_16x16x32_bf16 v[84:87], v[202:205], v[182:185], v[60:63]
	v_mfma_f32_16x16x32_bf16 v[60:63], v[198:201], v[186:189], v[80:83]
	v_mfma_f32_16x16x32_bf16 v[80:83], v[202:205], v[190:193], v[60:63]
	v_mfma_f32_16x16x32_bf16 v[60:63], v[206:209], v[178:181], v[76:79]
	v_mfma_f32_16x16x32_bf16 v[76:79], v[210:213], v[182:185], v[60:63]
	v_mfma_f32_16x16x32_bf16 v[60:63], v[206:209], v[186:189], v[72:75]
	v_mfma_f32_16x16x32_bf16 v[72:75], v[210:213], v[190:193], v[60:63]
	v_mfma_f32_16x16x32_bf16 v[60:63], v[214:217], v[178:181], v[68:71]
	v_mfma_f32_16x16x32_bf16 v[116:119], v[198:201], v[138:141], v[116:119]
	v_mfma_f32_16x16x32_bf16 v[112:115], v[198:201], v[170:173], v[112:115]
	v_mfma_f32_16x16x32_bf16 v[108:111], v[206:209], v[138:141], v[108:111]
	v_mfma_f32_16x16x32_bf16 v[104:107], v[206:209], v[170:173], v[104:107]
	v_mfma_f32_16x16x32_bf16 v[100:103], v[214:217], v[138:141], v[100:103]
	v_mfma_f32_16x16x32_bf16 v[96:99], v[214:217], v[170:173], v[96:99]
	v_mfma_f32_16x16x32_bf16 v[68:71], v[218:221], v[182:185], v[60:63]
	v_mfma_f32_16x16x32_bf16 v[60:63], v[214:217], v[186:189], v[64:67]
	v_mfma_f32_16x16x32_bf16 v[124:127], v[194:197], v[142:145], v[124:127]
	v_mfma_f32_16x16x32_bf16 v[120:123], v[194:197], v[174:177], v[120:123]
	v_mfma_f32_16x16x32_bf16 v[116:119], v[202:205], v[142:145], v[116:119]
	v_mfma_f32_16x16x32_bf16 v[112:115], v[202:205], v[174:177], v[112:115]
	v_mfma_f32_16x16x32_bf16 v[108:111], v[210:213], v[142:145], v[108:111]
	v_mfma_f32_16x16x32_bf16 v[104:107], v[210:213], v[174:177], v[104:107]
	v_mfma_f32_16x16x32_bf16 v[100:103], v[218:221], v[142:145], v[100:103]
	v_mfma_f32_16x16x32_bf16 v[96:99], v[218:221], v[174:177], v[96:99]
	v_mfma_f32_16x16x32_bf16 v[92:95], v[194:197], v[182:185], v[92:95]
	v_mfma_f32_16x16x32_bf16 v[60:63], v[218:221], v[190:193], v[60:63]
	s_barrier
	s_setprio 0
	ds_read_b128 v[194:197], v151 offset:49152
	ds_read_b128 v[198:201], v151 offset:50176
	ds_read_b128 v[202:205], v151 offset:51200
	ds_read_b128 v[206:209], v151 offset:52224
	ds_read_b128 v[210:213], v151 offset:53248
	ds_read_b128 v[214:217], v151 offset:54272
	ds_read_b128 v[218:221], v151 offset:55296
	ds_read_b128 v[222:225], v151 offset:56320
	s_waitcnt lgkmcnt(0)
	s_setprio 1
	s_barrier
	v_mfma_f32_16x16x32_bf16 v[64:67], v[194:197], v[138:141], v[226:229]
	v_mfma_f32_16x16x32_bf16 v[56:59], v[194:197], v[170:173], v[56:59]
	v_mfma_f32_16x16x32_bf16 v[52:55], v[202:205], v[138:141], v[52:55]
	v_mfma_f32_16x16x32_bf16 v[48:51], v[202:205], v[170:173], v[48:51]
	v_mfma_f32_16x16x32_bf16 v[44:47], v[210:213], v[138:141], v[44:47]
	v_mfma_f32_16x16x32_bf16 v[40:43], v[210:213], v[170:173], v[40:43]
	v_mfma_f32_16x16x32_bf16 v[36:39], v[218:221], v[138:141], v[36:39]
	v_mfma_f32_16x16x32_bf16 v[32:35], v[218:221], v[170:173], v[32:35]
	v_mfma_f32_16x16x32_bf16 v[28:31], v[194:197], v[178:181], v[28:31]
	v_mfma_f32_16x16x32_bf16 v[24:27], v[194:197], v[186:189], v[24:27]
	v_mfma_f32_16x16x32_bf16 v[20:23], v[202:205], v[178:181], v[20:23]
	v_mfma_f32_16x16x32_bf16 v[16:19], v[202:205], v[186:189], v[16:19]
	v_mfma_f32_16x16x32_bf16 v[12:15], v[210:213], v[178:181], v[12:15]
	v_mfma_f32_16x16x32_bf16 v[8:11], v[210:213], v[186:189], v[8:11]
	v_mfma_f32_16x16x32_bf16 v[4:7], v[218:221], v[178:181], v[4:7]
	v_mfma_f32_16x16x32_bf16 v[0:3], v[218:221], v[186:189], v[0:3]
	v_mfma_f32_16x16x32_bf16 v[64:67], v[198:201], v[142:145], v[64:67]
	v_mfma_f32_16x16x32_bf16 v[56:59], v[198:201], v[174:177], v[56:59]
	v_mfma_f32_16x16x32_bf16 v[52:55], v[206:209], v[142:145], v[52:55]
	v_mfma_f32_16x16x32_bf16 v[48:51], v[206:209], v[174:177], v[48:51]
	v_mfma_f32_16x16x32_bf16 v[44:47], v[214:217], v[142:145], v[44:47]
	v_mfma_f32_16x16x32_bf16 v[40:43], v[214:217], v[174:177], v[40:43]
	v_mfma_f32_16x16x32_bf16 v[36:39], v[222:225], v[142:145], v[36:39]
	v_mfma_f32_16x16x32_bf16 v[32:35], v[222:225], v[174:177], v[32:35]
	v_mfma_f32_16x16x32_bf16 v[28:31], v[198:201], v[182:185], v[28:31]
	v_mfma_f32_16x16x32_bf16 v[24:27], v[198:201], v[190:193], v[24:27]
	v_mfma_f32_16x16x32_bf16 v[20:23], v[206:209], v[182:185], v[20:23]
	v_mfma_f32_16x16x32_bf16 v[16:19], v[206:209], v[190:193], v[16:19]
	v_mfma_f32_16x16x32_bf16 v[12:15], v[214:217], v[182:185], v[12:15]
	v_mfma_f32_16x16x32_bf16 v[8:11], v[214:217], v[190:193], v[8:11]
	v_mfma_f32_16x16x32_bf16 v[4:7], v[222:225], v[182:185], v[4:7]
	v_mfma_f32_16x16x32_bf16 v[0:3], v[222:225], v[190:193], v[0:3]
	s_barrier
	s_setprio 0
	s_and_saveexec_b64 s[72:73], s[6:7]
	s_cbranch_execz .LBB0_157
	s_barrier

; #define STAGE(Pp, BASE, br, kt) do { const u16* _g = (BASE) + ((long)(br) * K + (long)(kt) * BK); \
;     __builtin_amdgcn_global_load_lds((const unsigned*)(_g + voff0), (unsigned*)((char*)(Pp) + tb16), 16, 0, 0); \
;     __builtin_amdgcn_global_load_lds((const unsigned*)(_g + voff1), (unsigned*)((char*)(Pp) + tb16 + 8192), 16, 0, 0); } while (0)
; #define LDA(dst, b, h) _Pragma("unroll") for (int m = 0; m < 4; ++m) _Pragma("unroll") for (int k = 0; k < 2; ++k) \
;     dst[m][k] = *reinterpret_cast<const bf16x8*>((const char*)shm + aB + (((b) * 2 + (h)) * 16384 + (m * 2 + k) * 1024))
; #define LDB(dst, b, h) _Pragma("unroll") for (int n = 0; n < 2; ++n) _Pragma("unroll") for (int k = 0; k < 2; ++k) \
;     dst[n][k] = *reinterpret_cast<const bf16x8*>((const char*)shm + bB + (((b) * 2 + (h)) * 16384 + (n * 2 + k) * 1024))
; #define WAIT_V(n) asm volatile("s_waitcnt vmcnt(" #n ")" ::: "memory")
; #define WAIT_L(n) asm volatile("s_waitcnt lgkmcnt(" #n ")" ::: "memory")
; #define BAR __builtin_amdgcn_s_barrier()
; #define SCHED __builtin_amdgcn_sched_barrier(0)
; template <int MODE> ...
;     ...
;     for (int t = 0; t < nt - 2; t += 2) {
;       LDB(B0, 0, 0); LDB(B1, 0, 1); LDA(At, 0, 0); STAGE(SA(1, 1), A, brow + HALF, t + 1);
;       WAIT_L(0); BAR; MMA2(0, 0, 0, 1); BAR; SCHED;
;       LDA(At, 0, 1); STAGE(SB(0, 0), Bt, bcol, t + 2); STAGE(SB(0, 1), Bt, bcol + HALF, t + 2); STAGE(SA(0, 0), A, brow, t + 2);
;       WAIT_V(6); WAIT_L(0); BAR; MMA2(1, 0, 1, 1); BAR; SCHED;
.LBB0_177:
	s_add_u32 s71, s32, 0xc000
	s_mov_b32 m0, s71
	ds_read_b128 v[168:171], v148
	ds_read_b128 v[172:175], v148 offset:1024
	ds_read_b128 v[176:179], v148 offset:2048
	ds_read_b128 v[180:183], v148 offset:3072
	ds_read_b128 v[184:187], v148 offset:16384
	ds_read_b128 v[188:191], v148 offset:17408
	ds_read_b128 v[192:195], v148 offset:18432
	ds_read_b128 v[196:199], v148 offset:19456
	ds_read_b128 v[200:203], v147
	ds_read_b128 v[204:207], v147 offset:1024
	ds_read_b128 v[208:211], v147 offset:2048
	ds_read_b128 v[212:215], v147 offset:3072
	ds_read_b128 v[216:219], v147 offset:4096
	ds_read_b128 v[220:223], v147 offset:5120
	ds_read_b128 v[224:227], v147 offset:6144
	ds_read_b128 v[228:231], v147 offset:7168
	s_add_u32 s88, s68, s12
	s_addc_u32 s89, s69, s13
	global_load_lds_dwordx4 v142, s[88:89]
	s_add_u32 s71, s32, 0xe000
	s_mov_b32 m0, s71
	s_nop 0
	s_add_u32 s90, s68, s12
	s_addc_u32 s91, s69, s13
	global_load_lds_dwordx4 v144, s[90:91]
	s_waitcnt lgkmcnt(0)
	s_setprio 1
	s_barrier
	v_mfma_f32_16x16x32_bf16 v[124:127], v[200:203], v[168:171], v[124:127]
	v_mfma_f32_16x16x32_bf16 v[120:123], v[200:203], v[176:179], v[120:123]
	v_mfma_f32_16x16x32_bf16 v[116:119], v[208:211], v[168:171], v[116:119]
	v_mfma_f32_16x16x32_bf16 v[112:115], v[208:211], v[176:179], v[112:115]
	v_mfma_f32_16x16x32_bf16 v[108:111], v[216:219], v[168:171], v[108:111]
	v_mfma_f32_16x16x32_bf16 v[104:107], v[216:219], v[176:179], v[104:107]
	v_mfma_f32_16x16x32_bf16 v[100:103], v[224:227], v[168:171], v[100:103]
	v_mfma_f32_16x16x32_bf16 v[96:99], v[224:227], v[176:179], v[96:99]
	v_mfma_f32_16x16x32_bf16 v[92:95], v[200:203], v[184:187], v[92:95]
	v_mfma_f32_16x16x32_bf16 v[88:91], v[200:203], v[192:195], v[88:91]
	v_mfma_f32_16x16x32_bf16 v[84:87], v[208:211], v[184:187], v[84:87]
	v_mfma_f32_16x16x32_bf16 v[80:83], v[208:211], v[192:195], v[80:83]
	v_mfma_f32_16x16x32_bf16 v[76:79], v[216:219], v[184:187], v[76:79]
	v_mfma_f32_16x16x32_bf16 v[72:75], v[216:219], v[192:195], v[72:75]
	v_mfma_f32_16x16x32_bf16 v[68:71], v[224:227], v[184:187], v[68:71]
	v_mfma_f32_16x16x32_bf16 v[64:67], v[224:227], v[192:195], v[64:67]
	v_mfma_f32_16x16x32_bf16 v[124:127], v[204:207], v[172:175], v[124:127]
	v_mfma_f32_16x16x32_bf16 v[120:123], v[204:207], v[180:183], v[120:123]
	v_mfma_f32_16x16x32_bf16 v[116:119], v[212:215], v[172:175], v[116:119]
	v_mfma_f32_16x16x32_bf16 v[112:115], v[212:215], v[180:183], v[112:115]
	v_mfma_f32_16x16x32_bf16 v[108:111], v[220:223], v[172:175], v[108:111]
	v_mfma_f32_16x16x32_bf16 v[104:107], v[220:223], v[180:183], v[104:107]
	v_mfma_f32_16x16x32_bf16 v[100:103], v[228:231], v[172:175], v[100:103]
	v_mfma_f32_16x16x32_bf16 v[96:99], v[228:231], v[180:183], v[96:99]
	v_mfma_f32_16x16x32_bf16 v[92:95], v[204:207], v[188:191], v[92:95]
	v_mfma_f32_16x16x32_bf16 v[88:91], v[204:207], v[196:199], v[88:91]
	v_mfma_f32_16x16x32_bf16 v[84:87], v[212:215], v[188:191], v[84:87]
	v_mfma_f32_16x16x32_bf16 v[80:83], v[212:215], v[196:199], v[80:83]
	v_mfma_f32_16x16x32_bf16 v[76:79], v[220:223], v[188:191], v[76:79]
	v_mfma_f32_16x16x32_bf16 v[72:75], v[220:223], v[196:199], v[72:75]
	v_mfma_f32_16x16x32_bf16 v[68:71], v[228:231], v[188:191], v[68:71]
	v_mfma_f32_16x16x32_bf16 v[64:67], v[228:231], v[196:199], v[64:67]
	s_barrier
	s_setprio 0
	s_add_u32 s71, s32, 0x10000
	s_mov_b32 m0, s71
	ds_read_b128 v[200:203], v147 offset:16384
	ds_read_b128 v[204:207], v147 offset:17408
	ds_read_b128 v[208:211], v147 offset:18432
	ds_read_b128 v[212:215], v147 offset:19456
	ds_read_b128 v[216:219], v147 offset:20480
	ds_read_b128 v[220:223], v147 offset:21504
	ds_read_b128 v[224:227], v147 offset:22528
	ds_read_b128 v[228:231], v147 offset:23552
	s_add_u32 s92, s68, s38
	s_addc_u32 s93, s69, s39
	global_load_lds_dwordx4 v138, s[92:93]
	s_add_u32 s71, s32, 0x12000
	s_mov_b32 m0, s71
	s_add_u32 s71, s32, 0x14000
	s_add_u32 s96, s68, s38
	s_addc_u32 s97, s69, s39
	global_load_lds_dwordx4 v140, s[96:97]
	s_mov_b32 m0, s71
	s_add_u32 s71, s32, 0x16000
	s_add_u32 s88, s68, s40
	s_addc_u32 s89, s69, s41
	global_load_lds_dwordx4 v138, s[88:89]
	s_mov_b32 m0, s71
	s_mov_b32 s71, s32
	s_add_u32 s90, s68, s40
	s_addc_u32 s91, s69, s41
	global_load_lds_dwordx4 v140, s[90:91]
	s_mov_b32 m0, s71
	s_add_u32 s71, s32, 0x2000
	s_add_u32 s92, s68, s42
	s_addc_u32 s93, s69, s43
	global_load_lds_dwordx4 v142, s[92:93]
	s_mov_b32 m0, s71
	s_nop 0
	s_add_u32 s96, s68, s42
	s_addc_u32 s97, s69, s43
	global_load_lds_dwordx4 v144, s[96:97]
	s_waitcnt vmcnt(6)
	s_waitcnt lgkmcnt(0)
	s_setprio 1
	s_barrier
; #define STAGE(Pp, BASE, br, kt) do { const u16* _g = (BASE) + ((long)(br) * K + (long)(kt) * BK); \
;     __builtin_amdgcn_global_load_lds((const unsigned*)(_g + voff0), (unsigned*)((char*)(Pp) + tb16), 16, 0, 0); \
;     __builtin_amdgcn_global_load_lds((const unsigned*)(_g + voff1), (unsigned*)((char*)(Pp) + tb16 + 8192), 16, 0, 0); } while (0)
; #define LDA(dst, b, h) _Pragma("unroll") for (int m = 0; m < 4; ++m) _Pragma("unroll") for (int k = 0; k < 2; ++k) \
;     dst[m][k] = *reinterpret_cast<const bf16x8*>((const char*)shm + aB + (((b) * 2 + (h)) * 16384 + (m * 2 + k) * 1024))
; #define LDB(dst, b, h) _Pragma("unroll") for (int n = 0; n < 2; ++n) _Pragma("unroll") for (int k = 0; k < 2; ++k) \
;     dst[n][k] = *reinterpret_cast<const bf16x8*>((const char*)shm + bB + (((b) * 2 + (h)) * 16384 + (n * 2 + k) * 1024))
; #define WAIT_V(n) asm volatile("s_waitcnt vmcnt(" #n ")" ::: "memory")
; #define WAIT_L(n) asm volatile("s_waitcnt lgkmcnt(" #n ")" ::: "memory")
; #define BAR __builtin_amdgcn_s_barrier()
; #define SCHED __builtin_amdgcn_sched_barrier(0)
; template <int MODE> ...
;     ...
;       WAIT_V(6); WAIT_L(0); BAR; MMA2(1, 0, 1, 1); BAR; SCHED;
;       LDB(B0, 1, 0); LDB(B1, 1, 1); LDA(At, 1, 0); STAGE(SA(0, 1), A, brow + HALF, t + 2);
;       WAIT_L(0); BAR; MMA2(0, 0, 0, 1); BAR; SCHED;
;       LDA(At, 1, 1); STAGE(SB(1, 0), Bt, bcol, t + 3); STAGE(SB(1, 1), Bt, bcol + HALF, t + 3); STAGE(SA(1, 0), A, brow, t + 3);
;       WAIT_V(6); WAIT_L(0); BAR; MMA2(1, 0, 1, 1); BAR; SCHED;
	v_mfma_f32_16x16x32_bf16 v[60:63], v[200:203], v[168:171], v[60:63]
	v_mfma_f32_16x16x32_bf16 v[56:59], v[200:203], v[176:179], v[56:59]
	v_mfma_f32_16x16x32_bf16 v[52:55], v[208:211], v[168:171], v[52:55]
	v_mfma_f32_16x16x32_bf16 v[48:51], v[208:211], v[176:179], v[48:51]
	v_mfma_f32_16x16x32_bf16 v[44:47], v[216:219], v[168:171], v[44:47]
	v_mfma_f32_16x16x32_bf16 v[40:43], v[216:219], v[176:179], v[40:43]
	v_mfma_f32_16x16x32_bf16 v[36:39], v[224:227], v[168:171], v[36:39]
	v_mfma_f32_16x16x32_bf16 v[32:35], v[224:227], v[176:179], v[32:35]
	v_mfma_f32_16x16x32_bf16 v[28:31], v[200:203], v[184:187], v[28:31]
	v_mfma_f32_16x16x32_bf16 v[24:27], v[200:203], v[192:195], v[24:27]
	v_mfma_f32_16x16x32_bf16 v[20:23], v[208:211], v[184:187], v[20:23]
	v_mfma_f32_16x16x32_bf16 v[16:19], v[208:211], v[192:195], v[16:19]
	v_mfma_f32_16x16x32_bf16 v[12:15], v[216:219], v[184:187], v[12:15]
	v_mfma_f32_16x16x32_bf16 v[8:11], v[216:219], v[192:195], v[8:11]
	v_mfma_f32_16x16x32_bf16 v[4:7], v[224:227], v[184:187], v[4:7]
	v_mfma_f32_16x16x32_bf16 v[0:3], v[224:227], v[192:195], v[0:3]
	v_mfma_f32_16x16x32_bf16 v[60:63], v[204:207], v[172:175], v[60:63]
	v_mfma_f32_16x16x32_bf16 v[56:59], v[204:207], v[180:183], v[56:59]
	v_mfma_f32_16x16x32_bf16 v[52:55], v[212:215], v[172:175], v[52:55]
	v_mfma_f32_16x16x32_bf16 v[48:51], v[212:215], v[180:183], v[48:51]
	v_mfma_f32_16x16x32_bf16 v[44:47], v[220:223], v[172:175], v[44:47]
	v_mfma_f32_16x16x32_bf16 v[40:43], v[220:223], v[180:183], v[40:43]
	v_mfma_f32_16x16x32_bf16 v[36:39], v[228:231], v[172:175], v[36:39]
	v_mfma_f32_16x16x32_bf16 v[32:35], v[228:231], v[180:183], v[32:35]
	v_mfma_f32_16x16x32_bf16 v[28:31], v[204:207], v[188:191], v[28:31]
	v_mfma_f32_16x16x32_bf16 v[24:27], v[204:207], v[196:199], v[24:27]
	v_mfma_f32_16x16x32_bf16 v[20:23], v[212:215], v[188:191], v[20:23]
	v_mfma_f32_16x16x32_bf16 v[16:19], v[212:215], v[196:199], v[16:19]
	v_mfma_f32_16x16x32_bf16 v[12:15], v[220:223], v[188:191], v[12:15]
	v_mfma_f32_16x16x32_bf16 v[8:11], v[220:223], v[196:199], v[8:11]
	v_mfma_f32_16x16x32_bf16 v[4:7], v[228:231], v[188:191], v[4:7]
	v_mfma_f32_16x16x32_bf16 v[0:3], v[228:231], v[196:199], v[0:3]
	s_barrier
	s_setprio 0
	s_add_u32 s71, s32, 0x4000
	s_mov_b32 m0, s71
	s_add_u32 s71, s32, 0x6000
	ds_read_b128 v[168:171], v148 offset:32768
	ds_read_b128 v[172:175], v148 offset:33792
	ds_read_b128 v[176:179], v148 offset:34816
	ds_read_b128 v[180:183], v148 offset:35840
	ds_read_b128 v[184:187], v148 offset:49152
	ds_read_b128 v[188:191], v148 offset:50176
	ds_read_b128 v[192:195], v148 offset:51200
	ds_read_b128 v[196:199], v148 offset:52224
	ds_read_b128 v[200:203], v147 offset:32768
	ds_read_b128 v[204:207], v147 offset:33792
	ds_read_b128 v[208:211], v147 offset:34816
	ds_read_b128 v[212:215], v147 offset:35840
	ds_read_b128 v[216:219], v147 offset:36864
	ds_read_b128 v[220:223], v147 offset:37888
	ds_read_b128 v[224:227], v147 offset:38912
	ds_read_b128 v[228:231], v147 offset:39936
	s_add_u32 s88, s68, s44
	s_addc_u32 s89, s69, s45
	global_load_lds_dwordx4 v142, s[88:89]
	s_mov_b32 m0, s71
	s_nop 0
	s_add_u32 s90, s68, s44
	s_addc_u32 s91, s69, s45
	global_load_lds_dwordx4 v144, s[90:91]
	s_waitcnt lgkmcnt(0)
	s_setprio 1
	s_barrier
	v_mfma_f32_16x16x32_bf16 v[124:127], v[200:203], v[168:171], v[124:127]
	v_mfma_f32_16x16x32_bf16 v[120:123], v[200:203], v[176:179], v[120:123]
	v_mfma_f32_16x16x32_bf16 v[116:119], v[208:211], v[168:171], v[116:119]
	v_mfma_f32_16x16x32_bf16 v[112:115], v[208:211], v[176:179], v[112:115]
	v_mfma_f32_16x16x32_bf16 v[108:111], v[216:219], v[168:171], v[108:111]
	v_mfma_f32_16x16x32_bf16 v[104:107], v[216:219], v[176:179], v[104:107]
	v_mfma_f32_16x16x32_bf16 v[100:103], v[224:227], v[168:171], v[100:103]
	v_mfma_f32_16x16x32_bf16 v[96:99], v[224:227], v[176:179], v[96:99]
	v_mfma_f32_16x16x32_bf16 v[92:95], v[200:203], v[184:187], v[92:95]
	v_mfma_f32_16x16x32_bf16 v[88:91], v[200:203], v[192:195], v[88:91]
	v_mfma_f32_16x16x32_bf16 v[84:87], v[208:211], v[184:187], v[84:87]
	v_mfma_f32_16x16x32_bf16 v[80:83], v[208:211], v[192:195], v[80:83]
	v_mfma_f32_16x16x32_bf16 v[76:79], v[216:219], v[184:187], v[76:79]
	v_mfma_f32_16x16x32_bf16 v[72:75], v[216:219], v[192:195], v[72:75]
	v_mfma_f32_16x16x32_bf16 v[68:71], v[224:227], v[184:187], v[68:71]
	v_mfma_f32_16x16x32_bf16 v[64:67], v[224:227], v[192:195], v[64:67]
	v_mfma_f32_16x16x32_bf16 v[124:127], v[204:207], v[172:175], v[124:127]
	v_mfma_f32_16x16x32_bf16 v[120:123], v[204:207], v[180:183], v[120:123]
	v_mfma_f32_16x16x32_bf16 v[116:119], v[212:215], v[172:175], v[116:119]
	v_mfma_f32_16x16x32_bf16 v[112:115], v[212:215], v[180:183], v[112:115]
	v_mfma_f32_16x16x32_bf16 v[108:111], v[220:223], v[172:175], v[108:111]
	v_mfma_f32_16x16x32_bf16 v[104:107], v[220:223], v[180:183], v[104:107]
	v_mfma_f32_16x16x32_bf16 v[100:103], v[228:231], v[172:175], v[100:103]
	v_mfma_f32_16x16x32_bf16 v[96:99], v[228:231], v[180:183], v[96:99]
	v_mfma_f32_16x16x32_bf16 v[92:95], v[204:207], v[188:191], v[92:95]
	v_mfma_f32_16x16x32_bf16 v[88:91], v[204:207], v[196:199], v[88:91]
	v_mfma_f32_16x16x32_bf16 v[84:87], v[212:215], v[188:191], v[84:87]
	v_mfma_f32_16x16x32_bf16 v[80:83], v[212:215], v[196:199], v[80:83]
	v_mfma_f32_16x16x32_bf16 v[76:79], v[220:223], v[188:191], v[76:79]
	v_mfma_f32_16x16x32_bf16 v[72:75], v[220:223], v[196:199], v[72:75]
	v_mfma_f32_16x16x32_bf16 v[68:71], v[228:231], v[188:191], v[68:71]
	v_mfma_f32_16x16x32_bf16 v[64:67], v[228:231], v[196:199], v[64:67]
	s_barrier
; #define STAGE(Pp, BASE, br, kt) do { const u16* _g = (BASE) + ((long)(br) * K + (long)(kt) * BK); \
;     __builtin_amdgcn_global_load_lds((const unsigned*)(_g + voff0), (unsigned*)((char*)(Pp) + tb16), 16, 0, 0); \
;     __builtin_amdgcn_global_load_lds((const unsigned*)(_g + voff1), (unsigned*)((char*)(Pp) + tb16 + 8192), 16, 0, 0); } while (0)
; #define LDA(dst, b, h) _Pragma("unroll") for (int m = 0; m < 4; ++m) _Pragma("unroll") for (int k = 0; k < 2; ++k) \
;     dst[m][k] = *reinterpret_cast<const bf16x8*>((const char*)shm + aB + (((b) * 2 + (h)) * 16384 + (m * 2 + k) * 1024))
; #define LDB(dst, b, h) _Pragma("unroll") for (int n = 0; n < 2; ++n) _Pragma("unroll") for (int k = 0; k < 2; ++k) \
;     dst[n][k] = *reinterpret_cast<const bf16x8*>((const char*)shm + bB + (((b) * 2 + (h)) * 16384 + (n * 2 + k) * 1024))
; #define WAIT_V(n) asm volatile("s_waitcnt vmcnt(" #n ")" ::: "memory")
; #define WAIT_L(n) asm volatile("s_waitcnt lgkmcnt(" #n ")" ::: "memory")
; #define BAR __builtin_amdgcn_s_barrier()
; #define SCHED __builtin_amdgcn_sched_barrier(0)
; template <int MODE> ...
;     ...
;       LDA(At, 1, 1); STAGE(SB(1, 0), Bt, bcol, t + 3); STAGE(SB(1, 1), Bt, bcol + HALF, t + 3); STAGE(SA(1, 0), A, brow, t + 3);
;       WAIT_V(6); WAIT_L(0); BAR; MMA2(1, 0, 1, 1); BAR; SCHED;
;     }
;     {
;       LDB(B0, 0, 0); LDB(B1, 0, 1); LDA(At, 0, 0); STAGE(SA(1, 1), A, brow + HALF, nt - 1);
;       WAIT_L(0); BAR; MMA2(0, 0, 0, 1); BAR; SCHED;
;       LDA(At, 0, 1); WAIT_V(0); WAIT_L(0); BAR; MMA2(1, 0, 1, 1); BAR; SCHED;
	s_setprio 0
	s_add_u32 s71, s32, 0x18000
	s_mov_b32 m0, s71
	s_add_u32 s71, s32, 0x1a000
	ds_read_b128 v[200:203], v147 offset:49152
	ds_read_b128 v[204:207], v147 offset:50176
	ds_read_b128 v[208:211], v147 offset:51200
	ds_read_b128 v[212:215], v147 offset:52224
	ds_read_b128 v[216:219], v147 offset:53248
	ds_read_b128 v[220:223], v147 offset:54272
	ds_read_b128 v[224:227], v147 offset:55296
	ds_read_b128 v[228:231], v147 offset:56320
	s_add_u32 s92, s68, s48
	s_addc_u32 s93, s69, s49
	global_load_lds_dwordx4 v138, s[92:93]
	s_mov_b32 m0, s71
	s_add_u32 s71, s32, 0x1c000
	s_add_u32 s96, s68, s48
	s_addc_u32 s97, s69, s49
	global_load_lds_dwordx4 v140, s[96:97]
	s_mov_b32 m0, s71
	s_add_u32 s71, s32, 0x1e000
	s_add_u32 s88, s68, s50
	s_addc_u32 s89, s69, s51
	global_load_lds_dwordx4 v138, s[88:89]
	s_mov_b32 m0, s71
	s_add_u32 s71, s32, 0x8000
	s_add_u32 s90, s68, s50
	s_addc_u32 s91, s69, s51
	global_load_lds_dwordx4 v140, s[90:91]
	s_mov_b32 m0, s71
	s_add_u32 s71, s32, 0xa000
	s_add_u32 s92, s68, s60
	s_addc_u32 s93, s69, s61
	global_load_lds_dwordx4 v142, s[92:93]
	s_mov_b32 m0, s71
	s_nop 0
	s_add_u32 s96, s68, s60
	s_addc_u32 s97, s69, s61
	global_load_lds_dwordx4 v144, s[96:97]
	s_waitcnt vmcnt(6)
	s_waitcnt lgkmcnt(0)
	s_setprio 1
	s_barrier
	v_mfma_f32_16x16x32_bf16 v[60:63], v[200:203], v[168:171], v[60:63]
	v_mfma_f32_16x16x32_bf16 v[56:59], v[200:203], v[176:179], v[56:59]
	v_mfma_f32_16x16x32_bf16 v[52:55], v[208:211], v[168:171], v[52:55]
	v_mfma_f32_16x16x32_bf16 v[48:51], v[208:211], v[176:179], v[48:51]
	v_mfma_f32_16x16x32_bf16 v[44:47], v[216:219], v[168:171], v[44:47]
	v_mfma_f32_16x16x32_bf16 v[40:43], v[216:219], v[176:179], v[40:43]
	v_mfma_f32_16x16x32_bf16 v[36:39], v[224:227], v[168:171], v[36:39]
	v_mfma_f32_16x16x32_bf16 v[32:35], v[224:227], v[176:179], v[32:35]
	v_mfma_f32_16x16x32_bf16 v[28:31], v[200:203], v[184:187], v[28:31]
	v_mfma_f32_16x16x32_bf16 v[24:27], v[200:203], v[192:195], v[24:27]
	v_mfma_f32_16x16x32_bf16 v[20:23], v[208:211], v[184:187], v[20:23]
	v_mfma_f32_16x16x32_bf16 v[16:19], v[208:211], v[192:195], v[16:19]
	v_mfma_f32_16x16x32_bf16 v[12:15], v[216:219], v[184:187], v[12:15]
	v_mfma_f32_16x16x32_bf16 v[8:11], v[216:219], v[192:195], v[8:11]
	v_mfma_f32_16x16x32_bf16 v[4:7], v[224:227], v[184:187], v[4:7]
	v_mfma_f32_16x16x32_bf16 v[0:3], v[224:227], v[192:195], v[0:3]
	v_mfma_f32_16x16x32_bf16 v[60:63], v[204:207], v[172:175], v[60:63]
	v_mfma_f32_16x16x32_bf16 v[56:59], v[204:207], v[180:183], v[56:59]
	v_mfma_f32_16x16x32_bf16 v[52:55], v[212:215], v[172:175], v[52:55]
	v_mfma_f32_16x16x32_bf16 v[48:51], v[212:215], v[180:183], v[48:51]
	v_mfma_f32_16x16x32_bf16 v[44:47], v[220:223], v[172:175], v[44:47]
	v_mfma_f32_16x16x32_bf16 v[40:43], v[220:223], v[180:183], v[40:43]
	v_mfma_f32_16x16x32_bf16 v[36:39], v[228:231], v[172:175], v[36:39]
	v_mfma_f32_16x16x32_bf16 v[32:35], v[228:231], v[180:183], v[32:35]
	v_mfma_f32_16x16x32_bf16 v[28:31], v[204:207], v[188:191], v[28:31]
	v_mfma_f32_16x16x32_bf16 v[24:27], v[204:207], v[196:199], v[24:27]
	v_mfma_f32_16x16x32_bf16 v[20:23], v[212:215], v[188:191], v[20:23]
	v_mfma_f32_16x16x32_bf16 v[16:19], v[212:215], v[196:199], v[16:19]
	v_mfma_f32_16x16x32_bf16 v[12:15], v[220:223], v[188:191], v[12:15]
	v_mfma_f32_16x16x32_bf16 v[8:11], v[220:223], v[196:199], v[8:11]
	v_mfma_f32_16x16x32_bf16 v[4:7], v[228:231], v[188:191], v[4:7]
	v_mfma_f32_16x16x32_bf16 v[0:3], v[228:231], v[196:199], v[0:3]
	s_barrier
	s_setprio 0
	s_add_i32 s70, s70, 2
	s_add_u32 s68, s68, 0x100
	s_addc_u32 s69, s69, 0
	s_cmp_lt_u32 s70, 60
	s_cbranch_scc1 .LBB0_177
	s_add_u32 s66, s66, 0x1f80
	v_readfirstlane_b32 s68, v165
	s_addc_u32 s67, s67, 0
	s_mov_b32 m0, s68
	v_readfirstlane_b32 s68, v166
	ds_read_b128 v[138:141], v148
	ds_read_b128 v[142:145], v148 offset:1024
	ds_read_b128 v[168:171], v148 offset:2048
	ds_read_b128 v[172:175], v148 offset:3072
	ds_read_b128 v[176:179], v148 offset:16384
	ds_read_b128 v[180:183], v148 offset:17408
	ds_read_b128 v[184:187], v148 offset:18432
	ds_read_b128 v[188:191], v148 offset:19456
	ds_read_b128 v[192:195], v147
	ds_read_b128 v[196:199], v147 offset:1024
	ds_read_b128 v[200:203], v147 offset:2048
	ds_read_b128 v[204:207], v147 offset:3072
	ds_read_b128 v[208:211], v147 offset:4096
	ds_read_b128 v[212:215], v147 offset:5120
	ds_read_b128 v[216:219], v147 offset:6144
	ds_read_b128 v[220:223], v147 offset:7168
	global_load_lds_dwordx4 v134, s[66:67]
	s_mov_b32 m0, s68
	s_nop 0
	global_load_lds_dwordx4 v136, s[66:67]
	s_waitcnt lgkmcnt(0)
	s_setprio 1
	s_barrier
; #define LDA(dst, b, h) _Pragma("unroll") for (int m = 0; m < 4; ++m) _Pragma("unroll") for (int k = 0; k < 2; ++k) \
;     dst[m][k] = *reinterpret_cast<const bf16x8*>((const char*)shm + aB + (((b) * 2 + (h)) * 16384 + (m * 2 + k) * 1024))
; #define LDB(dst, b, h) _Pragma("unroll") for (int n = 0; n < 2; ++n) _Pragma("unroll") for (int k = 0; k < 2; ++k) \
;     dst[n][k] = *reinterpret_cast<const bf16x8*>((const char*)shm + bB + (((b) * 2 + (h)) * 16384 + (n * 2 + k) * 1024))
; #define WAIT_V(n) asm volatile("s_waitcnt vmcnt(" #n ")" ::: "memory")
; #define WAIT_L(n) asm volatile("s_waitcnt lgkmcnt(" #n ")" ::: "memory")
; #define BAR __builtin_amdgcn_s_barrier()
; #define SCHED __builtin_amdgcn_sched_barrier(0)
; template <int MODE> ...
;     ...
;       WAIT_L(0); BAR; MMA2(0, 0, 0, 1); BAR; SCHED;
;       LDA(At, 0, 1); WAIT_V(0); WAIT_L(0); BAR; MMA2(1, 0, 1, 1); BAR; SCHED;
;       LDB(B0, 1, 0); LDB(B1, 1, 1); LDA(At, 1, 0); WAIT_L(0); BAR; MMA2(0, 0, 0, 1); BAR; SCHED;
;       LDA(At, 1, 1); WAIT_L(0); BAR; MMA2(1, 0, 1, 1); BAR; SCHED;
	v_mfma_f32_16x16x32_bf16 v[124:127], v[192:195], v[138:141], v[124:127]
	v_mfma_f32_16x16x32_bf16 v[120:123], v[192:195], v[168:171], v[120:123]
	v_mfma_f32_16x16x32_bf16 v[116:119], v[200:203], v[138:141], v[116:119]
	v_mfma_f32_16x16x32_bf16 v[112:115], v[200:203], v[168:171], v[112:115]
	v_mfma_f32_16x16x32_bf16 v[108:111], v[208:211], v[138:141], v[108:111]
	v_mfma_f32_16x16x32_bf16 v[104:107], v[208:211], v[168:171], v[104:107]
	v_mfma_f32_16x16x32_bf16 v[100:103], v[216:219], v[138:141], v[100:103]
	v_mfma_f32_16x16x32_bf16 v[96:99], v[216:219], v[168:171], v[96:99]
	v_mfma_f32_16x16x32_bf16 v[92:95], v[192:195], v[176:179], v[92:95]
	v_mfma_f32_16x16x32_bf16 v[88:91], v[192:195], v[184:187], v[88:91]
	v_mfma_f32_16x16x32_bf16 v[84:87], v[200:203], v[176:179], v[84:87]
	v_mfma_f32_16x16x32_bf16 v[80:83], v[200:203], v[184:187], v[80:83]
	v_mfma_f32_16x16x32_bf16 v[76:79], v[208:211], v[176:179], v[76:79]
	v_mfma_f32_16x16x32_bf16 v[72:75], v[208:211], v[184:187], v[72:75]
	v_mfma_f32_16x16x32_bf16 v[68:71], v[216:219], v[176:179], v[68:71]
	v_mfma_f32_16x16x32_bf16 v[64:67], v[216:219], v[184:187], v[64:67]
	v_mfma_f32_16x16x32_bf16 v[124:127], v[196:199], v[142:145], v[124:127]
	v_mfma_f32_16x16x32_bf16 v[120:123], v[196:199], v[172:175], v[120:123]
	v_mfma_f32_16x16x32_bf16 v[116:119], v[204:207], v[142:145], v[116:119]
	v_mfma_f32_16x16x32_bf16 v[112:115], v[204:207], v[172:175], v[112:115]
	v_mfma_f32_16x16x32_bf16 v[108:111], v[212:215], v[142:145], v[108:111]
	v_mfma_f32_16x16x32_bf16 v[104:107], v[212:215], v[172:175], v[104:107]
	v_mfma_f32_16x16x32_bf16 v[100:103], v[220:223], v[142:145], v[100:103]
	v_mfma_f32_16x16x32_bf16 v[96:99], v[220:223], v[172:175], v[96:99]
	v_mfma_f32_16x16x32_bf16 v[92:95], v[196:199], v[180:183], v[92:95]
	v_mfma_f32_16x16x32_bf16 v[88:91], v[196:199], v[188:191], v[88:91]
	v_mfma_f32_16x16x32_bf16 v[84:87], v[204:207], v[180:183], v[84:87]
	v_mfma_f32_16x16x32_bf16 v[80:83], v[204:207], v[188:191], v[80:83]
	v_mfma_f32_16x16x32_bf16 v[76:79], v[212:215], v[180:183], v[76:79]
	v_mfma_f32_16x16x32_bf16 v[72:75], v[212:215], v[188:191], v[72:75]
	v_mfma_f32_16x16x32_bf16 v[68:71], v[220:223], v[180:183], v[68:71]
	v_mfma_f32_16x16x32_bf16 v[64:67], v[220:223], v[188:191], v[64:67]
	s_barrier
	s_setprio 0
	ds_read_b128 v[192:195], v147 offset:16384
	ds_read_b128 v[196:199], v147 offset:17408
	ds_read_b128 v[200:203], v147 offset:18432
	ds_read_b128 v[204:207], v147 offset:19456
	ds_read_b128 v[208:211], v147 offset:20480
	ds_read_b128 v[212:215], v147 offset:21504
	ds_read_b128 v[216:219], v147 offset:22528
	ds_read_b128 v[220:223], v147 offset:23552
	s_waitcnt vmcnt(0)
	s_waitcnt lgkmcnt(0)
	s_setprio 1
	s_barrier
	v_mfma_f32_16x16x32_bf16 v[56:59], v[192:195], v[168:171], v[56:59]
	v_mfma_f32_16x16x32_bf16 v[52:55], v[200:203], v[138:141], v[52:55]
	v_mfma_f32_16x16x32_bf16 v[48:51], v[200:203], v[168:171], v[48:51]
	v_mfma_f32_16x16x32_bf16 v[44:47], v[208:211], v[138:141], v[44:47]
	v_mfma_f32_16x16x32_bf16 v[40:43], v[208:211], v[168:171], v[40:43]
	v_mfma_f32_16x16x32_bf16 v[36:39], v[216:219], v[138:141], v[36:39]
	v_mfma_f32_16x16x32_bf16 v[32:35], v[216:219], v[168:171], v[32:35]
	v_mfma_f32_16x16x32_bf16 v[28:31], v[192:195], v[176:179], v[28:31]
	v_mfma_f32_16x16x32_bf16 v[24:27], v[192:195], v[184:187], v[24:27]
	v_mfma_f32_16x16x32_bf16 v[20:23], v[200:203], v[176:179], v[20:23]
	v_mfma_f32_16x16x32_bf16 v[16:19], v[200:203], v[184:187], v[16:19]
	v_mfma_f32_16x16x32_bf16 v[12:15], v[208:211], v[176:179], v[12:15]
	v_mfma_f32_16x16x32_bf16 v[8:11], v[208:211], v[184:187], v[8:11]
	v_mfma_f32_16x16x32_bf16 v[4:7], v[216:219], v[176:179], v[4:7]
	v_mfma_f32_16x16x32_bf16 v[0:3], v[216:219], v[184:187], v[0:3]
	v_mfma_f32_16x16x32_bf16 v[60:63], v[192:195], v[138:141], v[60:63]
	v_mfma_f32_16x16x32_bf16 v[56:59], v[196:199], v[172:175], v[56:59]
	v_mfma_f32_16x16x32_bf16 v[52:55], v[204:207], v[142:145], v[52:55]
	v_mfma_f32_16x16x32_bf16 v[48:51], v[204:207], v[172:175], v[48:51]
	v_mfma_f32_16x16x32_bf16 v[44:47], v[212:215], v[142:145], v[44:47]
	v_mfma_f32_16x16x32_bf16 v[40:43], v[212:215], v[172:175], v[40:43]
	v_mfma_f32_16x16x32_bf16 v[36:39], v[220:223], v[142:145], v[36:39]
	v_mfma_f32_16x16x32_bf16 v[32:35], v[220:223], v[172:175], v[32:35]
	v_mfma_f32_16x16x32_bf16 v[28:31], v[196:199], v[180:183], v[28:31]
	v_mfma_f32_16x16x32_bf16 v[24:27], v[196:199], v[188:191], v[24:27]
	v_mfma_f32_16x16x32_bf16 v[20:23], v[204:207], v[180:183], v[20:23]
	v_mfma_f32_16x16x32_bf16 v[16:19], v[204:207], v[188:191], v[16:19]
	v_mfma_f32_16x16x32_bf16 v[12:15], v[212:215], v[180:183], v[12:15]
	v_mfma_f32_16x16x32_bf16 v[8:11], v[212:215], v[188:191], v[8:11]
	v_mfma_f32_16x16x32_bf16 v[4:7], v[220:223], v[180:183], v[4:7]
	v_mfma_f32_16x16x32_bf16 v[0:3], v[220:223], v[188:191], v[0:3]
	v_mfma_f32_16x16x32_bf16 v[224:227], v[196:199], v[142:145], v[60:63]
	s_barrier
	s_setprio 0
	ds_read_b128 v[138:141], v148 offset:32768
	ds_read_b128 v[142:145], v148 offset:33792
	ds_read_b128 v[168:171], v148 offset:34816
	ds_read_b128 v[172:175], v148 offset:35840
	ds_read_b128 v[176:179], v148 offset:49152
	ds_read_b128 v[180:183], v148 offset:50176
	ds_read_b128 v[184:187], v148 offset:51200
	ds_read_b128 v[188:191], v148 offset:52224
	ds_read_b128 v[60:63], v147 offset:32768
	ds_read_b128 v[192:195], v147 offset:33792
	ds_read_b128 v[196:199], v147 offset:34816
	ds_read_b128 v[200:203], v147 offset:35840
	ds_read_b128 v[204:207], v147 offset:36864
	ds_read_b128 v[208:211], v147 offset:37888
	ds_read_b128 v[212:215], v147 offset:38912
	ds_read_b128 v[216:219], v147 offset:39936
	s_waitcnt lgkmcnt(0)
	s_setprio 1
	s_barrier
; #define LDA(dst, b, h) _Pragma("unroll") for (int m = 0; m < 4; ++m) _Pragma("unroll") for (int k = 0; k < 2; ++k) \
;     dst[m][k] = *reinterpret_cast<const bf16x8*>((const char*)shm + aB + (((b) * 2 + (h)) * 16384 + (m * 2 + k) * 1024))
; #define LDB(dst, b, h) _Pragma("unroll") for (int n = 0; n < 2; ++n) _Pragma("unroll") for (int k = 0; k < 2; ++k) \
;     dst[n][k] = *reinterpret_cast<const bf16x8*>((const char*)shm + bB + (((b) * 2 + (h)) * 16384 + (n * 2 + k) * 1024))
; #define WAIT_L(n) asm volatile("s_waitcnt lgkmcnt(" #n ")" ::: "memory")
; #define BAR __builtin_amdgcn_s_barrier()
; #define SCHED __builtin_amdgcn_sched_barrier(0)
; template <int MODE> ...
;     ...
;       LDB(B0, 1, 0); LDB(B1, 1, 1); LDA(At, 1, 0); WAIT_L(0); BAR; MMA2(0, 0, 0, 1); BAR; SCHED;
;       LDA(At, 1, 1); WAIT_L(0); BAR; MMA2(1, 0, 1, 1); BAR; SCHED;
;     }
;     ...
;     if (wr == 0) BAR;
	v_mfma_f32_16x16x32_bf16 v[124:127], v[60:63], v[138:141], v[124:127]
	v_mfma_f32_16x16x32_bf16 v[120:123], v[60:63], v[168:171], v[120:123]
	v_mfma_f32_16x16x32_bf16 v[92:95], v[60:63], v[176:179], v[92:95]
	v_mfma_f32_16x16x32_bf16 v[60:63], v[60:63], v[184:187], v[88:91]
	v_mfma_f32_16x16x32_bf16 v[88:91], v[192:195], v[188:191], v[60:63]
	v_mfma_f32_16x16x32_bf16 v[60:63], v[196:199], v[176:179], v[84:87]
	v_mfma_f32_16x16x32_bf16 v[84:87], v[200:203], v[180:183], v[60:63]
	v_mfma_f32_16x16x32_bf16 v[60:63], v[196:199], v[184:187], v[80:83]
	v_mfma_f32_16x16x32_bf16 v[80:83], v[200:203], v[188:191], v[60:63]
	v_mfma_f32_16x16x32_bf16 v[60:63], v[204:207], v[176:179], v[76:79]
	v_mfma_f32_16x16x32_bf16 v[76:79], v[208:211], v[180:183], v[60:63]
	v_mfma_f32_16x16x32_bf16 v[60:63], v[204:207], v[184:187], v[72:75]
	v_mfma_f32_16x16x32_bf16 v[72:75], v[208:211], v[188:191], v[60:63]
	v_mfma_f32_16x16x32_bf16 v[60:63], v[212:215], v[176:179], v[68:71]
	v_mfma_f32_16x16x32_bf16 v[116:119], v[196:199], v[138:141], v[116:119]
	v_mfma_f32_16x16x32_bf16 v[112:115], v[196:199], v[168:171], v[112:115]
	v_mfma_f32_16x16x32_bf16 v[108:111], v[204:207], v[138:141], v[108:111]
	v_mfma_f32_16x16x32_bf16 v[104:107], v[204:207], v[168:171], v[104:107]
	v_mfma_f32_16x16x32_bf16 v[100:103], v[212:215], v[138:141], v[100:103]
	v_mfma_f32_16x16x32_bf16 v[96:99], v[212:215], v[168:171], v[96:99]
	v_mfma_f32_16x16x32_bf16 v[68:71], v[216:219], v[180:183], v[60:63]
	v_mfma_f32_16x16x32_bf16 v[60:63], v[212:215], v[184:187], v[64:67]
	v_mfma_f32_16x16x32_bf16 v[124:127], v[192:195], v[142:145], v[124:127]
	v_mfma_f32_16x16x32_bf16 v[120:123], v[192:195], v[172:175], v[120:123]
	v_mfma_f32_16x16x32_bf16 v[116:119], v[200:203], v[142:145], v[116:119]
	v_mfma_f32_16x16x32_bf16 v[112:115], v[200:203], v[172:175], v[112:115]
	v_mfma_f32_16x16x32_bf16 v[108:111], v[208:211], v[142:145], v[108:111]
	v_mfma_f32_16x16x32_bf16 v[104:107], v[208:211], v[172:175], v[104:107]
	v_mfma_f32_16x16x32_bf16 v[100:103], v[216:219], v[142:145], v[100:103]
	v_mfma_f32_16x16x32_bf16 v[96:99], v[216:219], v[172:175], v[96:99]
	v_mfma_f32_16x16x32_bf16 v[92:95], v[192:195], v[180:183], v[92:95]
	v_mfma_f32_16x16x32_bf16 v[60:63], v[216:219], v[188:191], v[60:63]
	s_barrier
	s_setprio 0
	ds_read_b128 v[192:195], v147 offset:49152
	ds_read_b128 v[196:199], v147 offset:50176
	ds_read_b128 v[200:203], v147 offset:51200
	ds_read_b128 v[204:207], v147 offset:52224
	ds_read_b128 v[208:211], v147 offset:53248
	ds_read_b128 v[212:215], v147 offset:54272
	ds_read_b128 v[216:219], v147 offset:55296
	ds_read_b128 v[220:223], v147 offset:56320
	s_waitcnt lgkmcnt(0)
	s_setprio 1
	s_barrier
	v_mfma_f32_16x16x32_bf16 v[64:67], v[192:195], v[138:141], v[224:227]
	v_mfma_f32_16x16x32_bf16 v[56:59], v[192:195], v[168:171], v[56:59]
	v_mfma_f32_16x16x32_bf16 v[52:55], v[200:203], v[138:141], v[52:55]
	v_mfma_f32_16x16x32_bf16 v[48:51], v[200:203], v[168:171], v[48:51]
	v_mfma_f32_16x16x32_bf16 v[44:47], v[208:211], v[138:141], v[44:47]
	v_mfma_f32_16x16x32_bf16 v[40:43], v[208:211], v[168:171], v[40:43]
	v_mfma_f32_16x16x32_bf16 v[36:39], v[216:219], v[138:141], v[36:39]
	v_mfma_f32_16x16x32_bf16 v[32:35], v[216:219], v[168:171], v[32:35]
	v_mfma_f32_16x16x32_bf16 v[28:31], v[192:195], v[176:179], v[28:31]
	v_mfma_f32_16x16x32_bf16 v[24:27], v[192:195], v[184:187], v[24:27]
	v_mfma_f32_16x16x32_bf16 v[20:23], v[200:203], v[176:179], v[20:23]
	v_mfma_f32_16x16x32_bf16 v[16:19], v[200:203], v[184:187], v[16:19]
	v_mfma_f32_16x16x32_bf16 v[12:15], v[208:211], v[176:179], v[12:15]
	v_mfma_f32_16x16x32_bf16 v[8:11], v[208:211], v[184:187], v[8:11]
	v_mfma_f32_16x16x32_bf16 v[4:7], v[216:219], v[176:179], v[4:7]
	v_mfma_f32_16x16x32_bf16 v[0:3], v[216:219], v[184:187], v[0:3]
	v_mfma_f32_16x16x32_bf16 v[64:67], v[196:199], v[142:145], v[64:67]
	v_mfma_f32_16x16x32_bf16 v[56:59], v[196:199], v[172:175], v[56:59]
	v_mfma_f32_16x16x32_bf16 v[52:55], v[204:207], v[142:145], v[52:55]
	v_mfma_f32_16x16x32_bf16 v[48:51], v[204:207], v[172:175], v[48:51]
	v_mfma_f32_16x16x32_bf16 v[44:47], v[212:215], v[142:145], v[44:47]
	v_mfma_f32_16x16x32_bf16 v[40:43], v[212:215], v[172:175], v[40:43]
	v_mfma_f32_16x16x32_bf16 v[36:39], v[220:223], v[142:145], v[36:39]
	v_mfma_f32_16x16x32_bf16 v[32:35], v[220:223], v[172:175], v[32:35]
	v_mfma_f32_16x16x32_bf16 v[28:31], v[196:199], v[180:183], v[28:31]
	v_mfma_f32_16x16x32_bf16 v[24:27], v[196:199], v[188:191], v[24:27]
	v_mfma_f32_16x16x32_bf16 v[20:23], v[204:207], v[180:183], v[20:23]
	v_mfma_f32_16x16x32_bf16 v[16:19], v[204:207], v[188:191], v[16:19]
	v_mfma_f32_16x16x32_bf16 v[12:15], v[212:215], v[180:183], v[12:15]
	v_mfma_f32_16x16x32_bf16 v[8:11], v[212:215], v[188:191], v[8:11]
	v_mfma_f32_16x16x32_bf16 v[4:7], v[220:223], v[180:183], v[4:7]
	v_mfma_f32_16x16x32_bf16 v[0:3], v[220:223], v[188:191], v[0:3]
	s_barrier
	s_setprio 0
	s_and_saveexec_b64 s[66:67], s[6:7]
	s_cbranch_execz .LBB0_180
	s_barrier

; #define STAGE(Pp, BASE, br, kt) do { const u16* _g = (BASE) + ((long)(br) * K + (long)(kt) * BK); \
;     __builtin_amdgcn_global_load_lds((const unsigned*)(_g + voff0), (unsigned*)((char*)(Pp) + tb16), 16, 0, 0); \
;     __builtin_amdgcn_global_load_lds((const unsigned*)(_g + voff1), (unsigned*)((char*)(Pp) + tb16 + 8192), 16, 0, 0); } while (0)
; #define LDA(dst, b, h) _Pragma("unroll") for (int m = 0; m < 4; ++m) _Pragma("unroll") for (int k = 0; k < 2; ++k) \
;     dst[m][k] = *reinterpret_cast<const bf16x8*>((const char*)shm + aB + (((b) * 2 + (h)) * 16384 + (m * 2 + k) * 1024))
; #define LDB(dst, b, h) _Pragma("unroll") for (int n = 0; n < 2; ++n) _Pragma("unroll") for (int k = 0; k < 2; ++k) \
;     dst[n][k] = *reinterpret_cast<const bf16x8*>((const char*)shm + bB + (((b) * 2 + (h)) * 16384 + (n * 2 + k) * 1024))
; #define WAIT_V(n) asm volatile("s_waitcnt vmcnt(" #n ")" ::: "memory")
; #define WAIT_L(n) asm volatile("s_waitcnt lgkmcnt(" #n ")" ::: "memory")
; #define BAR __builtin_amdgcn_s_barrier()
; #define SCHED __builtin_amdgcn_sched_barrier(0)
; template <int MODE> ...
;     ...
;       LDB(B0, 0, 0); LDB(B1, 0, 1); LDA(At, 0, 0); STAGE(SA(1, 1), A, brow + HALF, t + 1);
;       WAIT_L(0); BAR; MMA2(0, 0, 0, 1); BAR; SCHED;
;       LDA(At, 0, 1); STAGE(SB(0, 0), Bt, bcol, t + 2); STAGE(SB(0, 1), Bt, bcol + HALF, t + 2); STAGE(SA(0, 0), A, brow, t + 2);
;       WAIT_V(6); WAIT_L(0); BAR; MMA2(1, 0, 1, 1); BAR; SCHED;
.LBB0_486:
	s_add_u32 s74, s32, 0xc000
	s_mov_b32 m0, s74
	ds_read_b128 v[166:169], v145
	ds_read_b128 v[170:173], v145 offset:1024
	ds_read_b128 v[174:177], v145 offset:2048
	ds_read_b128 v[178:181], v145 offset:3072
	ds_read_b128 v[182:185], v145 offset:16384
	ds_read_b128 v[186:189], v145 offset:17408
	ds_read_b128 v[190:193], v145 offset:18432
	ds_read_b128 v[194:197], v145 offset:19456
	ds_read_b128 v[198:201], v144
	ds_read_b128 v[202:205], v144 offset:1024
	ds_read_b128 v[206:209], v144 offset:2048
	ds_read_b128 v[210:213], v144 offset:3072
	ds_read_b128 v[214:217], v144 offset:4096
	ds_read_b128 v[218:221], v144 offset:5120
	ds_read_b128 v[222:225], v144 offset:6144
	ds_read_b128 v[226:229], v144 offset:7168
	s_add_u32 s88, s72, s16
	s_addc_u32 s89, s73, s17
	global_load_lds_dwordx4 v140, s[88:89]
	s_add_u32 s74, s32, 0xe000
	s_mov_b32 m0, s74
	s_nop 0
	s_add_u32 s90, s72, s16
	s_addc_u32 s91, s73, s17
	global_load_lds_dwordx4 v142, s[90:91]
	s_waitcnt lgkmcnt(0)
	s_setprio 1
	s_barrier
	v_mfma_f32_16x16x32_bf16 v[124:127], v[198:201], v[166:169], v[124:127]
	v_mfma_f32_16x16x32_bf16 v[120:123], v[198:201], v[174:177], v[120:123]
	v_mfma_f32_16x16x32_bf16 v[116:119], v[206:209], v[166:169], v[116:119]
	v_mfma_f32_16x16x32_bf16 v[112:115], v[206:209], v[174:177], v[112:115]
	v_mfma_f32_16x16x32_bf16 v[108:111], v[214:217], v[166:169], v[108:111]
	v_mfma_f32_16x16x32_bf16 v[104:107], v[214:217], v[174:177], v[104:107]
	v_mfma_f32_16x16x32_bf16 v[100:103], v[222:225], v[166:169], v[100:103]
	v_mfma_f32_16x16x32_bf16 v[96:99], v[222:225], v[174:177], v[96:99]
	v_mfma_f32_16x16x32_bf16 v[92:95], v[198:201], v[182:185], v[92:95]
	v_mfma_f32_16x16x32_bf16 v[88:91], v[198:201], v[190:193], v[88:91]
	v_mfma_f32_16x16x32_bf16 v[84:87], v[206:209], v[182:185], v[84:87]
	v_mfma_f32_16x16x32_bf16 v[80:83], v[206:209], v[190:193], v[80:83]
	v_mfma_f32_16x16x32_bf16 v[76:79], v[214:217], v[182:185], v[76:79]
	v_mfma_f32_16x16x32_bf16 v[72:75], v[214:217], v[190:193], v[72:75]
	v_mfma_f32_16x16x32_bf16 v[68:71], v[222:225], v[182:185], v[68:71]
	v_mfma_f32_16x16x32_bf16 v[64:67], v[222:225], v[190:193], v[64:67]
	v_mfma_f32_16x16x32_bf16 v[124:127], v[202:205], v[170:173], v[124:127]
	v_mfma_f32_16x16x32_bf16 v[120:123], v[202:205], v[178:181], v[120:123]
	v_mfma_f32_16x16x32_bf16 v[116:119], v[210:213], v[170:173], v[116:119]
	v_mfma_f32_16x16x32_bf16 v[112:115], v[210:213], v[178:181], v[112:115]
	v_mfma_f32_16x16x32_bf16 v[108:111], v[218:221], v[170:173], v[108:111]
	v_mfma_f32_16x16x32_bf16 v[104:107], v[218:221], v[178:181], v[104:107]
	v_mfma_f32_16x16x32_bf16 v[100:103], v[226:229], v[170:173], v[100:103]
	v_mfma_f32_16x16x32_bf16 v[96:99], v[226:229], v[178:181], v[96:99]
	v_mfma_f32_16x16x32_bf16 v[92:95], v[202:205], v[186:189], v[92:95]
	v_mfma_f32_16x16x32_bf16 v[88:91], v[202:205], v[194:197], v[88:91]
	v_mfma_f32_16x16x32_bf16 v[84:87], v[210:213], v[186:189], v[84:87]
	v_mfma_f32_16x16x32_bf16 v[80:83], v[210:213], v[194:197], v[80:83]
	v_mfma_f32_16x16x32_bf16 v[76:79], v[218:221], v[186:189], v[76:79]
	v_mfma_f32_16x16x32_bf16 v[72:75], v[218:221], v[194:197], v[72:75]
	v_mfma_f32_16x16x32_bf16 v[68:71], v[226:229], v[186:189], v[68:71]
	v_mfma_f32_16x16x32_bf16 v[64:67], v[226:229], v[194:197], v[64:67]
	s_barrier
	s_setprio 0
	s_add_u32 s74, s32, 0x10000
	s_mov_b32 m0, s74
	ds_read_b128 v[198:201], v144 offset:16384
	ds_read_b128 v[202:205], v144 offset:17408
	ds_read_b128 v[206:209], v144 offset:18432
	ds_read_b128 v[210:213], v144 offset:19456
	ds_read_b128 v[214:217], v144 offset:20480
	ds_read_b128 v[218:221], v144 offset:21504
	ds_read_b128 v[222:225], v144 offset:22528
	ds_read_b128 v[226:229], v144 offset:23552
	s_add_u32 s92, s72, s38
	s_addc_u32 s93, s73, s39
	global_load_lds_dwordx4 v136, s[92:93]
	s_add_u32 s74, s32, 0x12000
	s_mov_b32 m0, s74
	s_add_u32 s74, s32, 0x14000
	s_add_u32 s96, s72, s38
	s_addc_u32 s97, s73, s39
	global_load_lds_dwordx4 v138, s[96:97]
	s_mov_b32 m0, s74
	s_add_u32 s74, s32, 0x16000
	s_add_u32 s88, s72, s40
	s_addc_u32 s89, s73, s41
	global_load_lds_dwordx4 v136, s[88:89]
	s_mov_b32 m0, s74
	s_mov_b32 s74, s32
	s_add_u32 s90, s72, s40
	s_addc_u32 s91, s73, s41
	global_load_lds_dwordx4 v138, s[90:91]
	s_mov_b32 m0, s74
	s_add_u32 s74, s32, 0x2000
	s_add_u32 s92, s72, s42
	s_addc_u32 s93, s73, s43
	global_load_lds_dwordx4 v140, s[92:93]
	s_mov_b32 m0, s74
	s_nop 0
	s_add_u32 s96, s72, s42
	s_addc_u32 s97, s73, s43
	global_load_lds_dwordx4 v142, s[96:97]
	s_waitcnt vmcnt(6)
	s_waitcnt lgkmcnt(0)
	s_setprio 1
	s_barrier
; #define STAGE(Pp, BASE, br, kt) do { const u16* _g = (BASE) + ((long)(br) * K + (long)(kt) * BK); \
;     __builtin_amdgcn_global_load_lds((const unsigned*)(_g + voff0), (unsigned*)((char*)(Pp) + tb16), 16, 0, 0); \
;     __builtin_amdgcn_global_load_lds((const unsigned*)(_g + voff1), (unsigned*)((char*)(Pp) + tb16 + 8192), 16, 0, 0); } while (0)
; #define LDA(dst, b, h) _Pragma("unroll") for (int m = 0; m < 4; ++m) _Pragma("unroll") for (int k = 0; k < 2; ++k) \
;     dst[m][k] = *reinterpret_cast<const bf16x8*>((const char*)shm + aB + (((b) * 2 + (h)) * 16384 + (m * 2 + k) * 1024))
; #define LDB(dst, b, h) _Pragma("unroll") for (int n = 0; n < 2; ++n) _Pragma("unroll") for (int k = 0; k < 2; ++k) \
;     dst[n][k] = *reinterpret_cast<const bf16x8*>((const char*)shm + bB + (((b) * 2 + (h)) * 16384 + (n * 2 + k) * 1024))
; #define WAIT_V(n) asm volatile("s_waitcnt vmcnt(" #n ")" ::: "memory")
; #define WAIT_L(n) asm volatile("s_waitcnt lgkmcnt(" #n ")" ::: "memory")
; #define BAR __builtin_amdgcn_s_barrier()
; #define SCHED __builtin_amdgcn_sched_barrier(0)
; template <int MODE> ...
;     ...
;       WAIT_V(6); WAIT_L(0); BAR; MMA2(1, 0, 1, 1); BAR; SCHED;
;       LDB(B0, 1, 0); LDB(B1, 1, 1); LDA(At, 1, 0); STAGE(SA(0, 1), A, brow + HALF, t + 2);
;       WAIT_L(0); BAR; MMA2(0, 0, 0, 1); BAR; SCHED;
	v_mfma_f32_16x16x32_bf16 v[60:63], v[198:201], v[166:169], v[60:63]
	v_mfma_f32_16x16x32_bf16 v[56:59], v[198:201], v[174:177], v[56:59]
	v_mfma_f32_16x16x32_bf16 v[52:55], v[206:209], v[166:169], v[52:55]
	v_mfma_f32_16x16x32_bf16 v[48:51], v[206:209], v[174:177], v[48:51]
	v_mfma_f32_16x16x32_bf16 v[44:47], v[214:217], v[166:169], v[44:47]
	v_mfma_f32_16x16x32_bf16 v[40:43], v[214:217], v[174:177], v[40:43]
	v_mfma_f32_16x16x32_bf16 v[36:39], v[222:225], v[166:169], v[36:39]
	v_mfma_f32_16x16x32_bf16 v[32:35], v[222:225], v[174:177], v[32:35]
	v_mfma_f32_16x16x32_bf16 v[28:31], v[198:201], v[182:185], v[28:31]
	v_mfma_f32_16x16x32_bf16 v[24:27], v[198:201], v[190:193], v[24:27]
	v_mfma_f32_16x16x32_bf16 v[20:23], v[206:209], v[182:185], v[20:23]
	v_mfma_f32_16x16x32_bf16 v[16:19], v[206:209], v[190:193], v[16:19]
	v_mfma_f32_16x16x32_bf16 v[12:15], v[214:217], v[182:185], v[12:15]
	v_mfma_f32_16x16x32_bf16 v[8:11], v[214:217], v[190:193], v[8:11]
	v_mfma_f32_16x16x32_bf16 v[4:7], v[222:225], v[182:185], v[4:7]
	v_mfma_f32_16x16x32_bf16 v[0:3], v[222:225], v[190:193], v[0:3]
	v_mfma_f32_16x16x32_bf16 v[60:63], v[202:205], v[170:173], v[60:63]
	v_mfma_f32_16x16x32_bf16 v[56:59], v[202:205], v[178:181], v[56:59]
	v_mfma_f32_16x16x32_bf16 v[52:55], v[210:213], v[170:173], v[52:55]
	v_mfma_f32_16x16x32_bf16 v[48:51], v[210:213], v[178:181], v[48:51]
	v_mfma_f32_16x16x32_bf16 v[44:47], v[218:221], v[170:173], v[44:47]
	v_mfma_f32_16x16x32_bf16 v[40:43], v[218:221], v[178:181], v[40:43]
	v_mfma_f32_16x16x32_bf16 v[36:39], v[226:229], v[170:173], v[36:39]
	v_mfma_f32_16x16x32_bf16 v[32:35], v[226:229], v[178:181], v[32:35]
	v_mfma_f32_16x16x32_bf16 v[28:31], v[202:205], v[186:189], v[28:31]
	v_mfma_f32_16x16x32_bf16 v[24:27], v[202:205], v[194:197], v[24:27]
	v_mfma_f32_16x16x32_bf16 v[20:23], v[210:213], v[186:189], v[20:23]
	v_mfma_f32_16x16x32_bf16 v[16:19], v[210:213], v[194:197], v[16:19]
	v_mfma_f32_16x16x32_bf16 v[12:15], v[218:221], v[186:189], v[12:15]
	v_mfma_f32_16x16x32_bf16 v[8:11], v[218:221], v[194:197], v[8:11]
	v_mfma_f32_16x16x32_bf16 v[4:7], v[226:229], v[186:189], v[4:7]
	v_mfma_f32_16x16x32_bf16 v[0:3], v[226:229], v[194:197], v[0:3]
	s_barrier
	s_setprio 0
	s_add_u32 s74, s32, 0x4000
	s_mov_b32 m0, s74
	s_add_u32 s74, s32, 0x6000
	ds_read_b128 v[166:169], v145 offset:32768
	ds_read_b128 v[170:173], v145 offset:33792
	ds_read_b128 v[174:177], v145 offset:34816
	ds_read_b128 v[178:181], v145 offset:35840
	ds_read_b128 v[182:185], v145 offset:49152
	ds_read_b128 v[186:189], v145 offset:50176
	ds_read_b128 v[190:193], v145 offset:51200
	ds_read_b128 v[194:197], v145 offset:52224
	ds_read_b128 v[198:201], v144 offset:32768
	ds_read_b128 v[202:205], v144 offset:33792
	ds_read_b128 v[206:209], v144 offset:34816
	ds_read_b128 v[210:213], v144 offset:35840
	ds_read_b128 v[214:217], v144 offset:36864
	ds_read_b128 v[218:221], v144 offset:37888
	ds_read_b128 v[222:225], v144 offset:38912
	ds_read_b128 v[226:229], v144 offset:39936
	s_add_u32 s88, s72, s44
	s_addc_u32 s89, s73, s45
	global_load_lds_dwordx4 v140, s[88:89]
	s_mov_b32 m0, s74
	s_nop 0
	s_add_u32 s90, s72, s44
	s_addc_u32 s91, s73, s45
	global_load_lds_dwordx4 v142, s[90:91]
	s_waitcnt lgkmcnt(0)
	s_setprio 1
	s_barrier
	v_mfma_f32_16x16x32_bf16 v[124:127], v[198:201], v[166:169], v[124:127]
	v_mfma_f32_16x16x32_bf16 v[120:123], v[198:201], v[174:177], v[120:123]
	v_mfma_f32_16x16x32_bf16 v[116:119], v[206:209], v[166:169], v[116:119]
	v_mfma_f32_16x16x32_bf16 v[112:115], v[206:209], v[174:177], v[112:115]
	v_mfma_f32_16x16x32_bf16 v[108:111], v[214:217], v[166:169], v[108:111]
	v_mfma_f32_16x16x32_bf16 v[104:107], v[214:217], v[174:177], v[104:107]
	v_mfma_f32_16x16x32_bf16 v[100:103], v[222:225], v[166:169], v[100:103]
	v_mfma_f32_16x16x32_bf16 v[96:99], v[222:225], v[174:177], v[96:99]
	v_mfma_f32_16x16x32_bf16 v[92:95], v[198:201], v[182:185], v[92:95]
	v_mfma_f32_16x16x32_bf16 v[88:91], v[198:201], v[190:193], v[88:91]
	v_mfma_f32_16x16x32_bf16 v[84:87], v[206:209], v[182:185], v[84:87]
	v_mfma_f32_16x16x32_bf16 v[80:83], v[206:209], v[190:193], v[80:83]
	v_mfma_f32_16x16x32_bf16 v[76:79], v[214:217], v[182:185], v[76:79]
	v_mfma_f32_16x16x32_bf16 v[72:75], v[214:217], v[190:193], v[72:75]
	v_mfma_f32_16x16x32_bf16 v[68:71], v[222:225], v[182:185], v[68:71]
	v_mfma_f32_16x16x32_bf16 v[64:67], v[222:225], v[190:193], v[64:67]
	v_mfma_f32_16x16x32_bf16 v[124:127], v[202:205], v[170:173], v[124:127]
	v_mfma_f32_16x16x32_bf16 v[120:123], v[202:205], v[178:181], v[120:123]
	v_mfma_f32_16x16x32_bf16 v[116:119], v[210:213], v[170:173], v[116:119]
	v_mfma_f32_16x16x32_bf16 v[112:115], v[210:213], v[178:181], v[112:115]
	v_mfma_f32_16x16x32_bf16 v[108:111], v[218:221], v[170:173], v[108:111]
	v_mfma_f32_16x16x32_bf16 v[104:107], v[218:221], v[178:181], v[104:107]
	v_mfma_f32_16x16x32_bf16 v[100:103], v[226:229], v[170:173], v[100:103]
	v_mfma_f32_16x16x32_bf16 v[96:99], v[226:229], v[178:181], v[96:99]
	v_mfma_f32_16x16x32_bf16 v[92:95], v[202:205], v[186:189], v[92:95]
	v_mfma_f32_16x16x32_bf16 v[88:91], v[202:205], v[194:197], v[88:91]
	v_mfma_f32_16x16x32_bf16 v[84:87], v[210:213], v[186:189], v[84:87]
	v_mfma_f32_16x16x32_bf16 v[80:83], v[210:213], v[194:197], v[80:83]
	v_mfma_f32_16x16x32_bf16 v[76:79], v[218:221], v[186:189], v[76:79]
	v_mfma_f32_16x16x32_bf16 v[72:75], v[218:221], v[194:197], v[72:75]
	v_mfma_f32_16x16x32_bf16 v[68:71], v[226:229], v[186:189], v[68:71]
	v_mfma_f32_16x16x32_bf16 v[64:67], v[226:229], v[194:197], v[64:67]
	s_barrier
; #define STAGE(Pp, BASE, br, kt) do { const u16* _g = (BASE) + ((long)(br) * K + (long)(kt) * BK); \
;     __builtin_amdgcn_global_load_lds((const unsigned*)(_g + voff0), (unsigned*)((char*)(Pp) + tb16), 16, 0, 0); \
;     __builtin_amdgcn_global_load_lds((const unsigned*)(_g + voff1), (unsigned*)((char*)(Pp) + tb16 + 8192), 16, 0, 0); } while (0)
; #define LDA(dst, b, h) _Pragma("unroll") for (int m = 0; m < 4; ++m) _Pragma("unroll") for (int k = 0; k < 2; ++k) \
;     dst[m][k] = *reinterpret_cast<const bf16x8*>((const char*)shm + aB + (((b) * 2 + (h)) * 16384 + (m * 2 + k) * 1024))
; #define LDB(dst, b, h) _Pragma("unroll") for (int n = 0; n < 2; ++n) _Pragma("unroll") for (int k = 0; k < 2; ++k) \
;     dst[n][k] = *reinterpret_cast<const bf16x8*>((const char*)shm + bB + (((b) * 2 + (h)) * 16384 + (n * 2 + k) * 1024))
; #define WAIT_V(n) asm volatile("s_waitcnt vmcnt(" #n ")" ::: "memory")
; #define WAIT_L(n) asm volatile("s_waitcnt lgkmcnt(" #n ")" ::: "memory")
; #define BAR __builtin_amdgcn_s_barrier()
; #define SCHED __builtin_amdgcn_sched_barrier(0)
; template <int MODE> ...
;     ...
;       LDA(At, 1, 1); STAGE(SB(1, 0), Bt, bcol, t + 3); STAGE(SB(1, 1), Bt, bcol + HALF, t + 3); STAGE(SA(1, 0), A, brow, t + 3);
;       WAIT_V(6); WAIT_L(0); BAR; MMA2(1, 0, 1, 1); BAR; SCHED;
;     }
;     {
;       LDB(B0, 0, 0); LDB(B1, 0, 1); LDA(At, 0, 0); STAGE(SA(1, 1), A, brow + HALF, nt - 1);
;       WAIT_L(0); BAR; MMA2(0, 0, 0, 1); BAR; SCHED;
	s_setprio 0
	s_add_u32 s74, s32, 0x18000
	s_mov_b32 m0, s74
	s_add_u32 s74, s32, 0x1a000
	ds_read_b128 v[198:201], v144 offset:49152
	ds_read_b128 v[202:205], v144 offset:50176
	ds_read_b128 v[206:209], v144 offset:51200
	ds_read_b128 v[210:213], v144 offset:52224
	ds_read_b128 v[214:217], v144 offset:53248
	ds_read_b128 v[218:221], v144 offset:54272
	ds_read_b128 v[222:225], v144 offset:55296
	ds_read_b128 v[226:229], v144 offset:56320
	s_add_u32 s92, s72, s48
	s_addc_u32 s93, s73, s49
	global_load_lds_dwordx4 v136, s[92:93]
	s_mov_b32 m0, s74
	s_add_u32 s74, s32, 0x1c000
	s_add_u32 s96, s72, s48
	s_addc_u32 s97, s73, s49
	global_load_lds_dwordx4 v138, s[96:97]
	s_mov_b32 m0, s74
	s_add_u32 s74, s32, 0x1e000
	s_add_u32 s88, s72, s50
	s_addc_u32 s89, s73, s51
	global_load_lds_dwordx4 v136, s[88:89]
	s_mov_b32 m0, s74
	s_add_u32 s74, s32, 0x8000
	s_add_u32 s90, s72, s50
	s_addc_u32 s91, s73, s51
	global_load_lds_dwordx4 v138, s[90:91]
	s_mov_b32 m0, s74
	s_add_u32 s74, s32, 0xa000
	s_add_u32 s92, s72, s60
	s_addc_u32 s93, s73, s61
	global_load_lds_dwordx4 v140, s[92:93]
	s_mov_b32 m0, s74
	s_nop 0
	s_add_u32 s96, s72, s60
	s_addc_u32 s97, s73, s61
	global_load_lds_dwordx4 v142, s[96:97]
	s_waitcnt vmcnt(6)
	s_waitcnt lgkmcnt(0)
	s_setprio 1
	s_barrier
	v_mfma_f32_16x16x32_bf16 v[60:63], v[198:201], v[166:169], v[60:63]
	v_mfma_f32_16x16x32_bf16 v[56:59], v[198:201], v[174:177], v[56:59]
	v_mfma_f32_16x16x32_bf16 v[52:55], v[206:209], v[166:169], v[52:55]
	v_mfma_f32_16x16x32_bf16 v[48:51], v[206:209], v[174:177], v[48:51]
	v_mfma_f32_16x16x32_bf16 v[44:47], v[214:217], v[166:169], v[44:47]
	v_mfma_f32_16x16x32_bf16 v[40:43], v[214:217], v[174:177], v[40:43]
	v_mfma_f32_16x16x32_bf16 v[36:39], v[222:225], v[166:169], v[36:39]
	v_mfma_f32_16x16x32_bf16 v[32:35], v[222:225], v[174:177], v[32:35]
	v_mfma_f32_16x16x32_bf16 v[28:31], v[198:201], v[182:185], v[28:31]
	v_mfma_f32_16x16x32_bf16 v[24:27], v[198:201], v[190:193], v[24:27]
	v_mfma_f32_16x16x32_bf16 v[20:23], v[206:209], v[182:185], v[20:23]
	v_mfma_f32_16x16x32_bf16 v[16:19], v[206:209], v[190:193], v[16:19]
	v_mfma_f32_16x16x32_bf16 v[12:15], v[214:217], v[182:185], v[12:15]
	v_mfma_f32_16x16x32_bf16 v[8:11], v[214:217], v[190:193], v[8:11]
	v_mfma_f32_16x16x32_bf16 v[4:7], v[222:225], v[182:185], v[4:7]
	v_mfma_f32_16x16x32_bf16 v[0:3], v[222:225], v[190:193], v[0:3]
	v_mfma_f32_16x16x32_bf16 v[60:63], v[202:205], v[170:173], v[60:63]
	v_mfma_f32_16x16x32_bf16 v[56:59], v[202:205], v[178:181], v[56:59]
	v_mfma_f32_16x16x32_bf16 v[52:55], v[210:213], v[170:173], v[52:55]
	v_mfma_f32_16x16x32_bf16 v[48:51], v[210:213], v[178:181], v[48:51]
	v_mfma_f32_16x16x32_bf16 v[44:47], v[218:221], v[170:173], v[44:47]
	v_mfma_f32_16x16x32_bf16 v[40:43], v[218:221], v[178:181], v[40:43]
	v_mfma_f32_16x16x32_bf16 v[36:39], v[226:229], v[170:173], v[36:39]
	v_mfma_f32_16x16x32_bf16 v[32:35], v[226:229], v[178:181], v[32:35]
	v_mfma_f32_16x16x32_bf16 v[28:31], v[202:205], v[186:189], v[28:31]
	v_mfma_f32_16x16x32_bf16 v[24:27], v[202:205], v[194:197], v[24:27]
	v_mfma_f32_16x16x32_bf16 v[20:23], v[210:213], v[186:189], v[20:23]
	v_mfma_f32_16x16x32_bf16 v[16:19], v[210:213], v[194:197], v[16:19]
	v_mfma_f32_16x16x32_bf16 v[12:15], v[218:221], v[186:189], v[12:15]
	v_mfma_f32_16x16x32_bf16 v[8:11], v[218:221], v[194:197], v[8:11]
	v_mfma_f32_16x16x32_bf16 v[4:7], v[226:229], v[186:189], v[4:7]
	v_mfma_f32_16x16x32_bf16 v[0:3], v[226:229], v[194:197], v[0:3]
	s_barrier
	s_setprio 0
	s_add_i32 s63, s63, 2
	s_add_u32 s72, s72, 0x100
	s_addc_u32 s73, s73, 0
	s_cmp_lt_u32 s63, 60
	s_cbranch_scc1 .LBB0_486
	s_add_u32 s70, s70, 0x1f80
	v_readfirstlane_b32 s63, v160
	s_addc_u32 s71, s71, 0
	s_mov_b32 m0, s63
	v_readfirstlane_b32 s63, v161
	ds_read_b128 v[136:139], v145
	ds_read_b128 v[140:143], v145 offset:1024
	ds_read_b128 v[166:169], v145 offset:2048
	ds_read_b128 v[170:173], v145 offset:3072
	ds_read_b128 v[174:177], v145 offset:16384
	ds_read_b128 v[178:181], v145 offset:17408
	ds_read_b128 v[182:185], v145 offset:18432
	ds_read_b128 v[186:189], v145 offset:19456
	ds_read_b128 v[190:193], v144
	ds_read_b128 v[194:197], v144 offset:1024
	ds_read_b128 v[198:201], v144 offset:2048
	ds_read_b128 v[202:205], v144 offset:3072
	ds_read_b128 v[206:209], v144 offset:4096
	ds_read_b128 v[210:213], v144 offset:5120
	ds_read_b128 v[214:217], v144 offset:6144
	ds_read_b128 v[218:221], v144 offset:7168
	global_load_lds_dwordx4 v132, s[70:71]
	s_mov_b32 m0, s63
	s_nop 0
	global_load_lds_dwordx4 v134, s[70:71]
	s_waitcnt lgkmcnt(0)
	s_setprio 1
	s_barrier
; #define LDA(dst, b, h) _Pragma("unroll") for (int m = 0; m < 4; ++m) _Pragma("unroll") for (int k = 0; k < 2; ++k) \
;     dst[m][k] = *reinterpret_cast<const bf16x8*>((const char*)shm + aB + (((b) * 2 + (h)) * 16384 + (m * 2 + k) * 1024))
; #define WAIT_V(n) asm volatile("s_waitcnt vmcnt(" #n ")" ::: "memory")
; #define WAIT_L(n) asm volatile("s_waitcnt lgkmcnt(" #n ")" ::: "memory")
; #define BAR __builtin_amdgcn_s_barrier()
; #define SCHED __builtin_amdgcn_sched_barrier(0)
; template <int MODE> ...
;     ...
;       WAIT_L(0); BAR; MMA2(0, 0, 0, 1); BAR; SCHED;
;       LDA(At, 0, 1); WAIT_V(0); WAIT_L(0); BAR; MMA2(1, 0, 1, 1); BAR; SCHED;
	v_mfma_f32_16x16x32_bf16 v[124:127], v[190:193], v[136:139], v[124:127]
	v_mfma_f32_16x16x32_bf16 v[116:119], v[198:201], v[136:139], v[116:119]
	v_mfma_f32_16x16x32_bf16 v[108:111], v[206:209], v[136:139], v[108:111]
	v_mfma_f32_16x16x32_bf16 v[100:103], v[214:217], v[136:139], v[100:103]
	v_mfma_f32_16x16x32_bf16 v[96:99], v[214:217], v[166:169], v[96:99]
	v_mfma_f32_16x16x32_bf16 v[92:95], v[190:193], v[174:177], v[92:95]
	v_mfma_f32_16x16x32_bf16 v[88:91], v[190:193], v[182:185], v[88:91]
	v_mfma_f32_16x16x32_bf16 v[80:83], v[198:201], v[182:185], v[80:83]
	v_mfma_f32_16x16x32_bf16 v[76:79], v[206:209], v[174:177], v[76:79]
	v_mfma_f32_16x16x32_bf16 v[124:127], v[194:197], v[140:143], v[124:127]
	v_mfma_f32_16x16x32_bf16 v[120:123], v[190:193], v[166:169], v[120:123]
	v_mfma_f32_16x16x32_bf16 v[116:119], v[202:205], v[140:143], v[116:119]
	v_mfma_f32_16x16x32_bf16 v[112:115], v[198:201], v[166:169], v[112:115]
	v_mfma_f32_16x16x32_bf16 v[108:111], v[210:213], v[140:143], v[108:111]
	v_mfma_f32_16x16x32_bf16 v[104:107], v[206:209], v[166:169], v[104:107]
	v_mfma_f32_16x16x32_bf16 v[100:103], v[218:221], v[140:143], v[100:103]
	v_mfma_f32_16x16x32_bf16 v[96:99], v[218:221], v[170:173], v[96:99]
	v_mfma_f32_16x16x32_bf16 v[92:95], v[194:197], v[178:181], v[92:95]
	v_mfma_f32_16x16x32_bf16 v[88:91], v[194:197], v[186:189], v[88:91]
	v_mfma_f32_16x16x32_bf16 v[84:87], v[198:201], v[174:177], v[84:87]
	v_mfma_f32_16x16x32_bf16 v[80:83], v[202:205], v[186:189], v[80:83]
	v_mfma_f32_16x16x32_bf16 v[76:79], v[210:213], v[178:181], v[76:79]
	v_mfma_f32_16x16x32_bf16 v[72:75], v[206:209], v[182:185], v[72:75]
	v_mfma_f32_16x16x32_bf16 v[68:71], v[214:217], v[174:177], v[68:71]
	v_mfma_f32_16x16x32_bf16 v[64:67], v[214:217], v[182:185], v[64:67]
	v_mfma_f32_16x16x32_bf16 v[222:225], v[194:197], v[170:173], v[120:123]
	v_mfma_f32_16x16x32_bf16 v[226:229], v[202:205], v[170:173], v[112:115]
	v_mfma_f32_16x16x32_bf16 v[230:233], v[210:213], v[170:173], v[104:107]
	v_mfma_f32_16x16x32_bf16 v[190:193], v[202:205], v[178:181], v[84:87]
	v_mfma_f32_16x16x32_bf16 v[194:197], v[210:213], v[186:189], v[72:75]
	v_mfma_f32_16x16x32_bf16 v[198:201], v[218:221], v[178:181], v[68:71]
	v_mfma_f32_16x16x32_bf16 v[202:205], v[218:221], v[186:189], v[64:67]
	s_barrier
	s_setprio 0
	s_nop 0
	ds_read_b128 v[64:67], v144 offset:16384
	ds_read_b128 v[68:71], v144 offset:17408
	ds_read_b128 v[72:75], v144 offset:18432
	ds_read_b128 v[84:87], v144 offset:19456
	ds_read_b128 v[104:107], v144 offset:20480
	ds_read_b128 v[112:115], v144 offset:21504
	ds_read_b128 v[120:123], v144 offset:22528
	ds_read_b128 v[206:209], v144 offset:23552
	s_waitcnt vmcnt(0)
	s_waitcnt lgkmcnt(0)
	s_setprio 1
	s_barrier
	v_mfma_f32_16x16x32_bf16 v[60:63], v[64:67], v[136:139], v[60:63]
	v_mfma_f32_16x16x32_bf16 v[56:59], v[64:67], v[166:169], v[56:59]
	v_mfma_f32_16x16x32_bf16 v[52:55], v[72:75], v[136:139], v[52:55]
	v_mfma_f32_16x16x32_bf16 v[48:51], v[72:75], v[166:169], v[48:51]
	v_mfma_f32_16x16x32_bf16 v[44:47], v[104:107], v[136:139], v[44:47]
	v_mfma_f32_16x16x32_bf16 v[40:43], v[104:107], v[166:169], v[40:43]
	v_mfma_f32_16x16x32_bf16 v[28:31], v[64:67], v[174:177], v[28:31]
	v_mfma_f32_16x16x32_bf16 v[24:27], v[64:67], v[182:185], v[24:27]
	v_mfma_f32_16x16x32_bf16 v[20:23], v[72:75], v[174:177], v[20:23]
	v_mfma_f32_16x16x32_bf16 v[60:63], v[68:71], v[140:143], v[60:63]
	v_mfma_f32_16x16x32_bf16 v[56:59], v[68:71], v[170:173], v[56:59]
	v_mfma_f32_16x16x32_bf16 v[52:55], v[84:87], v[140:143], v[52:55]
	v_mfma_f32_16x16x32_bf16 v[48:51], v[84:87], v[170:173], v[48:51]
	v_mfma_f32_16x16x32_bf16 v[44:47], v[112:115], v[140:143], v[44:47]
	v_mfma_f32_16x16x32_bf16 v[40:43], v[112:115], v[170:173], v[40:43]
	v_mfma_f32_16x16x32_bf16 v[36:39], v[120:123], v[136:139], v[36:39]
	v_mfma_f32_16x16x32_bf16 v[32:35], v[120:123], v[166:169], v[32:35]
	v_mfma_f32_16x16x32_bf16 v[28:31], v[68:71], v[178:181], v[28:31]
	v_mfma_f32_16x16x32_bf16 v[24:27], v[68:71], v[186:189], v[24:27]
	v_mfma_f32_16x16x32_bf16 v[20:23], v[84:87], v[178:181], v[20:23]
	v_mfma_f32_16x16x32_bf16 v[16:19], v[72:75], v[182:185], v[16:19]
	v_mfma_f32_16x16x32_bf16 v[12:15], v[104:107], v[174:177], v[12:15]
	v_mfma_f32_16x16x32_bf16 v[8:11], v[104:107], v[182:185], v[8:11]
	v_mfma_f32_16x16x32_bf16 v[4:7], v[120:123], v[174:177], v[4:7]
	v_mfma_f32_16x16x32_bf16 v[0:3], v[120:123], v[182:185], v[0:3]
	v_mfma_f32_16x16x32_bf16 v[136:139], v[206:209], v[140:143], v[36:39]
	v_mfma_f32_16x16x32_bf16 v[140:143], v[206:209], v[170:173], v[32:35]
	v_mfma_f32_16x16x32_bf16 v[166:169], v[84:87], v[186:189], v[16:19]
	v_mfma_f32_16x16x32_bf16 v[170:173], v[112:115], v[178:181], v[12:15]
	v_mfma_f32_16x16x32_bf16 v[210:213], v[112:115], v[186:189], v[8:11]
	v_mfma_f32_16x16x32_bf16 v[174:177], v[206:209], v[178:181], v[4:7]
	v_mfma_f32_16x16x32_bf16 v[178:181], v[206:209], v[186:189], v[0:3]
	s_barrier
; #define LDA(dst, b, h) _Pragma("unroll") for (int m = 0; m < 4; ++m) _Pragma("unroll") for (int k = 0; k < 2; ++k) \
;     dst[m][k] = *reinterpret_cast<const bf16x8*>((const char*)shm + aB + (((b) * 2 + (h)) * 16384 + (m * 2 + k) * 1024))
; #define LDB(dst, b, h) _Pragma("unroll") for (int n = 0; n < 2; ++n) _Pragma("unroll") for (int k = 0; k < 2; ++k) \
;     dst[n][k] = *reinterpret_cast<const bf16x8*>((const char*)shm + bB + (((b) * 2 + (h)) * 16384 + (n * 2 + k) * 1024))
; #define WAIT_L(n) asm volatile("s_waitcnt lgkmcnt(" #n ")" ::: "memory")
; #define BAR __builtin_amdgcn_s_barrier()
; #define SCHED __builtin_amdgcn_sched_barrier(0)
; template <int MODE> ...
;     ...
;       LDB(B0, 1, 0); LDB(B1, 1, 1); LDA(At, 1, 0); WAIT_L(0); BAR; MMA2(0, 0, 0, 1); BAR; SCHED;
;       LDA(At, 1, 1); WAIT_L(0); BAR; MMA2(1, 0, 1, 1); BAR; SCHED;
;     }
;     ...
;     if (wr == 0) BAR;
	s_setprio 0
	ds_read_b128 v[12:15], v145 offset:32768
	ds_read_b128 v[16:19], v145 offset:33792
	ds_read_b128 v[182:185], v145 offset:34816
	ds_read_b128 v[186:189], v145 offset:35840
	ds_read_b128 v[206:209], v145 offset:49152
	ds_read_b128 v[214:217], v145 offset:50176
	ds_read_b128 v[218:221], v145 offset:51200
	ds_read_b128 v[234:237], v145 offset:52224
	ds_read_b128 v[0:3], v144 offset:32768
	ds_read_b128 v[4:7], v144 offset:33792
	ds_read_b128 v[8:11], v144 offset:34816
	ds_read_b128 v[32:35], v144 offset:35840
	ds_read_b128 v[36:39], v144 offset:36864
	ds_read_b128 v[238:241], v144 offset:37888
	ds_read_b128 v[242:245], v144 offset:38912
	ds_read_b128 v[246:249], v144 offset:39936
	s_waitcnt lgkmcnt(0)
	s_setprio 1
	s_barrier
	v_mfma_f32_16x16x32_bf16 v[64:67], v[0:3], v[12:15], v[124:127]
	v_mfma_f32_16x16x32_bf16 v[68:71], v[242:245], v[182:185], v[96:99]
	v_mfma_f32_16x16x32_bf16 v[120:123], v[4:7], v[16:19], v[64:67]
	v_mfma_f32_16x16x32_bf16 v[64:67], v[0:3], v[182:185], v[222:225]
	v_mfma_f32_16x16x32_bf16 v[84:87], v[246:249], v[186:189], v[68:71]
	v_mfma_f32_16x16x32_bf16 v[68:71], v[0:3], v[206:209], v[92:95]
	v_mfma_f32_16x16x32_bf16 v[0:3], v[0:3], v[218:221], v[88:91]
	v_mfma_f32_16x16x32_bf16 v[88:91], v[4:7], v[234:237], v[0:3]
	v_mfma_f32_16x16x32_bf16 v[0:3], v[8:11], v[206:209], v[190:193]
	v_mfma_f32_16x16x32_bf16 v[124:127], v[4:7], v[186:189], v[64:67]
	v_mfma_f32_16x16x32_bf16 v[64:67], v[8:11], v[12:15], v[116:119]
	v_mfma_f32_16x16x32_bf16 v[72:75], v[32:35], v[214:217], v[0:3]
	v_mfma_f32_16x16x32_bf16 v[0:3], v[8:11], v[218:221], v[80:83]
	v_mfma_f32_16x16x32_bf16 v[112:115], v[32:35], v[16:19], v[64:67]
	v_mfma_f32_16x16x32_bf16 v[64:67], v[8:11], v[182:185], v[226:229]
	v_mfma_f32_16x16x32_bf16 v[92:95], v[32:35], v[234:237], v[0:3]
	v_mfma_f32_16x16x32_bf16 v[0:3], v[36:39], v[206:209], v[76:79]
	v_mfma_f32_16x16x32_bf16 v[116:119], v[32:35], v[186:189], v[64:67]
	v_mfma_f32_16x16x32_bf16 v[64:67], v[36:39], v[12:15], v[108:111]
	v_mfma_f32_16x16x32_bf16 v[76:79], v[238:241], v[214:217], v[0:3]
	v_mfma_f32_16x16x32_bf16 v[0:3], v[36:39], v[218:221], v[194:197]
	v_mfma_f32_16x16x32_bf16 v[104:107], v[238:241], v[16:19], v[64:67]
	v_mfma_f32_16x16x32_bf16 v[64:67], v[36:39], v[182:185], v[230:233]
	v_mfma_f32_16x16x32_bf16 v[96:99], v[238:241], v[234:237], v[0:3]
	v_mfma_f32_16x16x32_bf16 v[0:3], v[242:245], v[206:209], v[198:201]
	v_mfma_f32_16x16x32_bf16 v[108:111], v[238:241], v[186:189], v[64:67]
	v_mfma_f32_16x16x32_bf16 v[64:67], v[242:245], v[12:15], v[100:103]
	v_mfma_f32_16x16x32_bf16 v[80:83], v[246:249], v[214:217], v[0:3]
	v_mfma_f32_16x16x32_bf16 v[0:3], v[242:245], v[218:221], v[202:205]
	v_mfma_f32_16x16x32_bf16 v[64:67], v[246:249], v[16:19], v[64:67]
	v_mfma_f32_16x16x32_bf16 v[68:71], v[4:7], v[214:217], v[68:71]
	v_mfma_f32_16x16x32_bf16 v[100:103], v[246:249], v[234:237], v[0:3]
	s_barrier
	s_setprio 0
	ds_read_b128 v[190:193], v144 offset:49152
	ds_read_b128 v[194:197], v144 offset:50176
	ds_read_b128 v[198:201], v144 offset:51200
	ds_read_b128 v[202:205], v144 offset:52224
	ds_read_b128 v[222:225], v144 offset:53248
	ds_read_b128 v[226:229], v144 offset:54272
	ds_read_b128 v[230:233], v144 offset:55296
	ds_read_b128 v[238:241], v144 offset:56320
	s_waitcnt lgkmcnt(0)
	s_setprio 1
	s_barrier
	v_mfma_f32_16x16x32_bf16 v[4:7], v[190:193], v[182:185], v[56:59]
	v_mfma_f32_16x16x32_bf16 v[8:11], v[198:201], v[182:185], v[48:51]
	v_mfma_f32_16x16x32_bf16 v[0:3], v[190:193], v[12:15], v[60:63]
	v_mfma_f32_16x16x32_bf16 v[32:35], v[194:197], v[186:189], v[4:7]
	v_mfma_f32_16x16x32_bf16 v[4:7], v[198:201], v[12:15], v[52:55]
	v_mfma_f32_16x16x32_bf16 v[36:39], v[202:205], v[186:189], v[8:11]
	v_mfma_f32_16x16x32_bf16 v[8:11], v[222:225], v[12:15], v[44:47]
	v_mfma_f32_16x16x32_bf16 v[12:15], v[230:233], v[12:15], v[136:139]
	v_mfma_f32_16x16x32_bf16 v[0:3], v[194:197], v[16:19], v[0:3]
	v_mfma_f32_16x16x32_bf16 v[4:7], v[202:205], v[16:19], v[4:7]
	v_mfma_f32_16x16x32_bf16 v[8:11], v[226:229], v[16:19], v[8:11]
	v_mfma_f32_16x16x32_bf16 v[12:15], v[238:241], v[16:19], v[12:15]
	v_mfma_f32_16x16x32_bf16 v[16:19], v[230:233], v[182:185], v[140:143]
	v_mfma_f32_16x16x32_bf16 v[24:27], v[190:193], v[218:221], v[24:27]
	v_mfma_f32_16x16x32_bf16 v[44:47], v[238:241], v[186:189], v[16:19]
	v_mfma_f32_16x16x32_bf16 v[16:19], v[190:193], v[206:209], v[28:31]
	v_mfma_f32_16x16x32_bf16 v[48:51], v[194:197], v[234:237], v[24:27]
	v_mfma_f32_16x16x32_bf16 v[24:27], v[198:201], v[218:221], v[166:169]
	v_mfma_f32_16x16x32_bf16 v[28:31], v[222:225], v[218:221], v[210:213]
	v_mfma_f32_16x16x32_bf16 v[40:43], v[222:225], v[182:185], v[40:43]
	v_mfma_f32_16x16x32_bf16 v[20:23], v[198:201], v[206:209], v[20:23]
	v_mfma_f32_16x16x32_bf16 v[52:55], v[202:205], v[234:237], v[24:27]
	v_mfma_f32_16x16x32_bf16 v[24:27], v[222:225], v[206:209], v[170:173]
	v_mfma_f32_16x16x32_bf16 v[56:59], v[226:229], v[234:237], v[28:31]
	v_mfma_f32_16x16x32_bf16 v[28:31], v[230:233], v[206:209], v[174:177]
	v_mfma_f32_16x16x32_bf16 v[60:63], v[230:233], v[218:221], v[178:181]
	v_mfma_f32_16x16x32_bf16 v[40:43], v[226:229], v[186:189], v[40:43]
	v_mfma_f32_16x16x32_bf16 v[16:19], v[194:197], v[214:217], v[16:19]
	v_mfma_f32_16x16x32_bf16 v[20:23], v[202:205], v[214:217], v[20:23]
	v_mfma_f32_16x16x32_bf16 v[24:27], v[226:229], v[214:217], v[24:27]
	v_mfma_f32_16x16x32_bf16 v[28:31], v[238:241], v[214:217], v[28:31]
	v_mfma_f32_16x16x32_bf16 v[60:63], v[238:241], v[234:237], v[60:63]
	s_barrier
	s_setprio 0
	s_and_saveexec_b64 s[70:71], s[6:7]
	s_cbranch_execz .LBB0_489
	s_barrier

; #define STAGE(Pp, BASE, br, kt) do { const u16* _g = (BASE) + ((long)(br) * K + (long)(kt) * BK); \
;     __builtin_amdgcn_global_load_lds((const unsigned*)(_g + voff0), (unsigned*)((char*)(Pp) + tb16), 16, 0, 0); \
;     __builtin_amdgcn_global_load_lds((const unsigned*)(_g + voff1), (unsigned*)((char*)(Pp) + tb16 + 8192), 16, 0, 0); } while (0)
; #define LDA(dst, b, h) _Pragma("unroll") for (int m = 0; m < 4; ++m) _Pragma("unroll") for (int k = 0; k < 2; ++k) \
;     dst[m][k] = *reinterpret_cast<const bf16x8*>((const char*)shm + aB + (((b) * 2 + (h)) * 16384 + (m * 2 + k) * 1024))
; #define LDB(dst, b, h) _Pragma("unroll") for (int n = 0; n < 2; ++n) _Pragma("unroll") for (int k = 0; k < 2; ++k) \
;     dst[n][k] = *reinterpret_cast<const bf16x8*>((const char*)shm + bB + (((b) * 2 + (h)) * 16384 + (n * 2 + k) * 1024))
; #define WAIT_V(n) asm volatile("s_waitcnt vmcnt(" #n ")" ::: "memory")
; #define WAIT_L(n) asm volatile("s_waitcnt lgkmcnt(" #n ")" ::: "memory")
; #define BAR __builtin_amdgcn_s_barrier()
; #define SCHED __builtin_amdgcn_sched_barrier(0)
; template <int MODE> ...
;     ...
;       LDB(B0, 0, 0); LDB(B1, 0, 1); LDA(At, 0, 0); STAGE(SA(1, 1), A, brow + HALF, t + 1);
;       WAIT_L(0); BAR; MMA2(0, 0, 0, 1); BAR; SCHED;
;       LDA(At, 0, 1); STAGE(SB(0, 0), Bt, bcol, t + 2); STAGE(SB(0, 1), Bt, bcol + HALF, t + 2); STAGE(SA(0, 0), A, brow, t + 2);
;       WAIT_V(6); WAIT_L(0); BAR; MMA2(1, 0, 1, 1); BAR; SCHED;
.LBB0_591:
	s_add_u32 s65, s32, 0xc000
	s_mov_b32 m0, s65
	ds_read_b128 v[168:171], v149
	ds_read_b128 v[172:175], v149 offset:1024
	ds_read_b128 v[176:179], v149 offset:2048
	ds_read_b128 v[180:183], v149 offset:3072
	ds_read_b128 v[184:187], v149 offset:16384
	ds_read_b128 v[188:191], v149 offset:17408
	ds_read_b128 v[192:195], v149 offset:18432
	ds_read_b128 v[196:199], v149 offset:19456
	ds_read_b128 v[200:203], v148
	ds_read_b128 v[204:207], v148 offset:1024
	ds_read_b128 v[208:211], v148 offset:2048
	ds_read_b128 v[212:215], v148 offset:3072
	ds_read_b128 v[216:219], v148 offset:4096
	ds_read_b128 v[220:223], v148 offset:5120
	ds_read_b128 v[224:227], v148 offset:6144
	ds_read_b128 v[228:231], v148 offset:7168
	s_add_u32 s88, s10, s38
	s_addc_u32 s89, s11, s39
	global_load_lds_dwordx4 v142, s[88:89]
	s_add_u32 s65, s32, 0xe000
	s_mov_b32 m0, s65
	s_nop 0
	s_add_u32 s90, s10, s38
	s_addc_u32 s91, s11, s39
	global_load_lds_dwordx4 v144, s[90:91]
	s_waitcnt lgkmcnt(0)
	s_setprio 1
	s_barrier
	v_mfma_f32_16x16x32_bf16 v[124:127], v[200:203], v[168:171], v[124:127]
	v_mfma_f32_16x16x32_bf16 v[120:123], v[200:203], v[176:179], v[120:123]
	v_mfma_f32_16x16x32_bf16 v[116:119], v[208:211], v[168:171], v[116:119]
	v_mfma_f32_16x16x32_bf16 v[112:115], v[208:211], v[176:179], v[112:115]
	v_mfma_f32_16x16x32_bf16 v[108:111], v[216:219], v[168:171], v[108:111]
	v_mfma_f32_16x16x32_bf16 v[104:107], v[216:219], v[176:179], v[104:107]
	v_mfma_f32_16x16x32_bf16 v[100:103], v[224:227], v[168:171], v[100:103]
	v_mfma_f32_16x16x32_bf16 v[96:99], v[224:227], v[176:179], v[96:99]
	v_mfma_f32_16x16x32_bf16 v[88:91], v[200:203], v[184:187], v[88:91]
	v_mfma_f32_16x16x32_bf16 v[72:75], v[200:203], v[192:195], v[72:75]
	v_mfma_f32_16x16x32_bf16 v[56:59], v[208:211], v[184:187], v[56:59]
	v_mfma_f32_16x16x32_bf16 v[48:51], v[208:211], v[192:195], v[48:51]
	v_mfma_f32_16x16x32_bf16 v[44:47], v[216:219], v[184:187], v[44:47]
	v_mfma_f32_16x16x32_bf16 v[40:43], v[216:219], v[192:195], v[40:43]
	v_mfma_f32_16x16x32_bf16 v[36:39], v[224:227], v[184:187], v[36:39]
	v_mfma_f32_16x16x32_bf16 v[32:35], v[224:227], v[192:195], v[32:35]
	v_mfma_f32_16x16x32_bf16 v[124:127], v[204:207], v[172:175], v[124:127]
	v_mfma_f32_16x16x32_bf16 v[120:123], v[204:207], v[180:183], v[120:123]
	v_mfma_f32_16x16x32_bf16 v[116:119], v[212:215], v[172:175], v[116:119]
	v_mfma_f32_16x16x32_bf16 v[112:115], v[212:215], v[180:183], v[112:115]
	v_mfma_f32_16x16x32_bf16 v[108:111], v[220:223], v[172:175], v[108:111]
	v_mfma_f32_16x16x32_bf16 v[104:107], v[220:223], v[180:183], v[104:107]
	v_mfma_f32_16x16x32_bf16 v[100:103], v[228:231], v[172:175], v[100:103]
	v_mfma_f32_16x16x32_bf16 v[96:99], v[228:231], v[180:183], v[96:99]
	v_mfma_f32_16x16x32_bf16 v[88:91], v[204:207], v[188:191], v[88:91]
	v_mfma_f32_16x16x32_bf16 v[72:75], v[204:207], v[196:199], v[72:75]
	v_mfma_f32_16x16x32_bf16 v[56:59], v[212:215], v[188:191], v[56:59]
	v_mfma_f32_16x16x32_bf16 v[48:51], v[212:215], v[196:199], v[48:51]
	v_mfma_f32_16x16x32_bf16 v[44:47], v[220:223], v[188:191], v[44:47]
	v_mfma_f32_16x16x32_bf16 v[40:43], v[220:223], v[196:199], v[40:43]
	v_mfma_f32_16x16x32_bf16 v[36:39], v[228:231], v[188:191], v[36:39]
	v_mfma_f32_16x16x32_bf16 v[32:35], v[228:231], v[196:199], v[32:35]
	s_barrier
	s_setprio 0
	s_add_u32 s65, s32, 0x10000
	s_mov_b32 m0, s65
	ds_read_b128 v[200:203], v148 offset:16384
	ds_read_b128 v[204:207], v148 offset:17408
	ds_read_b128 v[208:211], v148 offset:18432
	ds_read_b128 v[212:215], v148 offset:19456
	ds_read_b128 v[216:219], v148 offset:20480
	ds_read_b128 v[220:223], v148 offset:21504
	ds_read_b128 v[224:227], v148 offset:22528
	ds_read_b128 v[228:231], v148 offset:23552
	s_add_u32 s92, s10, s40
	s_addc_u32 s93, s11, s41
	global_load_lds_dwordx4 v138, s[92:93]
	s_add_u32 s65, s32, 0x12000
	s_mov_b32 m0, s65
	s_add_u32 s65, s32, 0x14000
	s_add_u32 s96, s10, s40
	s_addc_u32 s97, s11, s41
	global_load_lds_dwordx4 v140, s[96:97]
	s_mov_b32 m0, s65
	s_add_u32 s65, s32, 0x16000
	s_add_u32 s88, s10, s42
	s_addc_u32 s89, s11, s43
	global_load_lds_dwordx4 v138, s[88:89]
	s_mov_b32 m0, s65
	s_mov_b32 s65, s32
	s_add_u32 s90, s10, s42
	s_addc_u32 s91, s11, s43
	global_load_lds_dwordx4 v140, s[90:91]
	s_mov_b32 m0, s65
	s_add_u32 s65, s32, 0x2000
	s_add_u32 s92, s10, s44
	s_addc_u32 s93, s11, s45
	global_load_lds_dwordx4 v142, s[92:93]
	s_mov_b32 m0, s65
	s_nop 0
	s_add_u32 s96, s10, s44
	s_addc_u32 s97, s11, s45
	global_load_lds_dwordx4 v144, s[96:97]
	s_waitcnt vmcnt(6)
	s_waitcnt lgkmcnt(0)
	s_setprio 1
	s_barrier
; #define STAGE(Pp, BASE, br, kt) do { const u16* _g = (BASE) + ((long)(br) * K + (long)(kt) * BK); \
;     __builtin_amdgcn_global_load_lds((const unsigned*)(_g + voff0), (unsigned*)((char*)(Pp) + tb16), 16, 0, 0); \
;     __builtin_amdgcn_global_load_lds((const unsigned*)(_g + voff1), (unsigned*)((char*)(Pp) + tb16 + 8192), 16, 0, 0); } while (0)
; #define LDA(dst, b, h) _Pragma("unroll") for (int m = 0; m < 4; ++m) _Pragma("unroll") for (int k = 0; k < 2; ++k) \
;     dst[m][k] = *reinterpret_cast<const bf16x8*>((const char*)shm + aB + (((b) * 2 + (h)) * 16384 + (m * 2 + k) * 1024))
; #define LDB(dst, b, h) _Pragma("unroll") for (int n = 0; n < 2; ++n) _Pragma("unroll") for (int k = 0; k < 2; ++k) \
;     dst[n][k] = *reinterpret_cast<const bf16x8*>((const char*)shm + bB + (((b) * 2 + (h)) * 16384 + (n * 2 + k) * 1024))
; #define WAIT_V(n) asm volatile("s_waitcnt vmcnt(" #n ")" ::: "memory")
; #define WAIT_L(n) asm volatile("s_waitcnt lgkmcnt(" #n ")" ::: "memory")
; #define BAR __builtin_amdgcn_s_barrier()
; #define SCHED __builtin_amdgcn_sched_barrier(0)
; template <int MODE> ...
;     ...
;       WAIT_V(6); WAIT_L(0); BAR; MMA2(1, 0, 1, 1); BAR; SCHED;
;       LDB(B0, 1, 0); LDB(B1, 1, 1); LDA(At, 1, 0); STAGE(SA(0, 1), A, brow + HALF, t + 2);
;       WAIT_L(0); BAR; MMA2(0, 0, 0, 1); BAR; SCHED;
	v_mfma_f32_16x16x32_bf16 v[28:31], v[200:203], v[168:171], v[28:31]
	v_mfma_f32_16x16x32_bf16 v[24:27], v[200:203], v[176:179], v[24:27]
	v_mfma_f32_16x16x32_bf16 v[20:23], v[208:211], v[168:171], v[20:23]
	v_mfma_f32_16x16x32_bf16 v[16:19], v[208:211], v[176:179], v[16:19]
	v_mfma_f32_16x16x32_bf16 v[12:15], v[216:219], v[168:171], v[12:15]
	v_mfma_f32_16x16x32_bf16 v[8:11], v[216:219], v[176:179], v[8:11]
	v_mfma_f32_16x16x32_bf16 v[4:7], v[224:227], v[168:171], v[4:7]
	v_mfma_f32_16x16x32_bf16 v[0:3], v[224:227], v[176:179], v[0:3]
	v_mfma_f32_16x16x32_bf16 v[52:55], v[200:203], v[184:187], v[52:55]
	v_mfma_f32_16x16x32_bf16 v[60:63], v[200:203], v[192:195], v[60:63]
	v_mfma_f32_16x16x32_bf16 v[64:67], v[208:211], v[184:187], v[64:67]
	v_mfma_f32_16x16x32_bf16 v[68:71], v[208:211], v[192:195], v[68:71]
	v_mfma_f32_16x16x32_bf16 v[76:79], v[216:219], v[184:187], v[76:79]
	v_mfma_f32_16x16x32_bf16 v[80:83], v[216:219], v[192:195], v[80:83]
	v_mfma_f32_16x16x32_bf16 v[84:87], v[224:227], v[184:187], v[84:87]
	v_mfma_f32_16x16x32_bf16 v[92:95], v[224:227], v[192:195], v[92:95]
	v_mfma_f32_16x16x32_bf16 v[28:31], v[204:207], v[172:175], v[28:31]
	v_mfma_f32_16x16x32_bf16 v[24:27], v[204:207], v[180:183], v[24:27]
	v_mfma_f32_16x16x32_bf16 v[20:23], v[212:215], v[172:175], v[20:23]
	v_mfma_f32_16x16x32_bf16 v[16:19], v[212:215], v[180:183], v[16:19]
	v_mfma_f32_16x16x32_bf16 v[12:15], v[220:223], v[172:175], v[12:15]
	v_mfma_f32_16x16x32_bf16 v[8:11], v[220:223], v[180:183], v[8:11]
	v_mfma_f32_16x16x32_bf16 v[4:7], v[228:231], v[172:175], v[4:7]
	v_mfma_f32_16x16x32_bf16 v[0:3], v[228:231], v[180:183], v[0:3]
	v_mfma_f32_16x16x32_bf16 v[52:55], v[204:207], v[188:191], v[52:55]
	v_mfma_f32_16x16x32_bf16 v[60:63], v[204:207], v[196:199], v[60:63]
	v_mfma_f32_16x16x32_bf16 v[64:67], v[212:215], v[188:191], v[64:67]
	v_mfma_f32_16x16x32_bf16 v[68:71], v[212:215], v[196:199], v[68:71]
	v_mfma_f32_16x16x32_bf16 v[76:79], v[220:223], v[188:191], v[76:79]
	v_mfma_f32_16x16x32_bf16 v[80:83], v[220:223], v[196:199], v[80:83]
	v_mfma_f32_16x16x32_bf16 v[84:87], v[228:231], v[188:191], v[84:87]
	v_mfma_f32_16x16x32_bf16 v[92:95], v[228:231], v[196:199], v[92:95]
	s_barrier
	s_setprio 0
	s_add_u32 s65, s32, 0x4000
	s_mov_b32 m0, s65
	s_add_u32 s65, s32, 0x6000
	ds_read_b128 v[168:171], v149 offset:32768
	ds_read_b128 v[172:175], v149 offset:33792
	ds_read_b128 v[176:179], v149 offset:34816
	ds_read_b128 v[180:183], v149 offset:35840
	ds_read_b128 v[184:187], v149 offset:49152
	ds_read_b128 v[188:191], v149 offset:50176
	ds_read_b128 v[192:195], v149 offset:51200
	ds_read_b128 v[196:199], v149 offset:52224
	ds_read_b128 v[200:203], v148 offset:32768
	ds_read_b128 v[204:207], v148 offset:33792
	ds_read_b128 v[208:211], v148 offset:34816
	ds_read_b128 v[212:215], v148 offset:35840
	ds_read_b128 v[216:219], v148 offset:36864
	ds_read_b128 v[220:223], v148 offset:37888
	ds_read_b128 v[224:227], v148 offset:38912
	ds_read_b128 v[228:231], v148 offset:39936
	s_add_u32 s88, s10, s48
	s_addc_u32 s89, s11, s49
	global_load_lds_dwordx4 v142, s[88:89]
	s_mov_b32 m0, s65
	s_nop 0
	s_add_u32 s90, s10, s48
	s_addc_u32 s91, s11, s49
	global_load_lds_dwordx4 v144, s[90:91]
	s_waitcnt lgkmcnt(0)
	s_setprio 1
	s_barrier
	v_mfma_f32_16x16x32_bf16 v[124:127], v[200:203], v[168:171], v[124:127]
	v_mfma_f32_16x16x32_bf16 v[120:123], v[200:203], v[176:179], v[120:123]
	v_mfma_f32_16x16x32_bf16 v[116:119], v[208:211], v[168:171], v[116:119]
	v_mfma_f32_16x16x32_bf16 v[112:115], v[208:211], v[176:179], v[112:115]
	v_mfma_f32_16x16x32_bf16 v[108:111], v[216:219], v[168:171], v[108:111]
	v_mfma_f32_16x16x32_bf16 v[104:107], v[216:219], v[176:179], v[104:107]
	v_mfma_f32_16x16x32_bf16 v[100:103], v[224:227], v[168:171], v[100:103]
	v_mfma_f32_16x16x32_bf16 v[96:99], v[224:227], v[176:179], v[96:99]
	v_mfma_f32_16x16x32_bf16 v[88:91], v[200:203], v[184:187], v[88:91]
	v_mfma_f32_16x16x32_bf16 v[72:75], v[200:203], v[192:195], v[72:75]
	v_mfma_f32_16x16x32_bf16 v[56:59], v[208:211], v[184:187], v[56:59]
	v_mfma_f32_16x16x32_bf16 v[48:51], v[208:211], v[192:195], v[48:51]
	v_mfma_f32_16x16x32_bf16 v[44:47], v[216:219], v[184:187], v[44:47]
	v_mfma_f32_16x16x32_bf16 v[40:43], v[216:219], v[192:195], v[40:43]
	v_mfma_f32_16x16x32_bf16 v[36:39], v[224:227], v[184:187], v[36:39]
	v_mfma_f32_16x16x32_bf16 v[32:35], v[224:227], v[192:195], v[32:35]
	v_mfma_f32_16x16x32_bf16 v[124:127], v[204:207], v[172:175], v[124:127]
	v_mfma_f32_16x16x32_bf16 v[120:123], v[204:207], v[180:183], v[120:123]
	v_mfma_f32_16x16x32_bf16 v[116:119], v[212:215], v[172:175], v[116:119]
	v_mfma_f32_16x16x32_bf16 v[112:115], v[212:215], v[180:183], v[112:115]
	v_mfma_f32_16x16x32_bf16 v[108:111], v[220:223], v[172:175], v[108:111]
	v_mfma_f32_16x16x32_bf16 v[104:107], v[220:223], v[180:183], v[104:107]
	v_mfma_f32_16x16x32_bf16 v[100:103], v[228:231], v[172:175], v[100:103]
	v_mfma_f32_16x16x32_bf16 v[96:99], v[228:231], v[180:183], v[96:99]
	v_mfma_f32_16x16x32_bf16 v[88:91], v[204:207], v[188:191], v[88:91]
	v_mfma_f32_16x16x32_bf16 v[72:75], v[204:207], v[196:199], v[72:75]
	v_mfma_f32_16x16x32_bf16 v[56:59], v[212:215], v[188:191], v[56:59]
	v_mfma_f32_16x16x32_bf16 v[48:51], v[212:215], v[196:199], v[48:51]
	v_mfma_f32_16x16x32_bf16 v[44:47], v[220:223], v[188:191], v[44:47]
	v_mfma_f32_16x16x32_bf16 v[40:43], v[220:223], v[196:199], v[40:43]
	v_mfma_f32_16x16x32_bf16 v[36:39], v[228:231], v[188:191], v[36:39]
	v_mfma_f32_16x16x32_bf16 v[32:35], v[228:231], v[196:199], v[32:35]
	s_barrier
; #define STAGE(Pp, BASE, br, kt) do { const u16* _g = (BASE) + ((long)(br) * K + (long)(kt) * BK); \
;     __builtin_amdgcn_global_load_lds((const unsigned*)(_g + voff0), (unsigned*)((char*)(Pp) + tb16), 16, 0, 0); \
;     __builtin_amdgcn_global_load_lds((const unsigned*)(_g + voff1), (unsigned*)((char*)(Pp) + tb16 + 8192), 16, 0, 0); } while (0)
; #define LDA(dst, b, h) _Pragma("unroll") for (int m = 0; m < 4; ++m) _Pragma("unroll") for (int k = 0; k < 2; ++k) \
;     dst[m][k] = *reinterpret_cast<const bf16x8*>((const char*)shm + aB + (((b) * 2 + (h)) * 16384 + (m * 2 + k) * 1024))
; #define LDB(dst, b, h) _Pragma("unroll") for (int n = 0; n < 2; ++n) _Pragma("unroll") for (int k = 0; k < 2; ++k) \
;     dst[n][k] = *reinterpret_cast<const bf16x8*>((const char*)shm + bB + (((b) * 2 + (h)) * 16384 + (n * 2 + k) * 1024))
; #define WAIT_V(n) asm volatile("s_waitcnt vmcnt(" #n ")" ::: "memory")
; #define WAIT_L(n) asm volatile("s_waitcnt lgkmcnt(" #n ")" ::: "memory")
; #define BAR __builtin_amdgcn_s_barrier()
; #define SCHED __builtin_amdgcn_sched_barrier(0)
; template <int MODE> ...
;     ...
;       LDA(At, 1, 1); STAGE(SB(1, 0), Bt, bcol, t + 3); STAGE(SB(1, 1), Bt, bcol + HALF, t + 3); STAGE(SA(1, 0), A, brow, t + 3);
;       WAIT_V(6); WAIT_L(0); BAR; MMA2(1, 0, 1, 1); BAR; SCHED;
;     }
;     {
;       LDB(B0, 0, 0); LDB(B1, 0, 1); LDA(At, 0, 0); STAGE(SA(1, 1), A, brow + HALF, nt - 1);
;       WAIT_L(0); BAR; MMA2(0, 0, 0, 1); BAR; SCHED;
	s_setprio 0
	s_add_u32 s65, s32, 0x18000
	s_mov_b32 m0, s65
	s_add_u32 s65, s32, 0x1a000
	ds_read_b128 v[200:203], v148 offset:49152
	ds_read_b128 v[204:207], v148 offset:50176
	ds_read_b128 v[208:211], v148 offset:51200
	ds_read_b128 v[212:215], v148 offset:52224
	ds_read_b128 v[216:219], v148 offset:53248
	ds_read_b128 v[220:223], v148 offset:54272
	ds_read_b128 v[224:227], v148 offset:55296
	ds_read_b128 v[228:231], v148 offset:56320
	s_add_u32 s92, s10, s50
	s_addc_u32 s93, s11, s51
	global_load_lds_dwordx4 v138, s[92:93]
	s_mov_b32 m0, s65
	s_add_u32 s65, s32, 0x1c000
	s_add_u32 s96, s10, s50
	s_addc_u32 s97, s11, s51
	global_load_lds_dwordx4 v140, s[96:97]
	s_mov_b32 m0, s65
	s_add_u32 s65, s32, 0x1e000
	s_add_u32 s88, s10, s60
	s_addc_u32 s89, s11, s61
	global_load_lds_dwordx4 v138, s[88:89]
	s_mov_b32 m0, s65
	s_add_u32 s65, s32, 0x8000
	s_add_u32 s90, s10, s60
	s_addc_u32 s91, s11, s61
	global_load_lds_dwordx4 v140, s[90:91]
	s_mov_b32 m0, s65
	s_add_u32 s65, s32, 0xa000
	s_add_u32 s92, s10, s62
	s_addc_u32 s93, s11, s63
	global_load_lds_dwordx4 v142, s[92:93]
	s_mov_b32 m0, s65
	s_nop 0
	s_add_u32 s96, s10, s62
	s_addc_u32 s97, s11, s63
	global_load_lds_dwordx4 v144, s[96:97]
	s_waitcnt vmcnt(6)
	s_waitcnt lgkmcnt(0)
	s_setprio 1
	s_barrier
	v_mfma_f32_16x16x32_bf16 v[28:31], v[200:203], v[168:171], v[28:31]
	v_mfma_f32_16x16x32_bf16 v[24:27], v[200:203], v[176:179], v[24:27]
	v_mfma_f32_16x16x32_bf16 v[20:23], v[208:211], v[168:171], v[20:23]
	v_mfma_f32_16x16x32_bf16 v[16:19], v[208:211], v[176:179], v[16:19]
	v_mfma_f32_16x16x32_bf16 v[12:15], v[216:219], v[168:171], v[12:15]
	v_mfma_f32_16x16x32_bf16 v[8:11], v[216:219], v[176:179], v[8:11]
	v_mfma_f32_16x16x32_bf16 v[4:7], v[224:227], v[168:171], v[4:7]
	v_mfma_f32_16x16x32_bf16 v[0:3], v[224:227], v[176:179], v[0:3]
	v_mfma_f32_16x16x32_bf16 v[52:55], v[200:203], v[184:187], v[52:55]
	v_mfma_f32_16x16x32_bf16 v[60:63], v[200:203], v[192:195], v[60:63]
	v_mfma_f32_16x16x32_bf16 v[64:67], v[208:211], v[184:187], v[64:67]
	v_mfma_f32_16x16x32_bf16 v[68:71], v[208:211], v[192:195], v[68:71]
	v_mfma_f32_16x16x32_bf16 v[76:79], v[216:219], v[184:187], v[76:79]
	v_mfma_f32_16x16x32_bf16 v[80:83], v[216:219], v[192:195], v[80:83]
	v_mfma_f32_16x16x32_bf16 v[84:87], v[224:227], v[184:187], v[84:87]
	v_mfma_f32_16x16x32_bf16 v[92:95], v[224:227], v[192:195], v[92:95]
	v_mfma_f32_16x16x32_bf16 v[28:31], v[204:207], v[172:175], v[28:31]
	v_mfma_f32_16x16x32_bf16 v[24:27], v[204:207], v[180:183], v[24:27]
	v_mfma_f32_16x16x32_bf16 v[20:23], v[212:215], v[172:175], v[20:23]
	v_mfma_f32_16x16x32_bf16 v[16:19], v[212:215], v[180:183], v[16:19]
	v_mfma_f32_16x16x32_bf16 v[12:15], v[220:223], v[172:175], v[12:15]
	v_mfma_f32_16x16x32_bf16 v[8:11], v[220:223], v[180:183], v[8:11]
	v_mfma_f32_16x16x32_bf16 v[4:7], v[228:231], v[172:175], v[4:7]
	v_mfma_f32_16x16x32_bf16 v[0:3], v[228:231], v[180:183], v[0:3]
	v_mfma_f32_16x16x32_bf16 v[52:55], v[204:207], v[188:191], v[52:55]
	v_mfma_f32_16x16x32_bf16 v[60:63], v[204:207], v[196:199], v[60:63]
	v_mfma_f32_16x16x32_bf16 v[64:67], v[212:215], v[188:191], v[64:67]
	v_mfma_f32_16x16x32_bf16 v[68:71], v[212:215], v[196:199], v[68:71]
	v_mfma_f32_16x16x32_bf16 v[76:79], v[220:223], v[188:191], v[76:79]
	v_mfma_f32_16x16x32_bf16 v[80:83], v[220:223], v[196:199], v[80:83]
	v_mfma_f32_16x16x32_bf16 v[84:87], v[228:231], v[188:191], v[84:87]
	v_mfma_f32_16x16x32_bf16 v[92:95], v[228:231], v[196:199], v[92:95]
	s_barrier
	s_setprio 0
	s_add_i32 s35, s35, 2
	s_add_u32 s10, s10, 0x100
	s_addc_u32 s11, s11, 0
	s_cmp_lt_u32 s35, 60
	s_cbranch_scc1 .LBB0_591
	s_add_u32 s8, s8, 0x1f80
	v_readfirstlane_b32 s10, v165
	s_addc_u32 s9, s9, 0
	s_mov_b32 m0, s10
	v_readfirstlane_b32 s10, v166
	ds_read_b128 v[138:141], v149
	ds_read_b128 v[142:145], v149 offset:1024
	ds_read_b128 v[168:171], v149 offset:2048
	ds_read_b128 v[172:175], v149 offset:3072
	ds_read_b128 v[176:179], v149 offset:16384
	ds_read_b128 v[180:183], v149 offset:17408
	ds_read_b128 v[184:187], v149 offset:18432
	ds_read_b128 v[188:191], v149 offset:19456
	ds_read_b128 v[192:195], v148
	ds_read_b128 v[196:199], v148 offset:1024
	ds_read_b128 v[200:203], v148 offset:2048
	ds_read_b128 v[204:207], v148 offset:3072
	ds_read_b128 v[208:211], v148 offset:4096
	ds_read_b128 v[212:215], v148 offset:5120
	ds_read_b128 v[216:219], v148 offset:6144
	ds_read_b128 v[220:223], v148 offset:7168
	global_load_lds_dwordx4 v134, s[8:9]
	s_mov_b32 m0, s10
	s_nop 0
	global_load_lds_dwordx4 v136, s[8:9]
	s_waitcnt lgkmcnt(0)
	s_setprio 1
	s_barrier
; #define LDA(dst, b, h) _Pragma("unroll") for (int m = 0; m < 4; ++m) _Pragma("unroll") for (int k = 0; k < 2; ++k) \
;     dst[m][k] = *reinterpret_cast<const bf16x8*>((const char*)shm + aB + (((b) * 2 + (h)) * 16384 + (m * 2 + k) * 1024))
; #define WAIT_V(n) asm volatile("s_waitcnt vmcnt(" #n ")" ::: "memory")
; #define WAIT_L(n) asm volatile("s_waitcnt lgkmcnt(" #n ")" ::: "memory")
; #define BAR __builtin_amdgcn_s_barrier()
; #define SCHED __builtin_amdgcn_sched_barrier(0)
; template <int MODE> ...
;     ...
;       WAIT_L(0); BAR; MMA2(0, 0, 0, 1); BAR; SCHED;
;       LDA(At, 0, 1); WAIT_V(0); WAIT_L(0); BAR; MMA2(1, 0, 1, 1); BAR; SCHED;
	v_mfma_f32_16x16x32_bf16 v[124:127], v[192:195], v[138:141], v[124:127]
	v_mfma_f32_16x16x32_bf16 v[120:123], v[192:195], v[168:171], v[120:123]
	v_mfma_f32_16x16x32_bf16 v[116:119], v[200:203], v[138:141], v[116:119]
	v_mfma_f32_16x16x32_bf16 v[112:115], v[200:203], v[168:171], v[112:115]
	v_mfma_f32_16x16x32_bf16 v[108:111], v[208:211], v[138:141], v[108:111]
	v_mfma_f32_16x16x32_bf16 v[104:107], v[208:211], v[168:171], v[104:107]
	v_mfma_f32_16x16x32_bf16 v[96:99], v[216:219], v[168:171], v[96:99]
	v_mfma_f32_16x16x32_bf16 v[88:91], v[192:195], v[176:179], v[88:91]
	v_mfma_f32_16x16x32_bf16 v[72:75], v[192:195], v[184:187], v[72:75]
	v_mfma_f32_16x16x32_bf16 v[56:59], v[200:203], v[176:179], v[56:59]
	v_mfma_f32_16x16x32_bf16 v[48:51], v[200:203], v[184:187], v[48:51]
	v_mfma_f32_16x16x32_bf16 v[44:47], v[208:211], v[176:179], v[44:47]
	v_mfma_f32_16x16x32_bf16 v[40:43], v[208:211], v[184:187], v[40:43]
	v_mfma_f32_16x16x32_bf16 v[36:39], v[216:219], v[176:179], v[36:39]
	v_mfma_f32_16x16x32_bf16 v[32:35], v[216:219], v[184:187], v[32:35]
	v_mfma_f32_16x16x32_bf16 v[124:127], v[196:199], v[142:145], v[124:127]
	v_mfma_f32_16x16x32_bf16 v[120:123], v[196:199], v[172:175], v[120:123]
	v_mfma_f32_16x16x32_bf16 v[116:119], v[204:207], v[142:145], v[116:119]
	v_mfma_f32_16x16x32_bf16 v[112:115], v[204:207], v[172:175], v[112:115]
	v_mfma_f32_16x16x32_bf16 v[108:111], v[212:215], v[142:145], v[108:111]
	v_mfma_f32_16x16x32_bf16 v[104:107], v[212:215], v[172:175], v[104:107]
	v_mfma_f32_16x16x32_bf16 v[100:103], v[216:219], v[138:141], v[100:103]
	v_mfma_f32_16x16x32_bf16 v[96:99], v[220:223], v[172:175], v[96:99]
	v_mfma_f32_16x16x32_bf16 v[88:91], v[196:199], v[180:183], v[88:91]
	v_mfma_f32_16x16x32_bf16 v[72:75], v[196:199], v[188:191], v[72:75]
	v_mfma_f32_16x16x32_bf16 v[56:59], v[204:207], v[180:183], v[56:59]
	v_mfma_f32_16x16x32_bf16 v[48:51], v[204:207], v[188:191], v[48:51]
	v_mfma_f32_16x16x32_bf16 v[44:47], v[212:215], v[180:183], v[44:47]
	v_mfma_f32_16x16x32_bf16 v[40:43], v[212:215], v[188:191], v[40:43]
	v_mfma_f32_16x16x32_bf16 v[36:39], v[220:223], v[180:183], v[36:39]
	v_mfma_f32_16x16x32_bf16 v[32:35], v[220:223], v[188:191], v[32:35]
	v_mfma_f32_16x16x32_bf16 v[224:227], v[220:223], v[142:145], v[100:103]
	s_barrier
	s_setprio 0
	s_nop 0
	ds_read_b128 v[100:103], v148 offset:16384
	ds_read_b128 v[192:195], v148 offset:17408
	ds_read_b128 v[196:199], v148 offset:18432
	ds_read_b128 v[200:203], v148 offset:19456
	ds_read_b128 v[204:207], v148 offset:20480
	ds_read_b128 v[208:211], v148 offset:21504
	ds_read_b128 v[212:215], v148 offset:22528
	ds_read_b128 v[216:219], v148 offset:23552
	s_waitcnt vmcnt(0)
	s_waitcnt lgkmcnt(0)
	s_setprio 1
	s_barrier
	v_mfma_f32_16x16x32_bf16 v[28:31], v[100:103], v[138:141], v[28:31]
	v_mfma_f32_16x16x32_bf16 v[20:23], v[196:199], v[138:141], v[20:23]
	v_mfma_f32_16x16x32_bf16 v[12:15], v[204:207], v[138:141], v[12:15]
	v_mfma_f32_16x16x32_bf16 v[4:7], v[212:215], v[138:141], v[4:7]
	v_mfma_f32_16x16x32_bf16 v[0:3], v[212:215], v[168:171], v[0:3]
	v_mfma_f32_16x16x32_bf16 v[28:31], v[192:195], v[142:145], v[28:31]
	v_mfma_f32_16x16x32_bf16 v[20:23], v[200:203], v[142:145], v[20:23]
	v_mfma_f32_16x16x32_bf16 v[220:223], v[208:211], v[142:145], v[12:15]
	v_mfma_f32_16x16x32_bf16 v[138:141], v[216:219], v[142:145], v[4:7]
	v_mfma_f32_16x16x32_bf16 v[142:145], v[216:219], v[172:175], v[0:3]
	v_mfma_f32_16x16x32_bf16 v[0:3], v[100:103], v[176:179], v[52:55]
	v_mfma_f32_16x16x32_bf16 v[24:27], v[100:103], v[168:171], v[24:27]
	v_mfma_f32_16x16x32_bf16 v[16:19], v[196:199], v[168:171], v[16:19]
	v_mfma_f32_16x16x32_bf16 v[8:11], v[204:207], v[168:171], v[8:11]
	v_mfma_f32_16x16x32_bf16 v[168:171], v[192:195], v[180:183], v[0:3]
	v_mfma_f32_16x16x32_bf16 v[0:3], v[100:103], v[184:187], v[60:63]
	v_mfma_f32_16x16x32_bf16 v[24:27], v[192:195], v[172:175], v[24:27]
	v_mfma_f32_16x16x32_bf16 v[16:19], v[200:203], v[172:175], v[16:19]
	v_mfma_f32_16x16x32_bf16 v[228:231], v[208:211], v[172:175], v[8:11]
	v_mfma_f32_16x16x32_bf16 v[172:175], v[192:195], v[188:191], v[0:3]
	v_mfma_f32_16x16x32_bf16 v[0:3], v[196:199], v[176:179], v[64:67]
	v_mfma_f32_16x16x32_bf16 v[192:195], v[200:203], v[180:183], v[0:3]
	v_mfma_f32_16x16x32_bf16 v[0:3], v[196:199], v[184:187], v[68:71]
	v_mfma_f32_16x16x32_bf16 v[196:199], v[200:203], v[188:191], v[0:3]
	v_mfma_f32_16x16x32_bf16 v[0:3], v[204:207], v[176:179], v[76:79]
	v_mfma_f32_16x16x32_bf16 v[200:203], v[208:211], v[180:183], v[0:3]
	v_mfma_f32_16x16x32_bf16 v[0:3], v[204:207], v[184:187], v[80:83]
	v_mfma_f32_16x16x32_bf16 v[204:207], v[208:211], v[188:191], v[0:3]
	v_mfma_f32_16x16x32_bf16 v[0:3], v[212:215], v[176:179], v[84:87]
	v_mfma_f32_16x16x32_bf16 v[176:179], v[216:219], v[180:183], v[0:3]
	v_mfma_f32_16x16x32_bf16 v[0:3], v[212:215], v[184:187], v[92:95]
	v_mfma_f32_16x16x32_bf16 v[180:183], v[216:219], v[188:191], v[0:3]
	s_barrier
; #define LDA(dst, b, h) _Pragma("unroll") for (int m = 0; m < 4; ++m) _Pragma("unroll") for (int k = 0; k < 2; ++k) \
;     dst[m][k] = *reinterpret_cast<const bf16x8*>((const char*)shm + aB + (((b) * 2 + (h)) * 16384 + (m * 2 + k) * 1024))
; #define LDB(dst, b, h) _Pragma("unroll") for (int n = 0; n < 2; ++n) _Pragma("unroll") for (int k = 0; k < 2; ++k) \
;     dst[n][k] = *reinterpret_cast<const bf16x8*>((const char*)shm + bB + (((b) * 2 + (h)) * 16384 + (n * 2 + k) * 1024))
; #define WAIT_L(n) asm volatile("s_waitcnt lgkmcnt(" #n ")" ::: "memory")
; #define BAR __builtin_amdgcn_s_barrier()
; #define SCHED __builtin_amdgcn_sched_barrier(0)
; template <int MODE> ...
;     ...
;       LDB(B0, 1, 0); LDB(B1, 1, 1); LDA(At, 1, 0); WAIT_L(0); BAR; MMA2(0, 0, 0, 1); BAR; SCHED;
;       LDA(At, 1, 1); WAIT_L(0); BAR; MMA2(1, 0, 1, 1); BAR; SCHED;
;     }
;     ...
;     if (wr == 0) BAR;
	s_setprio 0
	ds_read_b128 v[64:67], v149 offset:32768
	ds_read_b128 v[184:187], v149 offset:33792
	ds_read_b128 v[188:191], v149 offset:34816
	ds_read_b128 v[208:211], v149 offset:35840
	ds_read_b128 v[212:215], v149 offset:49152
	ds_read_b128 v[216:219], v149 offset:50176
	ds_read_b128 v[232:235], v149 offset:51200
	ds_read_b128 v[236:239], v149 offset:52224
	ds_read_b128 v[8:11], v148 offset:32768
	ds_read_b128 v[52:55], v148 offset:33792
	ds_read_b128 v[60:63], v148 offset:34816
	ds_read_b128 v[68:71], v148 offset:35840
	ds_read_b128 v[76:79], v148 offset:36864
	ds_read_b128 v[80:83], v148 offset:37888
	ds_read_b128 v[240:243], v148 offset:38912
	ds_read_b128 v[244:247], v148 offset:39936
	s_waitcnt lgkmcnt(0)
	s_setprio 1
	s_barrier
	v_mfma_f32_16x16x32_bf16 v[12:15], v[60:63], v[64:67], v[116:119]
	v_mfma_f32_16x16x32_bf16 v[0:3], v[8:11], v[64:67], v[124:127]
	v_mfma_f32_16x16x32_bf16 v[124:127], v[68:71], v[184:187], v[12:15]
	v_mfma_f32_16x16x32_bf16 v[12:15], v[60:63], v[188:191], v[112:115]
	v_mfma_f32_16x16x32_bf16 v[116:119], v[68:71], v[208:211], v[12:15]
	v_mfma_f32_16x16x32_bf16 v[12:15], v[76:79], v[64:67], v[108:111]
	v_mfma_f32_16x16x32_bf16 v[108:111], v[80:83], v[184:187], v[12:15]
	v_mfma_f32_16x16x32_bf16 v[12:15], v[76:79], v[188:191], v[104:107]
	v_mfma_f32_16x16x32_bf16 v[100:103], v[80:83], v[208:211], v[12:15]
	v_mfma_f32_16x16x32_bf16 v[12:15], v[240:243], v[64:67], v[224:227]
	v_mfma_f32_16x16x32_bf16 v[92:95], v[244:247], v[184:187], v[12:15]
	v_mfma_f32_16x16x32_bf16 v[12:15], v[240:243], v[188:191], v[96:99]
	v_mfma_f32_16x16x32_bf16 v[4:7], v[52:55], v[184:187], v[0:3]
	v_mfma_f32_16x16x32_bf16 v[0:3], v[8:11], v[188:191], v[120:123]
	v_mfma_f32_16x16x32_bf16 v[84:87], v[244:247], v[208:211], v[12:15]
	v_mfma_f32_16x16x32_bf16 v[12:15], v[8:11], v[212:215], v[88:91]
	v_mfma_f32_16x16x32_bf16 v[8:11], v[8:11], v[232:235], v[72:75]
	v_mfma_f32_16x16x32_bf16 v[0:3], v[52:55], v[208:211], v[0:3]
	v_mfma_f32_16x16x32_bf16 v[12:15], v[52:55], v[216:219], v[12:15]
	v_mfma_f32_16x16x32_bf16 v[8:11], v[52:55], v[236:239], v[8:11]
	v_mfma_f32_16x16x32_bf16 v[52:55], v[60:63], v[212:215], v[56:59]
	v_mfma_f32_16x16x32_bf16 v[48:51], v[60:63], v[232:235], v[48:51]
	v_mfma_f32_16x16x32_bf16 v[44:47], v[76:79], v[212:215], v[44:47]
	v_mfma_f32_16x16x32_bf16 v[40:43], v[76:79], v[232:235], v[40:43]
	v_mfma_f32_16x16x32_bf16 v[36:39], v[240:243], v[212:215], v[36:39]
	v_mfma_f32_16x16x32_bf16 v[32:35], v[240:243], v[232:235], v[32:35]
	v_mfma_f32_16x16x32_bf16 v[120:123], v[68:71], v[216:219], v[52:55]
	v_mfma_f32_16x16x32_bf16 v[112:115], v[68:71], v[236:239], v[48:51]
	v_mfma_f32_16x16x32_bf16 v[104:107], v[80:83], v[216:219], v[44:47]
	v_mfma_f32_16x16x32_bf16 v[96:99], v[80:83], v[236:239], v[40:43]
	v_mfma_f32_16x16x32_bf16 v[88:91], v[244:247], v[216:219], v[36:39]
	v_mfma_f32_16x16x32_bf16 v[80:83], v[244:247], v[236:239], v[32:35]
	s_barrier
	s_setprio 0
	s_nop 0
	ds_read_b128 v[32:35], v148 offset:49152
	ds_read_b128 v[40:43], v148 offset:50176
	ds_read_b128 v[48:51], v148 offset:51200
	ds_read_b128 v[224:227], v148 offset:52224
	ds_read_b128 v[240:243], v148 offset:53248
	ds_read_b128 v[244:247], v148 offset:54272
	ds_read_b128 v[248:251], v148 offset:55296
	ds_read_b128 v[130:133], v148 offset:56320
	s_waitcnt lgkmcnt(0)
	s_setprio 1
	s_barrier
	v_mfma_f32_16x16x32_bf16 v[24:27], v[32:35], v[188:191], v[24:27]
	v_mfma_f32_16x16x32_bf16 v[16:19], v[48:51], v[188:191], v[16:19]
	v_mfma_f32_16x16x32_bf16 v[68:71], v[40:43], v[208:211], v[24:27]
	v_mfma_f32_16x16x32_bf16 v[52:55], v[224:227], v[208:211], v[16:19]
	v_mfma_f32_16x16x32_bf16 v[16:19], v[240:243], v[64:67], v[220:223]
	v_mfma_f32_16x16x32_bf16 v[24:27], v[32:35], v[212:215], v[168:171]
	v_mfma_f32_16x16x32_bf16 v[44:47], v[244:247], v[184:187], v[16:19]
	v_mfma_f32_16x16x32_bf16 v[16:19], v[240:243], v[188:191], v[228:231]
	v_mfma_f32_16x16x32_bf16 v[72:75], v[40:43], v[216:219], v[24:27]
	v_mfma_f32_16x16x32_bf16 v[24:27], v[32:35], v[232:235], v[172:175]
	v_mfma_f32_16x16x32_bf16 v[28:31], v[32:35], v[64:67], v[28:31]
	v_mfma_f32_16x16x32_bf16 v[20:23], v[48:51], v[64:67], v[20:23]
	v_mfma_f32_16x16x32_bf16 v[36:39], v[244:247], v[208:211], v[16:19]
	v_mfma_f32_16x16x32_bf16 v[16:19], v[248:251], v[64:67], v[138:141]
	v_mfma_f32_16x16x32_bf16 v[64:67], v[40:43], v[236:239], v[24:27]
	v_mfma_f32_16x16x32_bf16 v[24:27], v[48:51], v[212:215], v[192:195]
	v_mfma_f32_16x16x32_bf16 v[56:59], v[224:227], v[216:219], v[24:27]
	v_mfma_f32_16x16x32_bf16 v[24:27], v[48:51], v[232:235], v[196:199]
	v_mfma_f32_16x16x32_bf16 v[48:51], v[224:227], v[236:239], v[24:27]
	v_mfma_f32_16x16x32_bf16 v[24:27], v[240:243], v[212:215], v[200:203]
	v_mfma_f32_16x16x32_bf16 v[76:79], v[40:43], v[184:187], v[28:31]
	v_mfma_f32_16x16x32_bf16 v[40:43], v[244:247], v[216:219], v[24:27]
	v_mfma_f32_16x16x32_bf16 v[24:27], v[240:243], v[232:235], v[204:207]
	v_mfma_f32_16x16x32_bf16 v[32:35], v[244:247], v[236:239], v[24:27]
	v_mfma_f32_16x16x32_bf16 v[24:27], v[248:251], v[212:215], v[176:179]
	v_mfma_f32_16x16x32_bf16 v[60:63], v[224:227], v[184:187], v[20:23]
	v_mfma_f32_16x16x32_bf16 v[20:23], v[130:133], v[184:187], v[16:19]
	v_mfma_f32_16x16x32_bf16 v[16:19], v[248:251], v[188:191], v[142:145]
	v_mfma_f32_16x16x32_bf16 v[28:31], v[130:133], v[216:219], v[24:27]
	v_mfma_f32_16x16x32_bf16 v[24:27], v[248:251], v[232:235], v[180:183]
	v_mfma_f32_16x16x32_bf16 v[16:19], v[130:133], v[208:211], v[16:19]
	v_mfma_f32_16x16x32_bf16 v[24:27], v[130:133], v[236:239], v[24:27]
	s_barrier
	s_setprio 0
	s_and_saveexec_b64 s[8:9], s[6:7]
	s_cbranch_execz .LBB0_594
	s_barrier

; #define STAGE(Pp, BASE, br, kt) do { const u16* _g = (BASE) + ((long)(br) * K + (long)(kt) * BK); \
;     __builtin_amdgcn_global_load_lds((const unsigned*)(_g + voff0), (unsigned*)((char*)(Pp) + tb16), 16, 0, 0); \
;     __builtin_amdgcn_global_load_lds((const unsigned*)(_g + voff1), (unsigned*)((char*)(Pp) + tb16 + 8192), 16, 0, 0); } while (0)
; #define LDA(dst, b, h) _Pragma("unroll") for (int m = 0; m < 4; ++m) _Pragma("unroll") for (int k = 0; k < 2; ++k) \
;     dst[m][k] = *reinterpret_cast<const bf16x8*>((const char*)shm + aB + (((b) * 2 + (h)) * 16384 + (m * 2 + k) * 1024))
; #define LDB(dst, b, h) _Pragma("unroll") for (int n = 0; n < 2; ++n) _Pragma("unroll") for (int k = 0; k < 2; ++k) \
;     dst[n][k] = *reinterpret_cast<const bf16x8*>((const char*)shm + bB + (((b) * 2 + (h)) * 16384 + (n * 2 + k) * 1024))
; #define WAIT_V(n) asm volatile("s_waitcnt vmcnt(" #n ")" ::: "memory")
; #define WAIT_L(n) asm volatile("s_waitcnt lgkmcnt(" #n ")" ::: "memory")
; #define BAR __builtin_amdgcn_s_barrier()
; #define SCHED __builtin_amdgcn_sched_barrier(0)
; template <int MODE> ...
;     ...
;       LDB(B0, 0, 0); LDB(B1, 0, 1); LDA(At, 0, 0); STAGE(SA(1, 1), A, brow + HALF, t + 1);
;       WAIT_L(0); BAR; MMA2(0, 0, 0, 1); BAR; SCHED;
;       LDA(At, 0, 1); STAGE(SB(0, 0), Bt, bcol, t + 2); STAGE(SB(0, 1), Bt, bcol + HALF, t + 2); STAGE(SA(0, 0), A, brow, t + 2);
;       WAIT_V(6); WAIT_L(0); BAR; MMA2(1, 0, 1, 1); BAR; SCHED;
.LBB0_848:
	s_add_u32 s64, s32, 0xc000
	s_mov_b32 m0, s64
	ds_read_b128 v[170:173], v151
	ds_read_b128 v[174:177], v151 offset:1024
	ds_read_b128 v[178:181], v151 offset:2048
	ds_read_b128 v[182:185], v151 offset:3072
	ds_read_b128 v[186:189], v151 offset:16384
	ds_read_b128 v[190:193], v151 offset:17408
	ds_read_b128 v[194:197], v151 offset:18432
	ds_read_b128 v[198:201], v151 offset:19456
	ds_read_b128 v[202:205], v150
	ds_read_b128 v[206:209], v150 offset:1024
	ds_read_b128 v[210:213], v150 offset:2048
	ds_read_b128 v[214:217], v150 offset:3072
	ds_read_b128 v[218:221], v150 offset:4096
	ds_read_b128 v[222:225], v150 offset:5120
	ds_read_b128 v[226:229], v150 offset:6144
	ds_read_b128 v[230:233], v150 offset:7168
	s_add_u32 s88, s62, s22
	s_addc_u32 s89, s63, s23
	global_load_lds_dwordx4 v146, s[88:89]
	s_add_u32 s64, s32, 0xe000
	s_mov_b32 m0, s64
	s_nop 0
	s_add_u32 s90, s62, s22
	s_addc_u32 s91, s63, s23
	global_load_lds_dwordx4 v148, s[90:91]
	s_waitcnt lgkmcnt(0)
	s_setprio 1
	s_barrier
	v_mfma_f32_16x16x32_bf16 v[124:127], v[202:205], v[170:173], v[124:127]
	v_mfma_f32_16x16x32_bf16 v[120:123], v[202:205], v[178:181], v[120:123]
	v_mfma_f32_16x16x32_bf16 v[116:119], v[210:213], v[170:173], v[116:119]
	v_mfma_f32_16x16x32_bf16 v[112:115], v[210:213], v[178:181], v[112:115]
	v_mfma_f32_16x16x32_bf16 v[108:111], v[218:221], v[170:173], v[108:111]
	v_mfma_f32_16x16x32_bf16 v[104:107], v[218:221], v[178:181], v[104:107]
	v_mfma_f32_16x16x32_bf16 v[100:103], v[226:229], v[170:173], v[100:103]
	v_mfma_f32_16x16x32_bf16 v[96:99], v[226:229], v[178:181], v[96:99]
	v_mfma_f32_16x16x32_bf16 v[92:95], v[202:205], v[186:189], v[92:95]
	v_mfma_f32_16x16x32_bf16 v[88:91], v[202:205], v[194:197], v[88:91]
	v_mfma_f32_16x16x32_bf16 v[84:87], v[210:213], v[186:189], v[84:87]
	v_mfma_f32_16x16x32_bf16 v[80:83], v[210:213], v[194:197], v[80:83]
	v_mfma_f32_16x16x32_bf16 v[76:79], v[218:221], v[186:189], v[76:79]
	v_mfma_f32_16x16x32_bf16 v[72:75], v[218:221], v[194:197], v[72:75]
	v_mfma_f32_16x16x32_bf16 v[68:71], v[226:229], v[186:189], v[68:71]
	v_mfma_f32_16x16x32_bf16 v[64:67], v[226:229], v[194:197], v[64:67]
	v_mfma_f32_16x16x32_bf16 v[124:127], v[206:209], v[174:177], v[124:127]
	v_mfma_f32_16x16x32_bf16 v[120:123], v[206:209], v[182:185], v[120:123]
	v_mfma_f32_16x16x32_bf16 v[116:119], v[214:217], v[174:177], v[116:119]
	v_mfma_f32_16x16x32_bf16 v[112:115], v[214:217], v[182:185], v[112:115]
	v_mfma_f32_16x16x32_bf16 v[108:111], v[222:225], v[174:177], v[108:111]
	v_mfma_f32_16x16x32_bf16 v[104:107], v[222:225], v[182:185], v[104:107]
	v_mfma_f32_16x16x32_bf16 v[100:103], v[230:233], v[174:177], v[100:103]
	v_mfma_f32_16x16x32_bf16 v[96:99], v[230:233], v[182:185], v[96:99]
	v_mfma_f32_16x16x32_bf16 v[92:95], v[206:209], v[190:193], v[92:95]
	v_mfma_f32_16x16x32_bf16 v[88:91], v[206:209], v[198:201], v[88:91]
	v_mfma_f32_16x16x32_bf16 v[84:87], v[214:217], v[190:193], v[84:87]
	v_mfma_f32_16x16x32_bf16 v[80:83], v[214:217], v[198:201], v[80:83]
	v_mfma_f32_16x16x32_bf16 v[76:79], v[222:225], v[190:193], v[76:79]
	v_mfma_f32_16x16x32_bf16 v[72:75], v[222:225], v[198:201], v[72:75]
	v_mfma_f32_16x16x32_bf16 v[68:71], v[230:233], v[190:193], v[68:71]
	v_mfma_f32_16x16x32_bf16 v[64:67], v[230:233], v[198:201], v[64:67]
	s_barrier
	s_setprio 0
	s_add_u32 s64, s32, 0x10000
	s_mov_b32 m0, s64
	ds_read_b128 v[202:205], v150 offset:16384
	ds_read_b128 v[206:209], v150 offset:17408
	ds_read_b128 v[210:213], v150 offset:18432
	ds_read_b128 v[214:217], v150 offset:19456
	ds_read_b128 v[218:221], v150 offset:20480
	ds_read_b128 v[222:225], v150 offset:21504
	ds_read_b128 v[226:229], v150 offset:22528
	ds_read_b128 v[230:233], v150 offset:23552
	s_add_u32 s92, s62, s24
	s_addc_u32 s93, s63, s25
	global_load_lds_dwordx4 v138, s[92:93]
	s_add_u32 s64, s32, 0x12000
	s_mov_b32 m0, s64
	s_add_u32 s64, s32, 0x14000
	s_add_u32 s96, s62, s24
	s_addc_u32 s97, s63, s25
	global_load_lds_dwordx4 v140, s[96:97]
	s_mov_b32 m0, s64
	s_add_u32 s64, s32, 0x16000
	s_add_u32 s88, s62, s26
	s_addc_u32 s89, s63, s27
	global_load_lds_dwordx4 v142, s[88:89]
	s_mov_b32 m0, s64
	s_mov_b32 s64, s32
	s_add_u32 s90, s62, s26
	s_addc_u32 s91, s63, s27
	global_load_lds_dwordx4 v144, s[90:91]
	s_mov_b32 m0, s64
	s_add_u32 s64, s32, 0x2000
	s_add_u32 s92, s62, s28
	s_addc_u32 s93, s63, s29
	global_load_lds_dwordx4 v146, s[92:93]
	s_mov_b32 m0, s64
	s_nop 0
	s_add_u32 s96, s62, s28
	s_addc_u32 s97, s63, s29
	global_load_lds_dwordx4 v148, s[96:97]
	s_waitcnt vmcnt(6)
	s_waitcnt lgkmcnt(0)
	s_setprio 1
	s_barrier
; #define STAGE(Pp, BASE, br, kt) do { const u16* _g = (BASE) + ((long)(br) * K + (long)(kt) * BK); \
;     __builtin_amdgcn_global_load_lds((const unsigned*)(_g + voff0), (unsigned*)((char*)(Pp) + tb16), 16, 0, 0); \
;     __builtin_amdgcn_global_load_lds((const unsigned*)(_g + voff1), (unsigned*)((char*)(Pp) + tb16 + 8192), 16, 0, 0); } while (0)
; #define LDA(dst, b, h) _Pragma("unroll") for (int m = 0; m < 4; ++m) _Pragma("unroll") for (int k = 0; k < 2; ++k) \
;     dst[m][k] = *reinterpret_cast<const bf16x8*>((const char*)shm + aB + (((b) * 2 + (h)) * 16384 + (m * 2 + k) * 1024))
; #define LDB(dst, b, h) _Pragma("unroll") for (int n = 0; n < 2; ++n) _Pragma("unroll") for (int k = 0; k < 2; ++k) \
;     dst[n][k] = *reinterpret_cast<const bf16x8*>((const char*)shm + bB + (((b) * 2 + (h)) * 16384 + (n * 2 + k) * 1024))
; #define WAIT_V(n) asm volatile("s_waitcnt vmcnt(" #n ")" ::: "memory")
; #define WAIT_L(n) asm volatile("s_waitcnt lgkmcnt(" #n ")" ::: "memory")
; #define BAR __builtin_amdgcn_s_barrier()
; #define SCHED __builtin_amdgcn_sched_barrier(0)
; template <int MODE> ...
;     ...
;       WAIT_V(6); WAIT_L(0); BAR; MMA2(1, 0, 1, 1); BAR; SCHED;
;       LDB(B0, 1, 0); LDB(B1, 1, 1); LDA(At, 1, 0); STAGE(SA(0, 1), A, brow + HALF, t + 2);
;       WAIT_L(0); BAR; MMA2(0, 0, 0, 1); BAR; SCHED;
	v_mfma_f32_16x16x32_bf16 v[60:63], v[202:205], v[170:173], v[60:63]
	v_mfma_f32_16x16x32_bf16 v[56:59], v[202:205], v[178:181], v[56:59]
	v_mfma_f32_16x16x32_bf16 v[52:55], v[210:213], v[170:173], v[52:55]
	v_mfma_f32_16x16x32_bf16 v[48:51], v[210:213], v[178:181], v[48:51]
	v_mfma_f32_16x16x32_bf16 v[44:47], v[218:221], v[170:173], v[44:47]
	v_mfma_f32_16x16x32_bf16 v[40:43], v[218:221], v[178:181], v[40:43]
	v_mfma_f32_16x16x32_bf16 v[36:39], v[226:229], v[170:173], v[36:39]
	v_mfma_f32_16x16x32_bf16 v[32:35], v[226:229], v[178:181], v[32:35]
	v_mfma_f32_16x16x32_bf16 v[28:31], v[202:205], v[186:189], v[28:31]
	v_mfma_f32_16x16x32_bf16 v[24:27], v[202:205], v[194:197], v[24:27]
	v_mfma_f32_16x16x32_bf16 v[20:23], v[210:213], v[186:189], v[20:23]
	v_mfma_f32_16x16x32_bf16 v[16:19], v[210:213], v[194:197], v[16:19]
	v_mfma_f32_16x16x32_bf16 v[12:15], v[218:221], v[186:189], v[12:15]
	v_mfma_f32_16x16x32_bf16 v[8:11], v[218:221], v[194:197], v[8:11]
	v_mfma_f32_16x16x32_bf16 v[4:7], v[226:229], v[186:189], v[4:7]
	v_mfma_f32_16x16x32_bf16 v[0:3], v[226:229], v[194:197], v[0:3]
	v_mfma_f32_16x16x32_bf16 v[60:63], v[206:209], v[174:177], v[60:63]
	v_mfma_f32_16x16x32_bf16 v[56:59], v[206:209], v[182:185], v[56:59]
	v_mfma_f32_16x16x32_bf16 v[52:55], v[214:217], v[174:177], v[52:55]
	v_mfma_f32_16x16x32_bf16 v[48:51], v[214:217], v[182:185], v[48:51]
	v_mfma_f32_16x16x32_bf16 v[44:47], v[222:225], v[174:177], v[44:47]
	v_mfma_f32_16x16x32_bf16 v[40:43], v[222:225], v[182:185], v[40:43]
	v_mfma_f32_16x16x32_bf16 v[36:39], v[230:233], v[174:177], v[36:39]
	v_mfma_f32_16x16x32_bf16 v[32:35], v[230:233], v[182:185], v[32:35]
	v_mfma_f32_16x16x32_bf16 v[28:31], v[206:209], v[190:193], v[28:31]
	v_mfma_f32_16x16x32_bf16 v[24:27], v[206:209], v[198:201], v[24:27]
	v_mfma_f32_16x16x32_bf16 v[20:23], v[214:217], v[190:193], v[20:23]
	v_mfma_f32_16x16x32_bf16 v[16:19], v[214:217], v[198:201], v[16:19]
	v_mfma_f32_16x16x32_bf16 v[12:15], v[222:225], v[190:193], v[12:15]
	v_mfma_f32_16x16x32_bf16 v[8:11], v[222:225], v[198:201], v[8:11]
	v_mfma_f32_16x16x32_bf16 v[4:7], v[230:233], v[190:193], v[4:7]
	v_mfma_f32_16x16x32_bf16 v[0:3], v[230:233], v[198:201], v[0:3]
	s_barrier
	s_setprio 0
	s_add_u32 s64, s32, 0x4000
	s_mov_b32 m0, s64
	s_add_u32 s64, s32, 0x6000
	ds_read_b128 v[170:173], v151 offset:32768
	ds_read_b128 v[174:177], v151 offset:33792
	ds_read_b128 v[178:181], v151 offset:34816
	ds_read_b128 v[182:185], v151 offset:35840
	ds_read_b128 v[186:189], v151 offset:49152
	ds_read_b128 v[190:193], v151 offset:50176
	ds_read_b128 v[194:197], v151 offset:51200
	ds_read_b128 v[198:201], v151 offset:52224
	ds_read_b128 v[202:205], v150 offset:32768
	ds_read_b128 v[206:209], v150 offset:33792
	ds_read_b128 v[210:213], v150 offset:34816
	ds_read_b128 v[214:217], v150 offset:35840
	ds_read_b128 v[218:221], v150 offset:36864
	ds_read_b128 v[222:225], v150 offset:37888
	ds_read_b128 v[226:229], v150 offset:38912
	ds_read_b128 v[230:233], v150 offset:39936
	s_add_u32 s88, s62, s36
	s_addc_u32 s89, s63, s37
	global_load_lds_dwordx4 v146, s[88:89]
	s_mov_b32 m0, s64
	s_nop 0
	s_add_u32 s90, s62, s36
	s_addc_u32 s91, s63, s37
	global_load_lds_dwordx4 v148, s[90:91]
	s_waitcnt lgkmcnt(0)
	s_setprio 1
	s_barrier
	v_mfma_f32_16x16x32_bf16 v[124:127], v[202:205], v[170:173], v[124:127]
	v_mfma_f32_16x16x32_bf16 v[120:123], v[202:205], v[178:181], v[120:123]
	v_mfma_f32_16x16x32_bf16 v[116:119], v[210:213], v[170:173], v[116:119]
	v_mfma_f32_16x16x32_bf16 v[112:115], v[210:213], v[178:181], v[112:115]
	v_mfma_f32_16x16x32_bf16 v[108:111], v[218:221], v[170:173], v[108:111]
	v_mfma_f32_16x16x32_bf16 v[104:107], v[218:221], v[178:181], v[104:107]
	v_mfma_f32_16x16x32_bf16 v[100:103], v[226:229], v[170:173], v[100:103]
	v_mfma_f32_16x16x32_bf16 v[96:99], v[226:229], v[178:181], v[96:99]
	v_mfma_f32_16x16x32_bf16 v[92:95], v[202:205], v[186:189], v[92:95]
	v_mfma_f32_16x16x32_bf16 v[88:91], v[202:205], v[194:197], v[88:91]
	v_mfma_f32_16x16x32_bf16 v[84:87], v[210:213], v[186:189], v[84:87]
	v_mfma_f32_16x16x32_bf16 v[80:83], v[210:213], v[194:197], v[80:83]
	v_mfma_f32_16x16x32_bf16 v[76:79], v[218:221], v[186:189], v[76:79]
	v_mfma_f32_16x16x32_bf16 v[72:75], v[218:221], v[194:197], v[72:75]
	v_mfma_f32_16x16x32_bf16 v[68:71], v[226:229], v[186:189], v[68:71]
	v_mfma_f32_16x16x32_bf16 v[64:67], v[226:229], v[194:197], v[64:67]
	v_mfma_f32_16x16x32_bf16 v[124:127], v[206:209], v[174:177], v[124:127]
	v_mfma_f32_16x16x32_bf16 v[120:123], v[206:209], v[182:185], v[120:123]
	v_mfma_f32_16x16x32_bf16 v[116:119], v[214:217], v[174:177], v[116:119]
	v_mfma_f32_16x16x32_bf16 v[112:115], v[214:217], v[182:185], v[112:115]
	v_mfma_f32_16x16x32_bf16 v[108:111], v[222:225], v[174:177], v[108:111]
	v_mfma_f32_16x16x32_bf16 v[104:107], v[222:225], v[182:185], v[104:107]
	v_mfma_f32_16x16x32_bf16 v[100:103], v[230:233], v[174:177], v[100:103]
	v_mfma_f32_16x16x32_bf16 v[96:99], v[230:233], v[182:185], v[96:99]
	v_mfma_f32_16x16x32_bf16 v[92:95], v[206:209], v[190:193], v[92:95]
	v_mfma_f32_16x16x32_bf16 v[88:91], v[206:209], v[198:201], v[88:91]
	v_mfma_f32_16x16x32_bf16 v[84:87], v[214:217], v[190:193], v[84:87]
	v_mfma_f32_16x16x32_bf16 v[80:83], v[214:217], v[198:201], v[80:83]
	v_mfma_f32_16x16x32_bf16 v[76:79], v[222:225], v[190:193], v[76:79]
	v_mfma_f32_16x16x32_bf16 v[72:75], v[222:225], v[198:201], v[72:75]
	v_mfma_f32_16x16x32_bf16 v[68:71], v[230:233], v[190:193], v[68:71]
	v_mfma_f32_16x16x32_bf16 v[64:67], v[230:233], v[198:201], v[64:67]
	s_barrier
; #define STAGE(Pp, BASE, br, kt) do { const u16* _g = (BASE) + ((long)(br) * K + (long)(kt) * BK); \
;     __builtin_amdgcn_global_load_lds((const unsigned*)(_g + voff0), (unsigned*)((char*)(Pp) + tb16), 16, 0, 0); \
;     __builtin_amdgcn_global_load_lds((const unsigned*)(_g + voff1), (unsigned*)((char*)(Pp) + tb16 + 8192), 16, 0, 0); } while (0)
; #define LDA(dst, b, h) _Pragma("unroll") for (int m = 0; m < 4; ++m) _Pragma("unroll") for (int k = 0; k < 2; ++k) \
;     dst[m][k] = *reinterpret_cast<const bf16x8*>((const char*)shm + aB + (((b) * 2 + (h)) * 16384 + (m * 2 + k) * 1024))
; #define LDB(dst, b, h) _Pragma("unroll") for (int n = 0; n < 2; ++n) _Pragma("unroll") for (int k = 0; k < 2; ++k) \
;     dst[n][k] = *reinterpret_cast<const bf16x8*>((const char*)shm + bB + (((b) * 2 + (h)) * 16384 + (n * 2 + k) * 1024))
; #define WAIT_V(n) asm volatile("s_waitcnt vmcnt(" #n ")" ::: "memory")
; #define WAIT_L(n) asm volatile("s_waitcnt lgkmcnt(" #n ")" ::: "memory")
; #define BAR __builtin_amdgcn_s_barrier()
; #define SCHED __builtin_amdgcn_sched_barrier(0)
; template <int MODE> ...
;     ...
;       LDA(At, 1, 1); STAGE(SB(1, 0), Bt, bcol, t + 3); STAGE(SB(1, 1), Bt, bcol + HALF, t + 3); STAGE(SA(1, 0), A, brow, t + 3);
;       WAIT_V(6); WAIT_L(0); BAR; MMA2(1, 0, 1, 1); BAR; SCHED;
;     }
;     {
;       LDB(B0, 0, 0); LDB(B1, 0, 1); LDA(At, 0, 0); STAGE(SA(1, 1), A, brow + HALF, nt - 1);
;       WAIT_L(0); BAR; MMA2(0, 0, 0, 1); BAR; SCHED;
	s_setprio 0
	s_add_u32 s64, s32, 0x18000
	s_mov_b32 m0, s64
	s_add_u32 s64, s32, 0x1a000
	ds_read_b128 v[202:205], v150 offset:49152
	ds_read_b128 v[206:209], v150 offset:50176
	ds_read_b128 v[210:213], v150 offset:51200
	ds_read_b128 v[214:217], v150 offset:52224
	ds_read_b128 v[218:221], v150 offset:53248
	ds_read_b128 v[222:225], v150 offset:54272
	ds_read_b128 v[226:229], v150 offset:55296
	ds_read_b128 v[230:233], v150 offset:56320
	s_add_u32 s92, s62, s38
	s_addc_u32 s93, s63, s39
	global_load_lds_dwordx4 v138, s[92:93]
	s_mov_b32 m0, s64
	s_add_u32 s64, s32, 0x1c000
	s_add_u32 s96, s62, s38
	s_addc_u32 s97, s63, s39
	global_load_lds_dwordx4 v140, s[96:97]
	s_mov_b32 m0, s64
	s_add_u32 s64, s32, 0x1e000
	s_add_u32 s88, s62, s40
	s_addc_u32 s89, s63, s41
	global_load_lds_dwordx4 v142, s[88:89]
	s_mov_b32 m0, s64
	s_add_u32 s64, s32, 0x8000
	s_add_u32 s90, s62, s40
	s_addc_u32 s91, s63, s41
	global_load_lds_dwordx4 v144, s[90:91]
	s_mov_b32 m0, s64
	s_add_u32 s64, s32, 0xa000
	s_add_u32 s92, s62, s42
	s_addc_u32 s93, s63, s43
	global_load_lds_dwordx4 v146, s[92:93]
	s_mov_b32 m0, s64
	s_nop 0
	s_add_u32 s96, s62, s42
	s_addc_u32 s97, s63, s43
	global_load_lds_dwordx4 v148, s[96:97]
	s_waitcnt vmcnt(6)
	s_waitcnt lgkmcnt(0)
	s_setprio 1
	s_barrier
	v_mfma_f32_16x16x32_bf16 v[60:63], v[202:205], v[170:173], v[60:63]
	v_mfma_f32_16x16x32_bf16 v[56:59], v[202:205], v[178:181], v[56:59]
	v_mfma_f32_16x16x32_bf16 v[52:55], v[210:213], v[170:173], v[52:55]
	v_mfma_f32_16x16x32_bf16 v[48:51], v[210:213], v[178:181], v[48:51]
	v_mfma_f32_16x16x32_bf16 v[44:47], v[218:221], v[170:173], v[44:47]
	v_mfma_f32_16x16x32_bf16 v[40:43], v[218:221], v[178:181], v[40:43]
	v_mfma_f32_16x16x32_bf16 v[36:39], v[226:229], v[170:173], v[36:39]
	v_mfma_f32_16x16x32_bf16 v[32:35], v[226:229], v[178:181], v[32:35]
	v_mfma_f32_16x16x32_bf16 v[28:31], v[202:205], v[186:189], v[28:31]
	v_mfma_f32_16x16x32_bf16 v[24:27], v[202:205], v[194:197], v[24:27]
	v_mfma_f32_16x16x32_bf16 v[20:23], v[210:213], v[186:189], v[20:23]
	v_mfma_f32_16x16x32_bf16 v[16:19], v[210:213], v[194:197], v[16:19]
	v_mfma_f32_16x16x32_bf16 v[12:15], v[218:221], v[186:189], v[12:15]
	v_mfma_f32_16x16x32_bf16 v[8:11], v[218:221], v[194:197], v[8:11]
	v_mfma_f32_16x16x32_bf16 v[4:7], v[226:229], v[186:189], v[4:7]
	v_mfma_f32_16x16x32_bf16 v[0:3], v[226:229], v[194:197], v[0:3]
	v_mfma_f32_16x16x32_bf16 v[60:63], v[206:209], v[174:177], v[60:63]
	v_mfma_f32_16x16x32_bf16 v[56:59], v[206:209], v[182:185], v[56:59]
	v_mfma_f32_16x16x32_bf16 v[52:55], v[214:217], v[174:177], v[52:55]
	v_mfma_f32_16x16x32_bf16 v[48:51], v[214:217], v[182:185], v[48:51]
	v_mfma_f32_16x16x32_bf16 v[44:47], v[222:225], v[174:177], v[44:47]
	v_mfma_f32_16x16x32_bf16 v[40:43], v[222:225], v[182:185], v[40:43]
	v_mfma_f32_16x16x32_bf16 v[36:39], v[230:233], v[174:177], v[36:39]
	v_mfma_f32_16x16x32_bf16 v[32:35], v[230:233], v[182:185], v[32:35]
	v_mfma_f32_16x16x32_bf16 v[28:31], v[206:209], v[190:193], v[28:31]
	v_mfma_f32_16x16x32_bf16 v[24:27], v[206:209], v[198:201], v[24:27]
	v_mfma_f32_16x16x32_bf16 v[20:23], v[214:217], v[190:193], v[20:23]
	v_mfma_f32_16x16x32_bf16 v[16:19], v[214:217], v[198:201], v[16:19]
	v_mfma_f32_16x16x32_bf16 v[12:15], v[222:225], v[190:193], v[12:15]
	v_mfma_f32_16x16x32_bf16 v[8:11], v[222:225], v[198:201], v[8:11]
	v_mfma_f32_16x16x32_bf16 v[4:7], v[230:233], v[190:193], v[4:7]
	v_mfma_f32_16x16x32_bf16 v[0:3], v[230:233], v[198:201], v[0:3]
	s_barrier
	s_setprio 0
	s_add_i32 s45, s45, 2
	s_add_u32 s62, s62, 0x100
	s_addc_u32 s63, s63, 0
	s_cmpk_lt_u32 s45, 0xa8
	s_cbranch_scc1 .LBB0_848
	s_add_u32 s60, s60, 0x5580
	v_readfirstlane_b32 s45, v167
	s_addc_u32 s61, s61, 0
	s_mov_b32 m0, s45
	v_readfirstlane_b32 s45, v168
	ds_read_b128 v[138:141], v151
	ds_read_b128 v[142:145], v151 offset:1024
	ds_read_b128 v[146:149], v151 offset:2048
	ds_read_b128 v[170:173], v151 offset:3072
	ds_read_b128 v[174:177], v151 offset:16384
	ds_read_b128 v[178:181], v151 offset:17408
	ds_read_b128 v[182:185], v151 offset:18432
	ds_read_b128 v[186:189], v151 offset:19456
	ds_read_b128 v[190:193], v150
	ds_read_b128 v[194:197], v150 offset:1024
	ds_read_b128 v[198:201], v150 offset:2048
	ds_read_b128 v[202:205], v150 offset:3072
	ds_read_b128 v[206:209], v150 offset:4096
	ds_read_b128 v[210:213], v150 offset:5120
	ds_read_b128 v[214:217], v150 offset:6144
	ds_read_b128 v[218:221], v150 offset:7168
	global_load_lds_dwordx4 v134, s[60:61]
	s_mov_b32 m0, s45
	s_nop 0
	global_load_lds_dwordx4 v136, s[60:61]
	s_waitcnt lgkmcnt(0)
	s_setprio 1
	s_barrier
; #define LDA(dst, b, h) _Pragma("unroll") for (int m = 0; m < 4; ++m) _Pragma("unroll") for (int k = 0; k < 2; ++k) \
;     dst[m][k] = *reinterpret_cast<const bf16x8*>((const char*)shm + aB + (((b) * 2 + (h)) * 16384 + (m * 2 + k) * 1024))
; #define WAIT_V(n) asm volatile("s_waitcnt vmcnt(" #n ")" ::: "memory")
; #define WAIT_L(n) asm volatile("s_waitcnt lgkmcnt(" #n ")" ::: "memory")
; #define BAR __builtin_amdgcn_s_barrier()
; #define SCHED __builtin_amdgcn_sched_barrier(0)
; template <int MODE> ...
;     ...
;       WAIT_L(0); BAR; MMA2(0, 0, 0, 1); BAR; SCHED;
;       LDA(At, 0, 1); WAIT_V(0); WAIT_L(0); BAR; MMA2(1, 0, 1, 1); BAR; SCHED;
	v_mfma_f32_16x16x32_bf16 v[124:127], v[190:193], v[138:141], v[124:127]
	v_mfma_f32_16x16x32_bf16 v[116:119], v[198:201], v[138:141], v[116:119]
	v_mfma_f32_16x16x32_bf16 v[108:111], v[206:209], v[138:141], v[108:111]
	v_mfma_f32_16x16x32_bf16 v[100:103], v[214:217], v[138:141], v[100:103]
	v_mfma_f32_16x16x32_bf16 v[96:99], v[214:217], v[146:149], v[96:99]
	v_mfma_f32_16x16x32_bf16 v[92:95], v[190:193], v[174:177], v[92:95]
	v_mfma_f32_16x16x32_bf16 v[88:91], v[190:193], v[182:185], v[88:91]
	v_mfma_f32_16x16x32_bf16 v[80:83], v[198:201], v[182:185], v[80:83]
	v_mfma_f32_16x16x32_bf16 v[76:79], v[206:209], v[174:177], v[76:79]
	v_mfma_f32_16x16x32_bf16 v[124:127], v[194:197], v[142:145], v[124:127]
	v_mfma_f32_16x16x32_bf16 v[120:123], v[190:193], v[146:149], v[120:123]
	v_mfma_f32_16x16x32_bf16 v[116:119], v[202:205], v[142:145], v[116:119]
	v_mfma_f32_16x16x32_bf16 v[112:115], v[198:201], v[146:149], v[112:115]
	v_mfma_f32_16x16x32_bf16 v[108:111], v[210:213], v[142:145], v[108:111]
	v_mfma_f32_16x16x32_bf16 v[104:107], v[206:209], v[146:149], v[104:107]
	v_mfma_f32_16x16x32_bf16 v[100:103], v[218:221], v[142:145], v[100:103]
	v_mfma_f32_16x16x32_bf16 v[96:99], v[218:221], v[170:173], v[96:99]
	v_mfma_f32_16x16x32_bf16 v[92:95], v[194:197], v[178:181], v[92:95]
	v_mfma_f32_16x16x32_bf16 v[88:91], v[194:197], v[186:189], v[88:91]
	v_mfma_f32_16x16x32_bf16 v[84:87], v[198:201], v[174:177], v[84:87]
	v_mfma_f32_16x16x32_bf16 v[80:83], v[202:205], v[186:189], v[80:83]
	v_mfma_f32_16x16x32_bf16 v[76:79], v[210:213], v[178:181], v[76:79]
	v_mfma_f32_16x16x32_bf16 v[72:75], v[206:209], v[182:185], v[72:75]
	v_mfma_f32_16x16x32_bf16 v[68:71], v[214:217], v[174:177], v[68:71]
	v_mfma_f32_16x16x32_bf16 v[64:67], v[214:217], v[182:185], v[64:67]
	v_mfma_f32_16x16x32_bf16 v[222:225], v[194:197], v[170:173], v[120:123]
	v_mfma_f32_16x16x32_bf16 v[226:229], v[202:205], v[170:173], v[112:115]
	v_mfma_f32_16x16x32_bf16 v[230:233], v[210:213], v[170:173], v[104:107]
	v_mfma_f32_16x16x32_bf16 v[190:193], v[202:205], v[178:181], v[84:87]
	v_mfma_f32_16x16x32_bf16 v[194:197], v[210:213], v[186:189], v[72:75]
	v_mfma_f32_16x16x32_bf16 v[198:201], v[218:221], v[178:181], v[68:71]
	v_mfma_f32_16x16x32_bf16 v[202:205], v[218:221], v[186:189], v[64:67]
	s_barrier
	s_setprio 0
	s_nop 0
	ds_read_b128 v[64:67], v150 offset:16384
	ds_read_b128 v[68:71], v150 offset:17408
	ds_read_b128 v[72:75], v150 offset:18432
	ds_read_b128 v[84:87], v150 offset:19456
	ds_read_b128 v[104:107], v150 offset:20480
	ds_read_b128 v[112:115], v150 offset:21504
	ds_read_b128 v[120:123], v150 offset:22528
	ds_read_b128 v[206:209], v150 offset:23552
	s_waitcnt vmcnt(0)
	s_waitcnt lgkmcnt(0)
	s_setprio 1
	s_barrier
	v_mfma_f32_16x16x32_bf16 v[60:63], v[64:67], v[138:141], v[60:63]
	v_mfma_f32_16x16x32_bf16 v[56:59], v[64:67], v[146:149], v[56:59]
	v_mfma_f32_16x16x32_bf16 v[52:55], v[72:75], v[138:141], v[52:55]
	v_mfma_f32_16x16x32_bf16 v[48:51], v[72:75], v[146:149], v[48:51]
	v_mfma_f32_16x16x32_bf16 v[44:47], v[104:107], v[138:141], v[44:47]
	v_mfma_f32_16x16x32_bf16 v[40:43], v[104:107], v[146:149], v[40:43]
	v_mfma_f32_16x16x32_bf16 v[28:31], v[64:67], v[174:177], v[28:31]
	v_mfma_f32_16x16x32_bf16 v[24:27], v[64:67], v[182:185], v[24:27]
	v_mfma_f32_16x16x32_bf16 v[20:23], v[72:75], v[174:177], v[20:23]
	v_mfma_f32_16x16x32_bf16 v[60:63], v[68:71], v[142:145], v[60:63]
	v_mfma_f32_16x16x32_bf16 v[56:59], v[68:71], v[170:173], v[56:59]
	v_mfma_f32_16x16x32_bf16 v[52:55], v[84:87], v[142:145], v[52:55]
	v_mfma_f32_16x16x32_bf16 v[48:51], v[84:87], v[170:173], v[48:51]
	v_mfma_f32_16x16x32_bf16 v[44:47], v[112:115], v[142:145], v[44:47]
	v_mfma_f32_16x16x32_bf16 v[40:43], v[112:115], v[170:173], v[40:43]
	v_mfma_f32_16x16x32_bf16 v[36:39], v[120:123], v[138:141], v[36:39]
	v_mfma_f32_16x16x32_bf16 v[32:35], v[120:123], v[146:149], v[32:35]
	v_mfma_f32_16x16x32_bf16 v[28:31], v[68:71], v[178:181], v[28:31]
	v_mfma_f32_16x16x32_bf16 v[24:27], v[68:71], v[186:189], v[24:27]
	v_mfma_f32_16x16x32_bf16 v[20:23], v[84:87], v[178:181], v[20:23]
	v_mfma_f32_16x16x32_bf16 v[16:19], v[72:75], v[182:185], v[16:19]
	v_mfma_f32_16x16x32_bf16 v[12:15], v[104:107], v[174:177], v[12:15]
	v_mfma_f32_16x16x32_bf16 v[8:11], v[104:107], v[182:185], v[8:11]
	v_mfma_f32_16x16x32_bf16 v[4:7], v[120:123], v[174:177], v[4:7]
	v_mfma_f32_16x16x32_bf16 v[0:3], v[120:123], v[182:185], v[0:3]
	v_mfma_f32_16x16x32_bf16 v[138:141], v[206:209], v[142:145], v[36:39]
	v_mfma_f32_16x16x32_bf16 v[142:145], v[206:209], v[170:173], v[32:35]
	v_mfma_f32_16x16x32_bf16 v[146:149], v[84:87], v[186:189], v[16:19]
	v_mfma_f32_16x16x32_bf16 v[170:173], v[112:115], v[178:181], v[12:15]
	v_mfma_f32_16x16x32_bf16 v[210:213], v[112:115], v[186:189], v[8:11]
	v_mfma_f32_16x16x32_bf16 v[174:177], v[206:209], v[178:181], v[4:7]
	v_mfma_f32_16x16x32_bf16 v[178:181], v[206:209], v[186:189], v[0:3]
	s_barrier
; #define LDA(dst, b, h) _Pragma("unroll") for (int m = 0; m < 4; ++m) _Pragma("unroll") for (int k = 0; k < 2; ++k) \
;     dst[m][k] = *reinterpret_cast<const bf16x8*>((const char*)shm + aB + (((b) * 2 + (h)) * 16384 + (m * 2 + k) * 1024))
; #define LDB(dst, b, h) _Pragma("unroll") for (int n = 0; n < 2; ++n) _Pragma("unroll") for (int k = 0; k < 2; ++k) \
;     dst[n][k] = *reinterpret_cast<const bf16x8*>((const char*)shm + bB + (((b) * 2 + (h)) * 16384 + (n * 2 + k) * 1024))
; #define WAIT_L(n) asm volatile("s_waitcnt lgkmcnt(" #n ")" ::: "memory")
; #define BAR __builtin_amdgcn_s_barrier()
; #define SCHED __builtin_amdgcn_sched_barrier(0)
; template <int MODE> ...
;     ...
;       LDB(B0, 1, 0); LDB(B1, 1, 1); LDA(At, 1, 0); WAIT_L(0); BAR; MMA2(0, 0, 0, 1); BAR; SCHED;
;       LDA(At, 1, 1); WAIT_L(0); BAR; MMA2(1, 0, 1, 1); BAR; SCHED;
;     }
;     ...
;     if (wr == 0) BAR;
	s_setprio 0
	ds_read_b128 v[12:15], v151 offset:32768
	ds_read_b128 v[16:19], v151 offset:33792
	ds_read_b128 v[182:185], v151 offset:34816
	ds_read_b128 v[186:189], v151 offset:35840
	ds_read_b128 v[206:209], v151 offset:49152
	ds_read_b128 v[214:217], v151 offset:50176
	ds_read_b128 v[218:221], v151 offset:51200
	ds_read_b128 v[234:237], v151 offset:52224
	ds_read_b128 v[0:3], v150 offset:32768
	ds_read_b128 v[4:7], v150 offset:33792
	ds_read_b128 v[8:11], v150 offset:34816
	ds_read_b128 v[32:35], v150 offset:35840
	ds_read_b128 v[36:39], v150 offset:36864
	ds_read_b128 v[238:241], v150 offset:37888
	ds_read_b128 v[242:245], v150 offset:38912
	ds_read_b128 v[246:249], v150 offset:39936
	s_waitcnt lgkmcnt(0)
	s_setprio 1
	s_barrier
	v_mfma_f32_16x16x32_bf16 v[64:67], v[0:3], v[12:15], v[124:127]
	v_mfma_f32_16x16x32_bf16 v[68:71], v[242:245], v[182:185], v[96:99]
	v_mfma_f32_16x16x32_bf16 v[120:123], v[4:7], v[16:19], v[64:67]
	v_mfma_f32_16x16x32_bf16 v[64:67], v[0:3], v[182:185], v[222:225]
	v_mfma_f32_16x16x32_bf16 v[84:87], v[246:249], v[186:189], v[68:71]
	v_mfma_f32_16x16x32_bf16 v[68:71], v[0:3], v[206:209], v[92:95]
	v_mfma_f32_16x16x32_bf16 v[0:3], v[0:3], v[218:221], v[88:91]
	v_mfma_f32_16x16x32_bf16 v[88:91], v[4:7], v[234:237], v[0:3]
	v_mfma_f32_16x16x32_bf16 v[0:3], v[8:11], v[206:209], v[190:193]
	v_mfma_f32_16x16x32_bf16 v[124:127], v[4:7], v[186:189], v[64:67]
	v_mfma_f32_16x16x32_bf16 v[64:67], v[8:11], v[12:15], v[116:119]
	v_mfma_f32_16x16x32_bf16 v[72:75], v[32:35], v[214:217], v[0:3]
	v_mfma_f32_16x16x32_bf16 v[0:3], v[8:11], v[218:221], v[80:83]
	v_mfma_f32_16x16x32_bf16 v[112:115], v[32:35], v[16:19], v[64:67]
	v_mfma_f32_16x16x32_bf16 v[64:67], v[8:11], v[182:185], v[226:229]
	v_mfma_f32_16x16x32_bf16 v[92:95], v[32:35], v[234:237], v[0:3]
	v_mfma_f32_16x16x32_bf16 v[0:3], v[36:39], v[206:209], v[76:79]
	v_mfma_f32_16x16x32_bf16 v[116:119], v[32:35], v[186:189], v[64:67]
	v_mfma_f32_16x16x32_bf16 v[64:67], v[36:39], v[12:15], v[108:111]
	v_mfma_f32_16x16x32_bf16 v[76:79], v[238:241], v[214:217], v[0:3]
	v_mfma_f32_16x16x32_bf16 v[0:3], v[36:39], v[218:221], v[194:197]
	v_mfma_f32_16x16x32_bf16 v[104:107], v[238:241], v[16:19], v[64:67]
	v_mfma_f32_16x16x32_bf16 v[64:67], v[36:39], v[182:185], v[230:233]
	v_mfma_f32_16x16x32_bf16 v[96:99], v[238:241], v[234:237], v[0:3]
	v_mfma_f32_16x16x32_bf16 v[0:3], v[242:245], v[206:209], v[198:201]
	v_mfma_f32_16x16x32_bf16 v[108:111], v[238:241], v[186:189], v[64:67]
	v_mfma_f32_16x16x32_bf16 v[64:67], v[242:245], v[12:15], v[100:103]
	v_mfma_f32_16x16x32_bf16 v[80:83], v[246:249], v[214:217], v[0:3]
	v_mfma_f32_16x16x32_bf16 v[0:3], v[242:245], v[218:221], v[202:205]
	v_mfma_f32_16x16x32_bf16 v[64:67], v[246:249], v[16:19], v[64:67]
	v_mfma_f32_16x16x32_bf16 v[68:71], v[4:7], v[214:217], v[68:71]
	v_mfma_f32_16x16x32_bf16 v[100:103], v[246:249], v[234:237], v[0:3]
	s_barrier
	s_setprio 0
	ds_read_b128 v[190:193], v150 offset:49152
	ds_read_b128 v[194:197], v150 offset:50176
	ds_read_b128 v[198:201], v150 offset:51200
	ds_read_b128 v[202:205], v150 offset:52224
	ds_read_b128 v[222:225], v150 offset:53248
	ds_read_b128 v[226:229], v150 offset:54272
	ds_read_b128 v[230:233], v150 offset:55296
	ds_read_b128 v[238:241], v150 offset:56320
	s_waitcnt lgkmcnt(0)
	s_setprio 1
	s_barrier
	v_mfma_f32_16x16x32_bf16 v[4:7], v[190:193], v[182:185], v[56:59]
	v_mfma_f32_16x16x32_bf16 v[8:11], v[198:201], v[182:185], v[48:51]
	v_mfma_f32_16x16x32_bf16 v[0:3], v[190:193], v[12:15], v[60:63]
	v_mfma_f32_16x16x32_bf16 v[32:35], v[194:197], v[186:189], v[4:7]
	v_mfma_f32_16x16x32_bf16 v[4:7], v[198:201], v[12:15], v[52:55]
	v_mfma_f32_16x16x32_bf16 v[36:39], v[202:205], v[186:189], v[8:11]
	v_mfma_f32_16x16x32_bf16 v[8:11], v[222:225], v[12:15], v[44:47]
	v_mfma_f32_16x16x32_bf16 v[12:15], v[230:233], v[12:15], v[138:141]
	v_mfma_f32_16x16x32_bf16 v[0:3], v[194:197], v[16:19], v[0:3]
	v_mfma_f32_16x16x32_bf16 v[4:7], v[202:205], v[16:19], v[4:7]
	v_mfma_f32_16x16x32_bf16 v[8:11], v[226:229], v[16:19], v[8:11]
	v_mfma_f32_16x16x32_bf16 v[12:15], v[238:241], v[16:19], v[12:15]
	v_mfma_f32_16x16x32_bf16 v[16:19], v[230:233], v[182:185], v[142:145]
	v_mfma_f32_16x16x32_bf16 v[24:27], v[190:193], v[218:221], v[24:27]
	v_mfma_f32_16x16x32_bf16 v[44:47], v[238:241], v[186:189], v[16:19]
	v_mfma_f32_16x16x32_bf16 v[16:19], v[190:193], v[206:209], v[28:31]
	v_mfma_f32_16x16x32_bf16 v[48:51], v[194:197], v[234:237], v[24:27]
	v_mfma_f32_16x16x32_bf16 v[24:27], v[198:201], v[218:221], v[146:149]
	v_mfma_f32_16x16x32_bf16 v[28:31], v[222:225], v[218:221], v[210:213]
	v_mfma_f32_16x16x32_bf16 v[40:43], v[222:225], v[182:185], v[40:43]
	v_mfma_f32_16x16x32_bf16 v[20:23], v[198:201], v[206:209], v[20:23]
	v_mfma_f32_16x16x32_bf16 v[52:55], v[202:205], v[234:237], v[24:27]
	v_mfma_f32_16x16x32_bf16 v[24:27], v[222:225], v[206:209], v[170:173]
	v_mfma_f32_16x16x32_bf16 v[56:59], v[226:229], v[234:237], v[28:31]
	v_mfma_f32_16x16x32_bf16 v[28:31], v[230:233], v[206:209], v[174:177]
	v_mfma_f32_16x16x32_bf16 v[60:63], v[230:233], v[218:221], v[178:181]
	v_mfma_f32_16x16x32_bf16 v[40:43], v[226:229], v[186:189], v[40:43]
	v_mfma_f32_16x16x32_bf16 v[16:19], v[194:197], v[214:217], v[16:19]
	v_mfma_f32_16x16x32_bf16 v[20:23], v[202:205], v[214:217], v[20:23]
	v_mfma_f32_16x16x32_bf16 v[24:27], v[226:229], v[214:217], v[24:27]
	v_mfma_f32_16x16x32_bf16 v[28:31], v[238:241], v[214:217], v[28:31]
	v_mfma_f32_16x16x32_bf16 v[60:63], v[238:241], v[234:237], v[60:63]
	s_barrier
	s_setprio 0
	s_and_saveexec_b64 s[60:61], s[6:7]
	s_cbranch_execz .LBB0_851
	s_barrier
